# K-loops: MFMA-section wave joins the closing barrier 2 MFMAs early, trailing 2 MFMAs issued after it at prio 2
# baseline (speedup 1.0000x reference)
; #define PG8_STAGE(bufoff, gbase, voff) do { _Pragma("unroll") for (int _i = 0; _i < 2; ++_i) \
;         __builtin_amdgcn_global_load_lds((const unsigned*)((const char*)(gbase) + (voff)[_i]), (LAS unsigned*)(lds + (bufoff) + ldsw + _i * 8192), 16, 0, 0); } while (0)
; #define PG8_LDA(dst, b, h) do { _Pragma("unroll") for (int m = 0; m < NM; ++m) _Pragma("unroll") for (int k = 0; k < 2; ++k) dst[m][k] = *(const LAS bf16x8*)(lds + PG8_SA(b, h) + aoff + m * 2048 + k * 1024); } while (0)
; #define PG8_LDB(dst, b, h) do { _Pragma("unroll") for (int n = 0; n < 2; ++n) _Pragma("unroll") for (int k = 0; k < 2; ++k) dst[n][k] = *(const LAS bf16x8*)(lds + PG8_SB(b, h) + boff + n * 2048 + k * 1024); } while (0)
; #define PG8_MMA(ai, bj, At, Bt) do { __builtin_amdgcn_s_setprio(1); _Pragma("unroll") for (int m = 0; m < NM; ++m) _Pragma("unroll") for (int n = 0; n < 2; ++n) _Pragma("unroll") for (int k = 0; k < 2; ++k) \
;         acc[ai][bj][m][n] = __builtin_amdgcn_mfma_f32_16x16x32_bf16(Bt[n][k], At[m][k], acc[ai][bj][m][n], 0, 0, 0); __builtin_amdgcn_s_setprio(0); } while (0)
; #define PG8_WAIT_V(n) asm volatile("s_waitcnt vmcnt(" #n ")" ::: "memory")
; #define PG8_WAIT_L(n) asm volatile("s_waitcnt lgkmcnt(" #n ")" ::: "memory")
; #define PG8_BAR __builtin_amdgcn_s_barrier()
; #define PG8_SCHED __builtin_amdgcn_sched_barrier(0)
;     ...
;             PG8_LDB(B0, 0, 0); PG8_LDB(B1, 0, 1); PG8_SCHED; PG8_LDA(At, 0, 0); PG8_STAGE(PG8_SA(1, 1), a1 + hstepA, voffA);
;             PG8_WAIT_V(8); PG8_WAIT_L(0); PG8_BAR; PG8_MMA(0, 0, At, B0); PG8_MMA(0, 1, At, B1); PG8_BAR; PG8_SCHED;
;             PG8_LDA(At, 0, 1); PG8_STAGE(PG8_SB(0, 0), b2, voffB); PG8_STAGE(PG8_SB(0, 1), b2 + hstepB, voffB); PG8_STAGE(PG8_SA(0, 0), a2, voffA);
.LBB0_200:
	ds_read_b128 v[26:29], v172
	ds_read_b128 v[30:33], v172 offset:1024
	ds_read_b128 v[42:45], v172 offset:2048
	ds_read_b128 v[46:49], v172 offset:3072
	ds_read_b128 v[146:149], v173
	ds_read_b128 v[150:153], v173 offset:1024
	ds_read_b128 v[164:167], v173 offset:2048
	ds_read_b128 v[168:171], v173 offset:3072
	s_add_u32 s30, s28, 0xfff80080
	s_addc_u32 s31, s29, -1
	s_cmp_eq_u32 s56, 28
	s_cselect_b32 s35, s2, s31
	s_cselect_b32 s34, s3, s30
	s_cselect_b32 s31, s9, s54
	s_cselect_b32 s30, s21, s23
	s_cselect_b32 s100, -1, 0
	s_andn2_b32 s100, s100, s101
	s_add_i32 m0, s43, 0xc000
	ds_read_b128 v[178:181], v174
	ds_read_b128 v[182:185], v174 offset:1024
	ds_read_b128 v[186:189], v174 offset:2048
	ds_read_b128 v[190:193], v174 offset:3072
	ds_read_b128 v[194:197], v174 offset:4096
	ds_read_b128 v[198:201], v174 offset:5120
	ds_read_b128 v[202:205], v174 offset:6144
	ds_read_b128 v[206:209], v174 offset:7168
	global_load_lds_dwordx4 v160, s[28:29]
	s_add_i32 m0, s43, 0xe000
	s_nop 0
	global_load_lds_dwordx4 v162, s[28:29]
	s_waitcnt vmcnt(8)
	s_waitcnt lgkmcnt(0)
	s_barrier
	s_setprio 1
	s_waitcnt lgkmcnt(0)
	v_mfma_f32_16x16x32_bf16 v[142:145], v[26:29], v[178:181], v[142:145]
	v_mfma_f32_16x16x32_bf16 v[138:141], v[42:45], v[178:181], v[138:141]
	v_mfma_f32_16x16x32_bf16 v[126:129], v[26:29], v[186:189], v[126:129]
	v_mfma_f32_16x16x32_bf16 v[122:125], v[42:45], v[186:189], v[122:125]
	v_mfma_f32_16x16x32_bf16 v[110:113], v[26:29], v[194:197], v[110:113]
	v_mfma_f32_16x16x32_bf16 v[106:109], v[42:45], v[194:197], v[106:109]
	v_mfma_f32_16x16x32_bf16 v[94:97], v[26:29], v[202:205], v[94:97]
	v_mfma_f32_16x16x32_bf16 v[90:93], v[42:45], v[202:205], v[90:93]
	v_mfma_f32_16x16x32_bf16 v[142:145], v[30:33], v[182:185], v[142:145]
	v_mfma_f32_16x16x32_bf16 v[138:141], v[46:49], v[182:185], v[138:141]
	v_mfma_f32_16x16x32_bf16 v[126:129], v[30:33], v[190:193], v[126:129]
	v_mfma_f32_16x16x32_bf16 v[122:125], v[46:49], v[190:193], v[122:125]
	v_mfma_f32_16x16x32_bf16 v[110:113], v[30:33], v[198:201], v[110:113]
	v_mfma_f32_16x16x32_bf16 v[106:109], v[46:49], v[198:201], v[106:109]
	v_mfma_f32_16x16x32_bf16 v[94:97], v[30:33], v[206:209], v[94:97]
	v_mfma_f32_16x16x32_bf16 v[90:93], v[46:49], v[206:209], v[90:93]
	s_setprio 0
	s_setprio 1
	v_mfma_f32_16x16x32_bf16 v[134:137], v[146:149], v[178:181], v[134:137]
	v_mfma_f32_16x16x32_bf16 v[130:133], v[164:167], v[178:181], v[130:133]
	v_mfma_f32_16x16x32_bf16 v[118:121], v[146:149], v[186:189], v[118:121]
	v_mfma_f32_16x16x32_bf16 v[114:117], v[164:167], v[186:189], v[114:117]
	v_mfma_f32_16x16x32_bf16 v[102:105], v[146:149], v[194:197], v[102:105]
	v_mfma_f32_16x16x32_bf16 v[98:101], v[164:167], v[194:197], v[98:101]
	v_mfma_f32_16x16x32_bf16 v[86:89], v[146:149], v[202:205], v[86:89]
	v_mfma_f32_16x16x32_bf16 v[82:85], v[164:167], v[202:205], v[82:85]
	v_mfma_f32_16x16x32_bf16 v[134:137], v[150:153], v[182:185], v[134:137]
	v_mfma_f32_16x16x32_bf16 v[130:133], v[168:171], v[182:185], v[130:133]
	v_mfma_f32_16x16x32_bf16 v[118:121], v[150:153], v[190:193], v[118:121]
	v_mfma_f32_16x16x32_bf16 v[114:117], v[168:171], v[190:193], v[114:117]
	v_mfma_f32_16x16x32_bf16 v[102:105], v[150:153], v[198:201], v[102:105]
	v_mfma_f32_16x16x32_bf16 v[98:101], v[168:171], v[198:201], v[98:101]
	s_setprio 2
	s_barrier
	v_mfma_f32_16x16x32_bf16 v[86:89], v[150:153], v[206:209], v[86:89]
	v_mfma_f32_16x16x32_bf16 v[82:85], v[168:171], v[206:209], v[82:85]
	s_setprio 0
	s_mov_b32 m0, s39
	v_lshl_add_u64 v[210:211], s[30:31], 0, v[0:1]
	s_add_u32 s72, s30, 0x80000
	s_addc_u32 s73, s31, 0
	ds_read_b128 v[178:181], v174 offset:16384
	ds_read_b128 v[182:185], v174 offset:17408
	ds_read_b128 v[186:189], v174 offset:18432
	ds_read_b128 v[190:193], v174 offset:19456
	ds_read_b128 v[194:197], v174 offset:20480
	ds_read_b128 v[198:201], v174 offset:21504
	ds_read_b128 v[202:205], v174 offset:22528
	ds_read_b128 v[206:209], v174 offset:23552
	s_cmp_lg_u32 s100, 0
	s_cbranch_scc1 .Ltl_ic_0s
	global_load_lds_dwordx4 v0, s[30:31]
	v_lshl_add_u64 v[212:213], s[30:31], 0, v[158:159]
	s_mov_b32 m0, s40
	s_nop 0
	global_load_lds_dwordx4 v158, s[30:31]
	s_mov_b32 m0, s41
	v_lshl_add_u64 v[216:217], s[34:35], 0, v[156:157]
	global_load_lds_dwordx4 v0, s[72:73]
	s_mov_b32 m0, s42
	s_nop 0
	global_load_lds_dwordx4 v158, s[72:73]
	v_lshl_add_u64 v[214:215], s[34:35], 0, v[154:155]
	s_mov_b32 m0, s43
	s_nop 0
	global_load_lds_dwordx4 v154, s[34:35]
	s_mov_b32 m0, s44
	s_nop 0
	global_load_lds_dwordx4 v156, s[34:35]
	s_waitcnt vmcnt(8)
	s_branch .Ltl_ic_0d

; #define PG8_STAGE(bufoff, gbase, voff) do { _Pragma("unroll") for (int _i = 0; _i < 2; ++_i) \
;         __builtin_amdgcn_global_load_lds((const unsigned*)((const char*)(gbase) + (voff)[_i]), (LAS unsigned*)(lds + (bufoff) + ldsw + _i * 8192), 16, 0, 0); } while (0)
; #define PG8_LDA(dst, b, h) do { _Pragma("unroll") for (int m = 0; m < NM; ++m) _Pragma("unroll") for (int k = 0; k < 2; ++k) dst[m][k] = *(const LAS bf16x8*)(lds + PG8_SA(b, h) + aoff + m * 2048 + k * 1024); } while (0)
; #define PG8_LDB(dst, b, h) do { _Pragma("unroll") for (int n = 0; n < 2; ++n) _Pragma("unroll") for (int k = 0; k < 2; ++k) dst[n][k] = *(const LAS bf16x8*)(lds + PG8_SB(b, h) + boff + n * 2048 + k * 1024); } while (0)
; #define PG8_MMA(ai, bj, At, Bt) do { __builtin_amdgcn_s_setprio(1); _Pragma("unroll") for (int m = 0; m < NM; ++m) _Pragma("unroll") for (int n = 0; n < 2; ++n) _Pragma("unroll") for (int k = 0; k < 2; ++k) \
;         acc[ai][bj][m][n] = __builtin_amdgcn_mfma_f32_16x16x32_bf16(Bt[n][k], At[m][k], acc[ai][bj][m][n], 0, 0, 0); __builtin_amdgcn_s_setprio(0); } while (0)
; #define PG8_WAIT_V(n) asm volatile("s_waitcnt vmcnt(" #n ")" ::: "memory")
; #define PG8_WAIT_L(n) asm volatile("s_waitcnt lgkmcnt(" #n ")" ::: "memory")
; #define PG8_BAR __builtin_amdgcn_s_barrier()
; #define PG8_SCHED __builtin_amdgcn_sched_barrier(0)
;     ...
;             PG8_WAIT_V(8); PG8_WAIT_L(0); PG8_BAR; PG8_MMA(1, 0, At, B0); PG8_MMA(1, 1, At, B1); PG8_BAR; PG8_SCHED;
;             PG8_LDB(B0, 1, 0); PG8_LDB(B1, 1, 1); PG8_SCHED; PG8_LDA(At, 1, 0); PG8_STAGE(PG8_SA(0, 1), a2 + hstepA, voffA);
.Ltl_ic_0d:
	s_waitcnt lgkmcnt(0)
	s_barrier
	s_setprio 1
	s_waitcnt lgkmcnt(0)
	v_mfma_f32_16x16x32_bf16 v[78:81], v[26:29], v[178:181], v[78:81]
	v_mfma_f32_16x16x32_bf16 v[74:77], v[42:45], v[178:181], v[74:77]
	v_mfma_f32_16x16x32_bf16 v[62:65], v[26:29], v[186:189], v[62:65]
	v_mfma_f32_16x16x32_bf16 v[58:61], v[42:45], v[186:189], v[58:61]
	v_mfma_f32_16x16x32_bf16 v[38:41], v[26:29], v[194:197], v[38:41]
	v_mfma_f32_16x16x32_bf16 v[34:37], v[42:45], v[194:197], v[34:37]
	v_mfma_f32_16x16x32_bf16 v[14:17], v[26:29], v[202:205], v[14:17]
	v_mfma_f32_16x16x32_bf16 v[10:13], v[42:45], v[202:205], v[10:13]
	v_mfma_f32_16x16x32_bf16 v[78:81], v[30:33], v[182:185], v[78:81]
	v_mfma_f32_16x16x32_bf16 v[74:77], v[46:49], v[182:185], v[74:77]
	v_mfma_f32_16x16x32_bf16 v[62:65], v[30:33], v[190:193], v[62:65]
	v_mfma_f32_16x16x32_bf16 v[58:61], v[46:49], v[190:193], v[58:61]
	v_mfma_f32_16x16x32_bf16 v[38:41], v[30:33], v[198:201], v[38:41]
	v_mfma_f32_16x16x32_bf16 v[34:37], v[46:49], v[198:201], v[34:37]
	v_mfma_f32_16x16x32_bf16 v[14:17], v[30:33], v[206:209], v[14:17]
	v_mfma_f32_16x16x32_bf16 v[10:13], v[46:49], v[206:209], v[10:13]
	s_setprio 0
	s_setprio 1
	v_mfma_f32_16x16x32_bf16 v[22:25], v[146:149], v[194:197], v[22:25]
	v_mfma_f32_16x16x32_bf16 v[18:21], v[164:167], v[194:197], v[18:21]
	v_mfma_f32_16x16x32_bf16 v[6:9], v[146:149], v[202:205], v[6:9]
	v_mfma_f32_16x16x32_bf16 v[2:5], v[164:167], v[202:205], v[2:5]
	v_mfma_f32_16x16x32_bf16 v[26:29], v[146:149], v[178:181], v[70:73]
	v_mfma_f32_16x16x32_bf16 v[30:33], v[164:167], v[178:181], v[66:69]
	v_mfma_f32_16x16x32_bf16 v[42:45], v[146:149], v[186:189], v[54:57]
	v_mfma_f32_16x16x32_bf16 v[46:49], v[164:167], v[186:189], v[50:53]
	v_mfma_f32_16x16x32_bf16 v[22:25], v[150:153], v[198:201], v[22:25]
	v_mfma_f32_16x16x32_bf16 v[18:21], v[168:171], v[198:201], v[18:21]
	v_mfma_f32_16x16x32_bf16 v[6:9], v[150:153], v[206:209], v[6:9]
	v_mfma_f32_16x16x32_bf16 v[2:5], v[168:171], v[206:209], v[2:5]
	v_mfma_f32_16x16x32_bf16 v[26:29], v[150:153], v[182:185], v[26:29]
	v_mfma_f32_16x16x32_bf16 v[30:33], v[168:171], v[182:185], v[30:33]
	s_setprio 2
	s_barrier
	v_mfma_f32_16x16x32_bf16 v[42:45], v[150:153], v[190:193], v[42:45]
	v_mfma_f32_16x16x32_bf16 v[46:49], v[168:171], v[190:193], v[46:49]
	s_setprio 0
	ds_read_b128 v[50:53], v175
	ds_read_b128 v[54:57], v175 offset:1024
	ds_read_b128 v[66:69], v175 offset:2048
	ds_read_b128 v[70:73], v175 offset:3072
	ds_read_b128 v[146:149], v176
	ds_read_b128 v[150:153], v176 offset:1024
	ds_read_b128 v[164:167], v176 offset:2048
	ds_read_b128 v[168:171], v176 offset:3072
	s_add_u32 s34, s34, 0x80000
	s_addc_u32 s35, s35, 0
	s_mov_b32 m0, s45
	ds_read_b128 v[178:181], v174 offset:32768
	ds_read_b128 v[182:185], v174 offset:33792
	ds_read_b128 v[186:189], v174 offset:34816
	ds_read_b128 v[190:193], v174 offset:35840
	ds_read_b128 v[194:197], v174 offset:36864
	ds_read_b128 v[198:201], v174 offset:37888
	ds_read_b128 v[202:205], v174 offset:38912
	ds_read_b128 v[206:209], v174 offset:39936
	s_cmp_lg_u32 s100, 0
	s_cbranch_scc1 .Ltl_ic_1s
	global_load_lds_dwordx4 v154, s[34:35]
	s_mov_b32 m0, s46
	s_nop 0
	global_load_lds_dwordx4 v156, s[34:35]
	s_waitcnt vmcnt(8)
	s_branch .Ltl_ic_1d

; #define PG8_STAGE(bufoff, gbase, voff) do { _Pragma("unroll") for (int _i = 0; _i < 2; ++_i) \
;         __builtin_amdgcn_global_load_lds((const unsigned*)((const char*)(gbase) + (voff)[_i]), (LAS unsigned*)(lds + (bufoff) + ldsw + _i * 8192), 16, 0, 0); } while (0)
; #define PG8_LDA(dst, b, h) do { _Pragma("unroll") for (int m = 0; m < NM; ++m) _Pragma("unroll") for (int k = 0; k < 2; ++k) dst[m][k] = *(const LAS bf16x8*)(lds + PG8_SA(b, h) + aoff + m * 2048 + k * 1024); } while (0)
; #define PG8_MMA(ai, bj, At, Bt) do { __builtin_amdgcn_s_setprio(1); _Pragma("unroll") for (int m = 0; m < NM; ++m) _Pragma("unroll") for (int n = 0; n < 2; ++n) _Pragma("unroll") for (int k = 0; k < 2; ++k) \
;         acc[ai][bj][m][n] = __builtin_amdgcn_mfma_f32_16x16x32_bf16(Bt[n][k], At[m][k], acc[ai][bj][m][n], 0, 0, 0); __builtin_amdgcn_s_setprio(0); } while (0)
; #define PG8_WAIT_V(n) asm volatile("s_waitcnt vmcnt(" #n ")" ::: "memory")
; #define PG8_WAIT_L(n) asm volatile("s_waitcnt lgkmcnt(" #n ")" ::: "memory")
; #define PG8_BAR __builtin_amdgcn_s_barrier()
; #define PG8_SCHED __builtin_amdgcn_sched_barrier(0)
;     ...
;             PG8_WAIT_V(8); PG8_WAIT_L(0); PG8_BAR; PG8_MMA(0, 0, At, B0); PG8_MMA(0, 1, At, B1); PG8_BAR; PG8_SCHED;
;             PG8_LDA(At, 1, 1); PG8_STAGE(PG8_SB(1, 0), b3, voffB); PG8_STAGE(PG8_SB(1, 1), b3 + hstepB, voffB); PG8_STAGE(PG8_SA(1, 0), a3, voffA);
.Ltl_ic_1d:
	s_waitcnt lgkmcnt(0)
	s_barrier
	s_setprio 1
	s_waitcnt lgkmcnt(0)
	v_mfma_f32_16x16x32_bf16 v[142:145], v[50:53], v[178:181], v[142:145]
	v_mfma_f32_16x16x32_bf16 v[138:141], v[66:69], v[178:181], v[138:141]
	v_mfma_f32_16x16x32_bf16 v[126:129], v[50:53], v[186:189], v[126:129]
	v_mfma_f32_16x16x32_bf16 v[122:125], v[66:69], v[186:189], v[122:125]
	v_mfma_f32_16x16x32_bf16 v[110:113], v[50:53], v[194:197], v[110:113]
	v_mfma_f32_16x16x32_bf16 v[106:109], v[66:69], v[194:197], v[106:109]
	v_mfma_f32_16x16x32_bf16 v[94:97], v[50:53], v[202:205], v[94:97]
	v_mfma_f32_16x16x32_bf16 v[90:93], v[66:69], v[202:205], v[90:93]
	v_mfma_f32_16x16x32_bf16 v[142:145], v[54:57], v[182:185], v[142:145]
	v_mfma_f32_16x16x32_bf16 v[138:141], v[70:73], v[182:185], v[138:141]
	v_mfma_f32_16x16x32_bf16 v[126:129], v[54:57], v[190:193], v[126:129]
	v_mfma_f32_16x16x32_bf16 v[122:125], v[70:73], v[190:193], v[122:125]
	v_mfma_f32_16x16x32_bf16 v[110:113], v[54:57], v[198:201], v[110:113]
	v_mfma_f32_16x16x32_bf16 v[106:109], v[70:73], v[198:201], v[106:109]
	v_mfma_f32_16x16x32_bf16 v[94:97], v[54:57], v[206:209], v[94:97]
	v_mfma_f32_16x16x32_bf16 v[90:93], v[70:73], v[206:209], v[90:93]
	s_setprio 0
	s_setprio 1
	v_mfma_f32_16x16x32_bf16 v[134:137], v[146:149], v[178:181], v[134:137]
	v_mfma_f32_16x16x32_bf16 v[130:133], v[164:167], v[178:181], v[130:133]
	v_mfma_f32_16x16x32_bf16 v[118:121], v[146:149], v[186:189], v[118:121]
	v_mfma_f32_16x16x32_bf16 v[114:117], v[164:167], v[186:189], v[114:117]
	v_mfma_f32_16x16x32_bf16 v[102:105], v[146:149], v[194:197], v[102:105]
	v_mfma_f32_16x16x32_bf16 v[98:101], v[164:167], v[194:197], v[98:101]
	v_mfma_f32_16x16x32_bf16 v[86:89], v[146:149], v[202:205], v[86:89]
	v_mfma_f32_16x16x32_bf16 v[82:85], v[164:167], v[202:205], v[82:85]
	v_mfma_f32_16x16x32_bf16 v[134:137], v[150:153], v[182:185], v[134:137]
	v_mfma_f32_16x16x32_bf16 v[130:133], v[168:171], v[182:185], v[130:133]
	v_mfma_f32_16x16x32_bf16 v[118:121], v[150:153], v[190:193], v[118:121]
	v_mfma_f32_16x16x32_bf16 v[114:117], v[168:171], v[190:193], v[114:117]
	v_mfma_f32_16x16x32_bf16 v[102:105], v[150:153], v[198:201], v[102:105]
	v_mfma_f32_16x16x32_bf16 v[98:101], v[168:171], v[198:201], v[98:101]
	s_setprio 2
	s_barrier
	v_mfma_f32_16x16x32_bf16 v[86:89], v[150:153], v[206:209], v[86:89]
	v_mfma_f32_16x16x32_bf16 v[82:85], v[168:171], v[206:209], v[82:85]
	s_setprio 0
	s_mov_b32 m0, s49
	v_lshl_add_u64 v[210:211], v[210:211], 0, s[66:67]
	s_add_u32 s30, s30, 0x80080
	s_addc_u32 s31, s31, 0
	ds_read_b128 v[178:181], v174 offset:49152
	ds_read_b128 v[182:185], v174 offset:50176
	ds_read_b128 v[186:189], v174 offset:51200
	ds_read_b128 v[190:193], v174 offset:52224
	ds_read_b128 v[194:197], v174 offset:53248
	ds_read_b128 v[198:201], v174 offset:54272
	ds_read_b128 v[202:205], v174 offset:55296
	ds_read_b128 v[206:209], v174 offset:56320
	s_cmp_lg_u32 s100, 0
	s_cbranch_scc1 .Ltl_ic_2s
	global_load_lds_dwordx4 v[210:211], off
	v_lshl_add_u64 v[210:211], v[212:213], 0, s[66:67]
	s_mov_b32 m0, s50
	s_nop 0
	global_load_lds_dwordx4 v[210:211], off
	s_mov_b32 m0, s58
	s_nop 0
	global_load_lds_dwordx4 v0, s[30:31]
	s_mov_b32 m0, s59
	s_nop 0
	global_load_lds_dwordx4 v158, s[30:31]
	v_lshl_add_u64 v[210:211], v[214:215], 0, s[66:67]
	s_mov_b32 m0, s51
	s_nop 0
	global_load_lds_dwordx4 v[210:211], off
	v_lshl_add_u64 v[210:211], v[216:217], 0, s[66:67]
	s_mov_b32 m0, s52
	s_nop 0
	global_load_lds_dwordx4 v[210:211], off
	s_waitcnt vmcnt(8)
	s_branch .Ltl_ic_2d

; #define PG8_STAGE(bufoff, gbase, voff) do { _Pragma("unroll") for (int _i = 0; _i < 2; ++_i) \
;         __builtin_amdgcn_global_load_lds((const unsigned*)((const char*)(gbase) + (voff)[_i]), (LAS unsigned*)(lds + (bufoff) + ldsw + _i * 8192), 16, 0, 0); } while (0)
; #define PG8_LDA(dst, b, h) do { _Pragma("unroll") for (int m = 0; m < NM; ++m) _Pragma("unroll") for (int k = 0; k < 2; ++k) dst[m][k] = *(const LAS bf16x8*)(lds + PG8_SA(b, h) + aoff + m * 2048 + k * 1024); } while (0)
; #define PG8_LDB(dst, b, h) do { _Pragma("unroll") for (int n = 0; n < 2; ++n) _Pragma("unroll") for (int k = 0; k < 2; ++k) dst[n][k] = *(const LAS bf16x8*)(lds + PG8_SB(b, h) + boff + n * 2048 + k * 1024); } while (0)
; #define PG8_WAIT_V(n) asm volatile("s_waitcnt vmcnt(" #n ")" ::: "memory")
; #define PG8_WAIT_L(n) asm volatile("s_waitcnt lgkmcnt(" #n ")" ::: "memory")
; #define PG8_BAR __builtin_amdgcn_s_barrier()
; #define PG8_SCHED __builtin_amdgcn_sched_barrier(0)
;     ...
;         for (int t = 0; t < nt; t += 2) {
;             const bool last = (t == nt - 2);
;             const char* a1 = cA + (size_t)(t + 1) * kstep;
;             const char* a2 = last ? nA : cA + (size_t)(t + 2) * kstep; const char* b2 = last ? nB : cB + (size_t)(t + 2) * kstep;
;             const char* a3 = a2 + kstep; const char* b3 = b2 + kstep;
;             if constexpr (SP2) {
;             PG8_LDB(B0, 0, 0); PG8_LDB(B1, 0, 1); PG8_SCHED; PG8_LDA(At, 0, 0); PG8_STAGE(PG8_SA(1, 1), a1 + hstepA, voffA);
;             PG8_WAIT_V(8); PG8_WAIT_L(0); PG8_BAR; PG8_MMA(0, 0, At, B0); PG8_MMA(0, 1, At, B1); PG8_BAR; PG8_SCHED;
;             PG8_LDA(At, 0, 1); PG8_STAGE(PG8_SB(0, 0), b2, voffB); PG8_STAGE(PG8_SB(0, 1), b2 + hstepB, voffB); PG8_STAGE(PG8_SA(0, 0), a2, voffA);
;             PG8_WAIT_V(8); PG8_WAIT_L(0); PG8_BAR; PG8_MMA(1, 0, At, B0); PG8_MMA(1, 1, At, B1); PG8_BAR; PG8_SCHED;
;             PG8_LDB(B0, 1, 0); PG8_LDB(B1, 1, 1); PG8_SCHED; PG8_LDA(At, 1, 0); PG8_STAGE(PG8_SA(0, 1), a2 + hstepA, voffA);
;             PG8_WAIT_V(8); PG8_WAIT_L(0); PG8_BAR; PG8_MMA(0, 0, At, B0); PG8_MMA(0, 1, At, B1); PG8_BAR; PG8_SCHED;
;             PG8_LDA(At, 1, 1); PG8_STAGE(PG8_SB(1, 0), b3, voffB); PG8_STAGE(PG8_SB(1, 1), b3 + hstepB, voffB); PG8_STAGE(PG8_SA(1, 0), a3, voffA);
;             PG8_WAIT_V(8); PG8_WAIT_L(0); PG8_BAR; PG8_MMA(1, 0, At, B0); PG8_MMA(1, 1, At, B1); PG8_BAR; PG8_SCHED;
.Ltl_ic_2d:
	s_waitcnt lgkmcnt(0)
	s_barrier
	s_setprio 1
	s_waitcnt lgkmcnt(0)
	v_mfma_f32_16x16x32_bf16 v[78:81], v[50:53], v[178:181], v[78:81]
	v_mfma_f32_16x16x32_bf16 v[74:77], v[66:69], v[178:181], v[74:77]
	v_mfma_f32_16x16x32_bf16 v[62:65], v[50:53], v[186:189], v[62:65]
	v_mfma_f32_16x16x32_bf16 v[58:61], v[66:69], v[186:189], v[58:61]
	v_mfma_f32_16x16x32_bf16 v[38:41], v[50:53], v[194:197], v[38:41]
	v_mfma_f32_16x16x32_bf16 v[34:37], v[66:69], v[194:197], v[34:37]
	v_mfma_f32_16x16x32_bf16 v[14:17], v[50:53], v[202:205], v[14:17]
	v_mfma_f32_16x16x32_bf16 v[10:13], v[66:69], v[202:205], v[10:13]
	v_mfma_f32_16x16x32_bf16 v[78:81], v[54:57], v[182:185], v[78:81]
	v_mfma_f32_16x16x32_bf16 v[74:77], v[70:73], v[182:185], v[74:77]
	v_mfma_f32_16x16x32_bf16 v[62:65], v[54:57], v[190:193], v[62:65]
	v_mfma_f32_16x16x32_bf16 v[58:61], v[70:73], v[190:193], v[58:61]
	v_mfma_f32_16x16x32_bf16 v[38:41], v[54:57], v[198:201], v[38:41]
	v_mfma_f32_16x16x32_bf16 v[34:37], v[70:73], v[198:201], v[34:37]
	v_mfma_f32_16x16x32_bf16 v[14:17], v[54:57], v[206:209], v[14:17]
	v_mfma_f32_16x16x32_bf16 v[10:13], v[70:73], v[206:209], v[10:13]
	s_setprio 0
	s_setprio 1
	v_mfma_f32_16x16x32_bf16 v[26:29], v[146:149], v[178:181], v[26:29]
	v_mfma_f32_16x16x32_bf16 v[70:73], v[150:153], v[182:185], v[26:29]
	v_mfma_f32_16x16x32_bf16 v[26:29], v[164:167], v[178:181], v[30:33]
	v_mfma_f32_16x16x32_bf16 v[66:69], v[168:171], v[182:185], v[26:29]
	v_mfma_f32_16x16x32_bf16 v[26:29], v[146:149], v[186:189], v[42:45]
	v_mfma_f32_16x16x32_bf16 v[54:57], v[150:153], v[190:193], v[26:29]
	v_mfma_f32_16x16x32_bf16 v[26:29], v[164:167], v[186:189], v[46:49]
	v_mfma_f32_16x16x32_bf16 v[22:25], v[146:149], v[194:197], v[22:25]
	v_mfma_f32_16x16x32_bf16 v[18:21], v[164:167], v[194:197], v[18:21]
	v_mfma_f32_16x16x32_bf16 v[6:9], v[146:149], v[202:205], v[6:9]
	v_mfma_f32_16x16x32_bf16 v[2:5], v[164:167], v[202:205], v[2:5]
	v_mfma_f32_16x16x32_bf16 v[50:53], v[168:171], v[190:193], v[26:29]
	v_mfma_f32_16x16x32_bf16 v[22:25], v[150:153], v[198:201], v[22:25]
	v_mfma_f32_16x16x32_bf16 v[18:21], v[168:171], v[198:201], v[18:21]
	s_setprio 2
	s_barrier
	v_mfma_f32_16x16x32_bf16 v[6:9], v[150:153], v[206:209], v[6:9]
	v_mfma_f32_16x16x32_bf16 v[2:5], v[168:171], v[206:209], v[2:5]
	s_setprio 0
	s_add_i32 s56, s56, 2
	s_add_u32 s28, s28, 0x100
	s_addc_u32 s29, s29, 0
	s_add_u32 s23, s23, 0x100
	s_addc_u32 s54, s54, 0
	s_cmp_gt_u32 s56, 29
	s_cbranch_scc0 .LBB0_200
	s_and_b64 vcc, exec, s[14:15]
	s_cbranch_vccz .LBB0_203
	s_barrier

; #define PG8_STAGE(bufoff, gbase, voff) do { _Pragma("unroll") for (int _i = 0; _i < 2; ++_i) \
;         __builtin_amdgcn_global_load_lds((const unsigned*)((const char*)(gbase) + (voff)[_i]), (LAS unsigned*)(lds + (bufoff) + ldsw + _i * 8192), 16, 0, 0); } while (0)
; #define PG8_LDA(dst, b, h) do { _Pragma("unroll") for (int m = 0; m < NM; ++m) _Pragma("unroll") for (int k = 0; k < 2; ++k) dst[m][k] = *(const LAS bf16x8*)(lds + PG8_SA(b, h) + aoff + m * 2048 + k * 1024); } while (0)
; #define PG8_LDB(dst, b, h) do { _Pragma("unroll") for (int n = 0; n < 2; ++n) _Pragma("unroll") for (int k = 0; k < 2; ++k) dst[n][k] = *(const LAS bf16x8*)(lds + PG8_SB(b, h) + boff + n * 2048 + k * 1024); } while (0)
; #define PG8_MMA(ai, bj, At, Bt) do { __builtin_amdgcn_s_setprio(1); _Pragma("unroll") for (int m = 0; m < NM; ++m) _Pragma("unroll") for (int n = 0; n < 2; ++n) _Pragma("unroll") for (int k = 0; k < 2; ++k) \
;         acc[ai][bj][m][n] = __builtin_amdgcn_mfma_f32_16x16x32_bf16(Bt[n][k], At[m][k], acc[ai][bj][m][n], 0, 0, 0); __builtin_amdgcn_s_setprio(0); } while (0)
; #define PG8_WAIT_V(n) asm volatile("s_waitcnt vmcnt(" #n ")" ::: "memory")
; #define PG8_WAIT_L(n) asm volatile("s_waitcnt lgkmcnt(" #n ")" ::: "memory")
; #define PG8_BAR __builtin_amdgcn_s_barrier()
; #define PG8_SCHED __builtin_amdgcn_sched_barrier(0)
;     ...
;             PG8_LDB(B0, 0, 0); PG8_LDB(B1, 0, 1); PG8_SCHED; PG8_LDA(At, 0, 0); PG8_STAGE(PG8_SA(1, 1), a1 + hstepA, voffA);
;             PG8_WAIT_V(8); PG8_WAIT_L(0); PG8_BAR; PG8_MMA(0, 0, At, B0); PG8_MMA(0, 1, At, B1); PG8_BAR; PG8_SCHED;
;             PG8_LDA(At, 0, 1); PG8_STAGE(PG8_SB(0, 0), b2, voffB); PG8_STAGE(PG8_SB(0, 1), b2 + hstepB, voffB); PG8_STAGE(PG8_SA(0, 0), a2, voffA);
.LBB0_703:
	v_add_u32_e32 v0, s50, v146
	ds_read_b128 v[138:141], v0
	ds_read_b128 v[142:145], v0 offset:1024
	ds_read_b128 v[148:151], v0 offset:2048
	ds_read_b128 v[152:155], v0 offset:3072
	v_add_u32_e32 v0, s54, v146
	ds_read_b128 v[156:159], v0
	ds_read_b128 v[160:163], v0 offset:1024
	ds_read_b128 v[164:167], v0 offset:2048
	ds_read_b128 v[168:171], v0 offset:3072
	s_add_u32 s12, s10, 0xfff80080
	s_addc_u32 s13, s11, -1
	s_cmp_eq_u32 s39, 28
	s_cselect_b32 s37, s2, s13
	s_cselect_b32 s36, s3, s12
	s_cselect_b32 s13, s9, s38
	s_cselect_b32 s12, s27, s29
	s_cselect_b32 s100, -1, 0
	s_andn2_b32 s100, s100, s101
	s_add_i32 m0, s58, 0xc000
	ds_read_b128 v[172:175], v147
	ds_read_b128 v[176:179], v147 offset:1024
	ds_read_b128 v[180:183], v147 offset:2048
	ds_read_b128 v[184:187], v147 offset:3072
	ds_read_b128 v[188:191], v147 offset:4096
	ds_read_b128 v[192:195], v147 offset:5120
	ds_read_b128 v[196:199], v147 offset:6144
	ds_read_b128 v[200:203], v147 offset:7168
	global_load_lds_dwordx4 v134, s[10:11]
	s_add_i32 m0, s58, 0xe000
	s_nop 0
	global_load_lds_dwordx4 v136, s[10:11]
	s_waitcnt vmcnt(8)
	s_waitcnt lgkmcnt(0)
	s_barrier
	s_setprio 1
	s_waitcnt lgkmcnt(0)
	v_mfma_f32_16x16x32_bf16 v[126:129], v[138:141], v[172:175], v[126:129]
	v_mfma_f32_16x16x32_bf16 v[122:125], v[148:151], v[172:175], v[122:125]
	v_mfma_f32_16x16x32_bf16 v[110:113], v[138:141], v[180:183], v[110:113]
	v_mfma_f32_16x16x32_bf16 v[106:109], v[148:151], v[180:183], v[106:109]
	v_mfma_f32_16x16x32_bf16 v[94:97], v[138:141], v[188:191], v[94:97]
	v_mfma_f32_16x16x32_bf16 v[90:93], v[148:151], v[188:191], v[90:93]
	v_mfma_f32_16x16x32_bf16 v[78:81], v[138:141], v[196:199], v[78:81]
	v_mfma_f32_16x16x32_bf16 v[74:77], v[148:151], v[196:199], v[74:77]
	v_mfma_f32_16x16x32_bf16 v[126:129], v[142:145], v[176:179], v[126:129]
	v_mfma_f32_16x16x32_bf16 v[122:125], v[152:155], v[176:179], v[122:125]
	v_mfma_f32_16x16x32_bf16 v[110:113], v[142:145], v[184:187], v[110:113]
	v_mfma_f32_16x16x32_bf16 v[106:109], v[152:155], v[184:187], v[106:109]
	v_mfma_f32_16x16x32_bf16 v[94:97], v[142:145], v[192:195], v[94:97]
	v_mfma_f32_16x16x32_bf16 v[90:93], v[152:155], v[192:195], v[90:93]
	v_mfma_f32_16x16x32_bf16 v[78:81], v[142:145], v[200:203], v[78:81]
	v_mfma_f32_16x16x32_bf16 v[74:77], v[152:155], v[200:203], v[74:77]
	s_setprio 0
	s_setprio 1
	v_mfma_f32_16x16x32_bf16 v[118:121], v[156:159], v[172:175], v[118:121]
	v_mfma_f32_16x16x32_bf16 v[114:117], v[164:167], v[172:175], v[114:117]
	v_mfma_f32_16x16x32_bf16 v[102:105], v[156:159], v[180:183], v[102:105]
	v_mfma_f32_16x16x32_bf16 v[98:101], v[164:167], v[180:183], v[98:101]
	v_mfma_f32_16x16x32_bf16 v[86:89], v[156:159], v[188:191], v[86:89]
	v_mfma_f32_16x16x32_bf16 v[82:85], v[164:167], v[188:191], v[82:85]
	v_mfma_f32_16x16x32_bf16 v[70:73], v[156:159], v[196:199], v[70:73]
	v_mfma_f32_16x16x32_bf16 v[66:69], v[164:167], v[196:199], v[66:69]
	v_mfma_f32_16x16x32_bf16 v[118:121], v[160:163], v[176:179], v[118:121]
	v_mfma_f32_16x16x32_bf16 v[114:117], v[168:171], v[176:179], v[114:117]
	v_mfma_f32_16x16x32_bf16 v[102:105], v[160:163], v[184:187], v[102:105]
	v_mfma_f32_16x16x32_bf16 v[98:101], v[168:171], v[184:187], v[98:101]
	v_mfma_f32_16x16x32_bf16 v[86:89], v[160:163], v[192:195], v[86:89]
	v_mfma_f32_16x16x32_bf16 v[82:85], v[168:171], v[192:195], v[82:85]
	s_setprio 2
	s_barrier
	v_mfma_f32_16x16x32_bf16 v[70:73], v[160:163], v[200:203], v[70:73]
	v_mfma_f32_16x16x32_bf16 v[66:69], v[168:171], v[200:203], v[66:69]
	s_setprio 0
	s_mov_b32 m0, s51
	v_lshl_add_u64 v[204:205], s[12:13], 0, v[130:131]
	s_add_u32 s40, s12, 0x80000
	s_addc_u32 s41, s13, 0
	ds_read_b128 v[172:175], v147 offset:16384
	ds_read_b128 v[176:179], v147 offset:17408
	ds_read_b128 v[180:183], v147 offset:18432
	ds_read_b128 v[184:187], v147 offset:19456
	ds_read_b128 v[188:191], v147 offset:20480
	ds_read_b128 v[192:195], v147 offset:21504
	ds_read_b128 v[196:199], v147 offset:22528
	ds_read_b128 v[200:203], v147 offset:23552
	s_cmp_lg_u32 s100, 0
	s_cbranch_scc1 .Ltl_ia_0s
	global_load_lds_dwordx4 v130, s[12:13]
	v_lshl_add_u64 v[206:207], s[12:13], 0, v[132:133]
	s_mov_b32 m0, s52
	s_nop 0
	global_load_lds_dwordx4 v132, s[12:13]
	s_mov_b32 m0, s56
	v_lshl_add_u64 v[210:211], s[36:37], 0, v[132:133]
	global_load_lds_dwordx4 v130, s[40:41]
	s_mov_b32 m0, s57
	s_nop 0
	global_load_lds_dwordx4 v132, s[40:41]
	v_lshl_add_u64 v[208:209], s[36:37], 0, v[130:131]
	s_mov_b32 m0, s58
	s_nop 0
	global_load_lds_dwordx4 v130, s[36:37]
	s_mov_b32 m0, s59
	s_nop 0
	global_load_lds_dwordx4 v132, s[36:37]
	s_waitcnt vmcnt(8)
	s_branch .Ltl_ia_0d

; #define PG8_STAGE(bufoff, gbase, voff) do { _Pragma("unroll") for (int _i = 0; _i < 2; ++_i) \
;         __builtin_amdgcn_global_load_lds((const unsigned*)((const char*)(gbase) + (voff)[_i]), (LAS unsigned*)(lds + (bufoff) + ldsw + _i * 8192), 16, 0, 0); } while (0)
; #define PG8_LDA(dst, b, h) do { _Pragma("unroll") for (int m = 0; m < NM; ++m) _Pragma("unroll") for (int k = 0; k < 2; ++k) dst[m][k] = *(const LAS bf16x8*)(lds + PG8_SA(b, h) + aoff + m * 2048 + k * 1024); } while (0)
; #define PG8_LDB(dst, b, h) do { _Pragma("unroll") for (int n = 0; n < 2; ++n) _Pragma("unroll") for (int k = 0; k < 2; ++k) dst[n][k] = *(const LAS bf16x8*)(lds + PG8_SB(b, h) + boff + n * 2048 + k * 1024); } while (0)
; #define PG8_MMA(ai, bj, At, Bt) do { __builtin_amdgcn_s_setprio(1); _Pragma("unroll") for (int m = 0; m < NM; ++m) _Pragma("unroll") for (int n = 0; n < 2; ++n) _Pragma("unroll") for (int k = 0; k < 2; ++k) \
;         acc[ai][bj][m][n] = __builtin_amdgcn_mfma_f32_16x16x32_bf16(Bt[n][k], At[m][k], acc[ai][bj][m][n], 0, 0, 0); __builtin_amdgcn_s_setprio(0); } while (0)
; #define PG8_WAIT_V(n) asm volatile("s_waitcnt vmcnt(" #n ")" ::: "memory")
; #define PG8_WAIT_L(n) asm volatile("s_waitcnt lgkmcnt(" #n ")" ::: "memory")
; #define PG8_BAR __builtin_amdgcn_s_barrier()
; #define PG8_SCHED __builtin_amdgcn_sched_barrier(0)
;     ...
;             PG8_WAIT_V(8); PG8_WAIT_L(0); PG8_BAR; PG8_MMA(1, 0, At, B0); PG8_MMA(1, 1, At, B1); PG8_BAR; PG8_SCHED;
;             PG8_LDB(B0, 1, 0); PG8_LDB(B1, 1, 1); PG8_SCHED; PG8_LDA(At, 1, 0); PG8_STAGE(PG8_SA(0, 1), a2 + hstepA, voffA);
.Ltl_ia_0d:
	s_waitcnt lgkmcnt(0)
	s_barrier
	s_setprio 1
	s_waitcnt lgkmcnt(0)
	v_mfma_f32_16x16x32_bf16 v[62:65], v[138:141], v[172:175], v[62:65]
	v_mfma_f32_16x16x32_bf16 v[58:61], v[148:151], v[172:175], v[58:61]
	v_mfma_f32_16x16x32_bf16 v[46:49], v[138:141], v[180:183], v[46:49]
	v_mfma_f32_16x16x32_bf16 v[42:45], v[148:151], v[180:183], v[42:45]
	v_mfma_f32_16x16x32_bf16 v[30:33], v[138:141], v[188:191], v[30:33]
	v_mfma_f32_16x16x32_bf16 v[26:29], v[148:151], v[188:191], v[26:29]
	v_mfma_f32_16x16x32_bf16 v[14:17], v[138:141], v[196:199], v[14:17]
	v_mfma_f32_16x16x32_bf16 v[10:13], v[148:151], v[196:199], v[10:13]
	v_mfma_f32_16x16x32_bf16 v[62:65], v[142:145], v[176:179], v[62:65]
	v_mfma_f32_16x16x32_bf16 v[58:61], v[152:155], v[176:179], v[58:61]
	v_mfma_f32_16x16x32_bf16 v[46:49], v[142:145], v[184:187], v[46:49]
	v_mfma_f32_16x16x32_bf16 v[42:45], v[152:155], v[184:187], v[42:45]
	v_mfma_f32_16x16x32_bf16 v[30:33], v[142:145], v[192:195], v[30:33]
	v_mfma_f32_16x16x32_bf16 v[26:29], v[152:155], v[192:195], v[26:29]
	v_mfma_f32_16x16x32_bf16 v[14:17], v[142:145], v[200:203], v[14:17]
	v_mfma_f32_16x16x32_bf16 v[10:13], v[152:155], v[200:203], v[10:13]
	s_setprio 0
	s_setprio 1
	v_mfma_f32_16x16x32_bf16 v[54:57], v[156:159], v[172:175], v[54:57]
	v_mfma_f32_16x16x32_bf16 v[50:53], v[164:167], v[172:175], v[50:53]
	v_mfma_f32_16x16x32_bf16 v[38:41], v[156:159], v[180:183], v[38:41]
	v_mfma_f32_16x16x32_bf16 v[34:37], v[164:167], v[180:183], v[34:37]
	v_mfma_f32_16x16x32_bf16 v[22:25], v[156:159], v[188:191], v[22:25]
	v_mfma_f32_16x16x32_bf16 v[18:21], v[164:167], v[188:191], v[18:21]
	v_mfma_f32_16x16x32_bf16 v[6:9], v[156:159], v[196:199], v[6:9]
	v_mfma_f32_16x16x32_bf16 v[2:5], v[164:167], v[196:199], v[2:5]
	v_mfma_f32_16x16x32_bf16 v[54:57], v[160:163], v[176:179], v[54:57]
	v_mfma_f32_16x16x32_bf16 v[50:53], v[168:171], v[176:179], v[50:53]
	v_mfma_f32_16x16x32_bf16 v[38:41], v[160:163], v[184:187], v[38:41]
	v_mfma_f32_16x16x32_bf16 v[34:37], v[168:171], v[184:187], v[34:37]
	v_mfma_f32_16x16x32_bf16 v[22:25], v[160:163], v[192:195], v[22:25]
	v_mfma_f32_16x16x32_bf16 v[18:21], v[168:171], v[192:195], v[18:21]
	s_setprio 2
	s_barrier
	v_mfma_f32_16x16x32_bf16 v[6:9], v[160:163], v[200:203], v[6:9]
	v_mfma_f32_16x16x32_bf16 v[2:5], v[168:171], v[200:203], v[2:5]
	s_setprio 0
	v_add_u32_e32 v0, s64, v146
	ds_read_b128 v[138:141], v0
	ds_read_b128 v[142:145], v0 offset:1024
	ds_read_b128 v[148:151], v0 offset:2048
	ds_read_b128 v[152:155], v0 offset:3072
	v_add_u32_e32 v0, s71, v146
	ds_read_b128 v[156:159], v0
	ds_read_b128 v[160:163], v0 offset:1024
	ds_read_b128 v[164:167], v0 offset:2048
	ds_read_b128 v[168:171], v0 offset:3072
	s_add_u32 s36, s36, 0x80000
	s_addc_u32 s37, s37, 0
	s_mov_b32 m0, s62
	ds_read_b128 v[172:175], v147 offset:32768
	ds_read_b128 v[176:179], v147 offset:33792
	ds_read_b128 v[180:183], v147 offset:34816
	ds_read_b128 v[184:187], v147 offset:35840
	ds_read_b128 v[188:191], v147 offset:36864
	ds_read_b128 v[192:195], v147 offset:37888
	ds_read_b128 v[196:199], v147 offset:38912
	ds_read_b128 v[200:203], v147 offset:39936
	s_cmp_lg_u32 s100, 0
	s_cbranch_scc1 .Ltl_ia_1s
	global_load_lds_dwordx4 v130, s[36:37]
	s_mov_b32 m0, s63
	s_nop 0
	global_load_lds_dwordx4 v132, s[36:37]
	s_waitcnt vmcnt(8)
	s_branch .Ltl_ia_1d

; #define PG8_STAGE(bufoff, gbase, voff) do { _Pragma("unroll") for (int _i = 0; _i < 2; ++_i) \
;         __builtin_amdgcn_global_load_lds((const unsigned*)((const char*)(gbase) + (voff)[_i]), (LAS unsigned*)(lds + (bufoff) + ldsw + _i * 8192), 16, 0, 0); } while (0)
; #define PG8_LDA(dst, b, h) do { _Pragma("unroll") for (int m = 0; m < NM; ++m) _Pragma("unroll") for (int k = 0; k < 2; ++k) dst[m][k] = *(const LAS bf16x8*)(lds + PG8_SA(b, h) + aoff + m * 2048 + k * 1024); } while (0)
; #define PG8_MMA(ai, bj, At, Bt) do { __builtin_amdgcn_s_setprio(1); _Pragma("unroll") for (int m = 0; m < NM; ++m) _Pragma("unroll") for (int n = 0; n < 2; ++n) _Pragma("unroll") for (int k = 0; k < 2; ++k) \
;         acc[ai][bj][m][n] = __builtin_amdgcn_mfma_f32_16x16x32_bf16(Bt[n][k], At[m][k], acc[ai][bj][m][n], 0, 0, 0); __builtin_amdgcn_s_setprio(0); } while (0)
; #define PG8_WAIT_V(n) asm volatile("s_waitcnt vmcnt(" #n ")" ::: "memory")
; #define PG8_WAIT_L(n) asm volatile("s_waitcnt lgkmcnt(" #n ")" ::: "memory")
; #define PG8_BAR __builtin_amdgcn_s_barrier()
; #define PG8_SCHED __builtin_amdgcn_sched_barrier(0)
;     ...
;             PG8_WAIT_V(8); PG8_WAIT_L(0); PG8_BAR; PG8_MMA(0, 0, At, B0); PG8_MMA(0, 1, At, B1); PG8_BAR; PG8_SCHED;
;             PG8_LDA(At, 1, 1); PG8_STAGE(PG8_SB(1, 0), b3, voffB); PG8_STAGE(PG8_SB(1, 1), b3 + hstepB, voffB); PG8_STAGE(PG8_SA(1, 0), a3, voffA);
.Ltl_ia_1d:
	s_waitcnt lgkmcnt(0)
	s_barrier
	s_setprio 1
	s_waitcnt lgkmcnt(0)
	v_mfma_f32_16x16x32_bf16 v[126:129], v[138:141], v[172:175], v[126:129]
	v_mfma_f32_16x16x32_bf16 v[122:125], v[148:151], v[172:175], v[122:125]
	v_mfma_f32_16x16x32_bf16 v[110:113], v[138:141], v[180:183], v[110:113]
	v_mfma_f32_16x16x32_bf16 v[106:109], v[148:151], v[180:183], v[106:109]
	v_mfma_f32_16x16x32_bf16 v[94:97], v[138:141], v[188:191], v[94:97]
	v_mfma_f32_16x16x32_bf16 v[90:93], v[148:151], v[188:191], v[90:93]
	v_mfma_f32_16x16x32_bf16 v[78:81], v[138:141], v[196:199], v[78:81]
	v_mfma_f32_16x16x32_bf16 v[74:77], v[148:151], v[196:199], v[74:77]
	v_mfma_f32_16x16x32_bf16 v[126:129], v[142:145], v[176:179], v[126:129]
	v_mfma_f32_16x16x32_bf16 v[122:125], v[152:155], v[176:179], v[122:125]
	v_mfma_f32_16x16x32_bf16 v[110:113], v[142:145], v[184:187], v[110:113]
	v_mfma_f32_16x16x32_bf16 v[106:109], v[152:155], v[184:187], v[106:109]
	v_mfma_f32_16x16x32_bf16 v[94:97], v[142:145], v[192:195], v[94:97]
	v_mfma_f32_16x16x32_bf16 v[90:93], v[152:155], v[192:195], v[90:93]
	v_mfma_f32_16x16x32_bf16 v[78:81], v[142:145], v[200:203], v[78:81]
	v_mfma_f32_16x16x32_bf16 v[74:77], v[152:155], v[200:203], v[74:77]
	s_setprio 0
	s_setprio 1
	v_mfma_f32_16x16x32_bf16 v[118:121], v[156:159], v[172:175], v[118:121]
	v_mfma_f32_16x16x32_bf16 v[114:117], v[164:167], v[172:175], v[114:117]
	v_mfma_f32_16x16x32_bf16 v[102:105], v[156:159], v[180:183], v[102:105]
	v_mfma_f32_16x16x32_bf16 v[98:101], v[164:167], v[180:183], v[98:101]
	v_mfma_f32_16x16x32_bf16 v[86:89], v[156:159], v[188:191], v[86:89]
	v_mfma_f32_16x16x32_bf16 v[82:85], v[164:167], v[188:191], v[82:85]
	v_mfma_f32_16x16x32_bf16 v[70:73], v[156:159], v[196:199], v[70:73]
	v_mfma_f32_16x16x32_bf16 v[66:69], v[164:167], v[196:199], v[66:69]
	v_mfma_f32_16x16x32_bf16 v[118:121], v[160:163], v[176:179], v[118:121]
	v_mfma_f32_16x16x32_bf16 v[114:117], v[168:171], v[176:179], v[114:117]
	v_mfma_f32_16x16x32_bf16 v[102:105], v[160:163], v[184:187], v[102:105]
	v_mfma_f32_16x16x32_bf16 v[98:101], v[168:171], v[184:187], v[98:101]
	v_mfma_f32_16x16x32_bf16 v[86:89], v[160:163], v[192:195], v[86:89]
	v_mfma_f32_16x16x32_bf16 v[82:85], v[168:171], v[192:195], v[82:85]
	s_setprio 2
	s_barrier
	v_mfma_f32_16x16x32_bf16 v[70:73], v[160:163], v[200:203], v[70:73]
	v_mfma_f32_16x16x32_bf16 v[66:69], v[168:171], v[200:203], v[66:69]
	s_setprio 0
	s_mov_b32 m0, s65
	v_lshl_add_u64 v[204:205], v[204:205], 0, s[66:67]
	s_add_u32 s12, s12, 0x80080
	s_addc_u32 s13, s13, 0
	ds_read_b128 v[172:175], v147 offset:49152
	ds_read_b128 v[176:179], v147 offset:50176
	ds_read_b128 v[180:183], v147 offset:51200
	ds_read_b128 v[184:187], v147 offset:52224
	ds_read_b128 v[188:191], v147 offset:53248
	ds_read_b128 v[192:195], v147 offset:54272
	ds_read_b128 v[196:199], v147 offset:55296
	ds_read_b128 v[200:203], v147 offset:56320
	s_cmp_lg_u32 s100, 0
	s_cbranch_scc1 .Ltl_ia_2s
	global_load_lds_dwordx4 v[204:205], off
	v_lshl_add_u64 v[204:205], v[206:207], 0, s[66:67]
	s_mov_b32 m0, s68
	s_nop 0
	global_load_lds_dwordx4 v[204:205], off
	s_mov_b32 m0, s72
	s_nop 0
	global_load_lds_dwordx4 v130, s[12:13]
	s_mov_b32 m0, s73
	s_nop 0
	global_load_lds_dwordx4 v132, s[12:13]
	v_lshl_add_u64 v[204:205], v[208:209], 0, s[66:67]
	s_mov_b32 m0, s69
	s_nop 0
	global_load_lds_dwordx4 v[204:205], off
	v_lshl_add_u64 v[204:205], v[210:211], 0, s[66:67]
	s_mov_b32 m0, s70
	s_nop 0
	global_load_lds_dwordx4 v[204:205], off
	s_waitcnt vmcnt(8)
	s_branch .Ltl_ia_2d

; #define PG8_STAGE(bufoff, gbase, voff) do { _Pragma("unroll") for (int _i = 0; _i < 2; ++_i) \
;         __builtin_amdgcn_global_load_lds((const unsigned*)((const char*)(gbase) + (voff)[_i]), (LAS unsigned*)(lds + (bufoff) + ldsw + _i * 8192), 16, 0, 0); } while (0)
; #define PG8_LDA(dst, b, h) do { _Pragma("unroll") for (int m = 0; m < NM; ++m) _Pragma("unroll") for (int k = 0; k < 2; ++k) dst[m][k] = *(const LAS bf16x8*)(lds + PG8_SA(b, h) + aoff + m * 2048 + k * 1024); } while (0)
; #define PG8_MMA(ai, bj, At, Bt) do { __builtin_amdgcn_s_setprio(1); _Pragma("unroll") for (int m = 0; m < NM; ++m) _Pragma("unroll") for (int n = 0; n < 2; ++n) _Pragma("unroll") for (int k = 0; k < 2; ++k) \
;         acc[ai][bj][m][n] = __builtin_amdgcn_mfma_f32_16x16x32_bf16(Bt[n][k], At[m][k], acc[ai][bj][m][n], 0, 0, 0); __builtin_amdgcn_s_setprio(0); } while (0)
; #define PG8_WAIT_V(n) asm volatile("s_waitcnt vmcnt(" #n ")" ::: "memory")
; #define PG8_WAIT_L(n) asm volatile("s_waitcnt lgkmcnt(" #n ")" ::: "memory")
; #define PG8_BAR __builtin_amdgcn_s_barrier()
; #define PG8_SCHED __builtin_amdgcn_sched_barrier(0)
;     ...
;             PG8_WAIT_V(8); PG8_WAIT_L(0); PG8_BAR; PG8_MMA(0, 0, At, B0); PG8_MMA(0, 1, At, B1); PG8_BAR; PG8_SCHED;
;             PG8_LDA(At, 1, 1); PG8_STAGE(PG8_SB(1, 0), b3, voffB); PG8_STAGE(PG8_SB(1, 1), b3 + hstepB, voffB); PG8_STAGE(PG8_SA(1, 0), a3, voffA);
;             PG8_WAIT_V(8); PG8_WAIT_L(0); PG8_BAR; PG8_MMA(1, 0, At, B0); PG8_MMA(1, 1, At, B1); PG8_BAR; PG8_SCHED;
.Ltl_ia_2d:
	s_waitcnt lgkmcnt(0)
	s_barrier
	s_setprio 1
	s_waitcnt lgkmcnt(0)
	v_mfma_f32_16x16x32_bf16 v[62:65], v[138:141], v[172:175], v[62:65]
	v_mfma_f32_16x16x32_bf16 v[58:61], v[148:151], v[172:175], v[58:61]
	v_mfma_f32_16x16x32_bf16 v[46:49], v[138:141], v[180:183], v[46:49]
	v_mfma_f32_16x16x32_bf16 v[42:45], v[148:151], v[180:183], v[42:45]
	v_mfma_f32_16x16x32_bf16 v[30:33], v[138:141], v[188:191], v[30:33]
	v_mfma_f32_16x16x32_bf16 v[26:29], v[148:151], v[188:191], v[26:29]
	v_mfma_f32_16x16x32_bf16 v[14:17], v[138:141], v[196:199], v[14:17]
	v_mfma_f32_16x16x32_bf16 v[10:13], v[148:151], v[196:199], v[10:13]
	v_mfma_f32_16x16x32_bf16 v[62:65], v[142:145], v[176:179], v[62:65]
	v_mfma_f32_16x16x32_bf16 v[58:61], v[152:155], v[176:179], v[58:61]
	v_mfma_f32_16x16x32_bf16 v[46:49], v[142:145], v[184:187], v[46:49]
	v_mfma_f32_16x16x32_bf16 v[42:45], v[152:155], v[184:187], v[42:45]
	v_mfma_f32_16x16x32_bf16 v[30:33], v[142:145], v[192:195], v[30:33]
	v_mfma_f32_16x16x32_bf16 v[26:29], v[152:155], v[192:195], v[26:29]
	v_mfma_f32_16x16x32_bf16 v[14:17], v[142:145], v[200:203], v[14:17]
	v_mfma_f32_16x16x32_bf16 v[10:13], v[152:155], v[200:203], v[10:13]
	s_setprio 0
	s_setprio 1
	v_mfma_f32_16x16x32_bf16 v[54:57], v[156:159], v[172:175], v[54:57]
	v_mfma_f32_16x16x32_bf16 v[50:53], v[164:167], v[172:175], v[50:53]
	v_mfma_f32_16x16x32_bf16 v[38:41], v[156:159], v[180:183], v[38:41]
	v_mfma_f32_16x16x32_bf16 v[34:37], v[164:167], v[180:183], v[34:37]
	v_mfma_f32_16x16x32_bf16 v[22:25], v[156:159], v[188:191], v[22:25]
	v_mfma_f32_16x16x32_bf16 v[18:21], v[164:167], v[188:191], v[18:21]
	v_mfma_f32_16x16x32_bf16 v[6:9], v[156:159], v[196:199], v[6:9]
	v_mfma_f32_16x16x32_bf16 v[2:5], v[164:167], v[196:199], v[2:5]
	v_mfma_f32_16x16x32_bf16 v[54:57], v[160:163], v[176:179], v[54:57]
	v_mfma_f32_16x16x32_bf16 v[50:53], v[168:171], v[176:179], v[50:53]
	v_mfma_f32_16x16x32_bf16 v[38:41], v[160:163], v[184:187], v[38:41]
	v_mfma_f32_16x16x32_bf16 v[34:37], v[168:171], v[184:187], v[34:37]
	v_mfma_f32_16x16x32_bf16 v[22:25], v[160:163], v[192:195], v[22:25]
	v_mfma_f32_16x16x32_bf16 v[18:21], v[168:171], v[192:195], v[18:21]
	s_setprio 2
	s_barrier
	v_mfma_f32_16x16x32_bf16 v[6:9], v[160:163], v[200:203], v[6:9]
	v_mfma_f32_16x16x32_bf16 v[2:5], v[168:171], v[200:203], v[2:5]
	s_setprio 0
	s_add_i32 s39, s39, 2
	s_add_u32 s10, s10, 0x100
	s_addc_u32 s11, s11, 0
	s_add_u32 s29, s29, 0x100
	s_addc_u32 s38, s38, 0
	s_cmp_gt_u32 s39, 29
	s_cbranch_scc0 .LBB0_703
	s_and_b64 vcc, exec, s[18:19]
	s_cbranch_vccz .LBB0_706
	s_barrier

; #define PG8_STAGE(bufoff, gbase, voff) do { _Pragma("unroll") for (int _i = 0; _i < 2; ++_i) \
;         __builtin_amdgcn_global_load_lds((const unsigned*)((const char*)(gbase) + (voff)[_i]), (LAS unsigned*)(lds + (bufoff) + ldsw + _i * 8192), 16, 0, 0); } while (0)
; #define PG8_LDA(dst, b, h) do { _Pragma("unroll") for (int m = 0; m < NM; ++m) _Pragma("unroll") for (int k = 0; k < 2; ++k) dst[m][k] = *(const LAS bf16x8*)(lds + PG8_SA(b, h) + aoff + m * 2048 + k * 1024); } while (0)
; #define PG8_LDB(dst, b, h) do { _Pragma("unroll") for (int n = 0; n < 2; ++n) _Pragma("unroll") for (int k = 0; k < 2; ++k) dst[n][k] = *(const LAS bf16x8*)(lds + PG8_SB(b, h) + boff + n * 2048 + k * 1024); } while (0)
; #define PG8_MMA(ai, bj, At, Bt) do { __builtin_amdgcn_s_setprio(1); _Pragma("unroll") for (int m = 0; m < NM; ++m) _Pragma("unroll") for (int n = 0; n < 2; ++n) _Pragma("unroll") for (int k = 0; k < 2; ++k) \
;         acc[ai][bj][m][n] = __builtin_amdgcn_mfma_f32_16x16x32_bf16(Bt[n][k], At[m][k], acc[ai][bj][m][n], 0, 0, 0); __builtin_amdgcn_s_setprio(0); } while (0)
; #define PG8_WAIT_V(n) asm volatile("s_waitcnt vmcnt(" #n ")" ::: "memory")
; #define PG8_WAIT_L(n) asm volatile("s_waitcnt lgkmcnt(" #n ")" ::: "memory")
; #define PG8_BAR __builtin_amdgcn_s_barrier()
; #define PG8_SCHED __builtin_amdgcn_sched_barrier(0)
;     ...
;             PG8_LDB(B0, 0, 0); PG8_LDB(B1, 0, 1); PG8_SCHED; PG8_LDA(At, 0, 0); PG8_STAGE(PG8_SA(1, 1), a1 + hstepA, voffA);
;             PG8_WAIT_V(8); PG8_WAIT_L(0); PG8_BAR; PG8_MMA(0, 0, At, B0); PG8_MMA(0, 1, At, B1); PG8_BAR; PG8_SCHED;
;             PG8_LDA(At, 0, 1); PG8_STAGE(PG8_SB(0, 0), b2, voffB); PG8_STAGE(PG8_SB(0, 1), b2 + hstepB, voffB); PG8_STAGE(PG8_SA(0, 0), a2, voffA);
.LBB0_1192:
	v_add_u32_e32 v0, s49, v216
	ds_read_b128 v[10:13], v0
	ds_read_b128 v[14:17], v0 offset:1024
	ds_read_b128 v[18:21], v0 offset:2048
	ds_read_b128 v[22:25], v0 offset:3072
	v_add_u32_e32 v0, s58, v216
	ds_read_b128 v[26:29], v0
	ds_read_b128 v[30:33], v0 offset:1024
	ds_read_b128 v[42:45], v0 offset:2048
	ds_read_b128 v[46:49], v0 offset:3072
	s_add_u32 s12, s10, 0xfffe0080
	s_addc_u32 s13, s11, -1
	s_cmp_eq_u32 s54, 4
	s_cselect_b32 s35, s2, s13
	s_cselect_b32 s34, s3, s12
	s_cselect_b32 s13, s7, s52
	s_cselect_b32 s12, s27, s9
	s_cselect_b32 s100, -1, 0
	s_andn2_b32 s100, s100, s101
	s_add_i32 m0, s62, 0xc000
	ds_read_b128 v[50:53], v217
	ds_read_b128 v[54:57], v217 offset:1024
	ds_read_b128 v[58:61], v217 offset:2048
	ds_read_b128 v[62:65], v217 offset:3072
	ds_read_b128 v[178:181], v217 offset:4096
	ds_read_b128 v[182:185], v217 offset:5120
	ds_read_b128 v[198:201], v217 offset:6144
	ds_read_b128 v[208:211], v217 offset:7168
	global_load_lds_dwordx4 v194, s[10:11]
	s_add_i32 m0, s62, 0xe000
	s_nop 0
	global_load_lds_dwordx4 v196, s[10:11]
	s_waitcnt vmcnt(8)
	s_waitcnt lgkmcnt(0)
	s_barrier
	s_setprio 1
	s_waitcnt lgkmcnt(0)
	v_mfma_f32_16x16x32_bf16 v[38:41], v[10:13], v[50:53], v[38:41]
	v_mfma_f32_16x16x32_bf16 v[34:37], v[18:21], v[50:53], v[34:37]
	v_mfma_f32_16x16x32_bf16 v[174:177], v[10:13], v[58:61], v[174:177]
	v_mfma_f32_16x16x32_bf16 v[170:173], v[18:21], v[58:61], v[170:173]
	v_mfma_f32_16x16x32_bf16 v[158:161], v[10:13], v[178:181], v[158:161]
	v_mfma_f32_16x16x32_bf16 v[154:157], v[18:21], v[178:181], v[154:157]
	v_mfma_f32_16x16x32_bf16 v[142:145], v[10:13], v[198:201], v[142:145]
	v_mfma_f32_16x16x32_bf16 v[138:141], v[18:21], v[198:201], v[138:141]
	v_mfma_f32_16x16x32_bf16 v[38:41], v[14:17], v[54:57], v[38:41]
	v_mfma_f32_16x16x32_bf16 v[34:37], v[22:25], v[54:57], v[34:37]
	v_mfma_f32_16x16x32_bf16 v[174:177], v[14:17], v[62:65], v[174:177]
	v_mfma_f32_16x16x32_bf16 v[170:173], v[22:25], v[62:65], v[170:173]
	v_mfma_f32_16x16x32_bf16 v[158:161], v[14:17], v[182:185], v[158:161]
	v_mfma_f32_16x16x32_bf16 v[154:157], v[22:25], v[182:185], v[154:157]
	v_mfma_f32_16x16x32_bf16 v[142:145], v[14:17], v[208:211], v[142:145]
	v_mfma_f32_16x16x32_bf16 v[138:141], v[22:25], v[208:211], v[138:141]
	s_setprio 0
	s_setprio 1
	v_mfma_f32_16x16x32_bf16 v[6:9], v[26:29], v[50:53], v[6:9]
	v_mfma_f32_16x16x32_bf16 v[2:5], v[42:45], v[50:53], v[2:5]
	v_mfma_f32_16x16x32_bf16 v[6:9], v[30:33], v[54:57], v[6:9]
	v_mfma_f32_16x16x32_bf16 v[2:5], v[46:49], v[54:57], v[2:5]
	v_mfma_f32_16x16x32_bf16 v[50:53], v[26:29], v[58:61], v[166:169]
	v_mfma_f32_16x16x32_bf16 v[54:57], v[42:45], v[58:61], v[162:165]
	v_mfma_f32_16x16x32_bf16 v[134:137], v[26:29], v[198:201], v[134:137]
	v_mfma_f32_16x16x32_bf16 v[130:133], v[42:45], v[198:201], v[130:133]
	v_mfma_f32_16x16x32_bf16 v[50:53], v[30:33], v[62:65], v[50:53]
	v_mfma_f32_16x16x32_bf16 v[54:57], v[46:49], v[62:65], v[54:57]
	v_mfma_f32_16x16x32_bf16 v[58:61], v[26:29], v[178:181], v[150:153]
	v_mfma_f32_16x16x32_bf16 v[62:65], v[42:45], v[178:181], v[146:149]
	v_mfma_f32_16x16x32_bf16 v[134:137], v[30:33], v[208:211], v[134:137]
	v_mfma_f32_16x16x32_bf16 v[130:133], v[46:49], v[208:211], v[130:133]
	s_setprio 2
	s_barrier
	v_mfma_f32_16x16x32_bf16 v[58:61], v[30:33], v[182:185], v[58:61]
	v_mfma_f32_16x16x32_bf16 v[62:65], v[46:49], v[182:185], v[62:65]
	s_setprio 0
	s_mov_b32 m0, s50
	v_lshl_add_u64 v[202:203], s[12:13], 0, v[188:189]
	s_add_u32 s56, s12, 0x20000
	s_addc_u32 s57, s13, 0
	ds_read_b128 v[146:149], v217 offset:16384
	ds_read_b128 v[150:153], v217 offset:17408
	ds_read_b128 v[162:165], v217 offset:18432
	ds_read_b128 v[166:169], v217 offset:19456
	ds_read_b128 v[178:181], v217 offset:20480
	ds_read_b128 v[182:185], v217 offset:21504
	ds_read_b128 v[198:201], v217 offset:22528
	ds_read_b128 v[208:211], v217 offset:23552
	s_cmp_lg_u32 s100, 0
	s_cbranch_scc1 .Ltl_qp_0s
	global_load_lds_dwordx4 v188, s[12:13]
	v_lshl_add_u64 v[204:205], s[12:13], 0, v[192:193]
	s_mov_b32 m0, s51
	s_nop 0
	global_load_lds_dwordx4 v192, s[12:13]
	s_mov_b32 m0, s59
	v_lshl_add_u64 v[222:223], s[34:35], 0, v[190:191]
	global_load_lds_dwordx4 v188, s[56:57]
	s_mov_b32 m0, s60
	s_nop 0
	global_load_lds_dwordx4 v192, s[56:57]
	v_lshl_add_u64 v[206:207], s[34:35], 0, v[186:187]
	s_mov_b32 m0, s62
	s_nop 0
	global_load_lds_dwordx4 v186, s[34:35]
	s_mov_b32 m0, s63
	s_nop 0
	global_load_lds_dwordx4 v190, s[34:35]
	s_waitcnt vmcnt(8)
	s_branch .Ltl_qp_0d

; #define PG8_STAGE(bufoff, gbase, voff) do { _Pragma("unroll") for (int _i = 0; _i < 2; ++_i) \
;         __builtin_amdgcn_global_load_lds((const unsigned*)((const char*)(gbase) + (voff)[_i]), (LAS unsigned*)(lds + (bufoff) + ldsw + _i * 8192), 16, 0, 0); } while (0)
; #define PG8_LDA(dst, b, h) do { _Pragma("unroll") for (int m = 0; m < NM; ++m) _Pragma("unroll") for (int k = 0; k < 2; ++k) dst[m][k] = *(const LAS bf16x8*)(lds + PG8_SA(b, h) + aoff + m * 2048 + k * 1024); } while (0)
; #define PG8_LDB(dst, b, h) do { _Pragma("unroll") for (int n = 0; n < 2; ++n) _Pragma("unroll") for (int k = 0; k < 2; ++k) dst[n][k] = *(const LAS bf16x8*)(lds + PG8_SB(b, h) + boff + n * 2048 + k * 1024); } while (0)
; #define PG8_MMA(ai, bj, At, Bt) do { __builtin_amdgcn_s_setprio(1); _Pragma("unroll") for (int m = 0; m < NM; ++m) _Pragma("unroll") for (int n = 0; n < 2; ++n) _Pragma("unroll") for (int k = 0; k < 2; ++k) \
;         acc[ai][bj][m][n] = __builtin_amdgcn_mfma_f32_16x16x32_bf16(Bt[n][k], At[m][k], acc[ai][bj][m][n], 0, 0, 0); __builtin_amdgcn_s_setprio(0); } while (0)
; #define PG8_WAIT_V(n) asm volatile("s_waitcnt vmcnt(" #n ")" ::: "memory")
; #define PG8_WAIT_L(n) asm volatile("s_waitcnt lgkmcnt(" #n ")" ::: "memory")
; #define PG8_BAR __builtin_amdgcn_s_barrier()
; #define PG8_SCHED __builtin_amdgcn_sched_barrier(0)
;     ...
;             PG8_WAIT_V(8); PG8_WAIT_L(0); PG8_BAR; PG8_MMA(1, 0, At, B0); PG8_MMA(1, 1, At, B1); PG8_BAR; PG8_SCHED;
;             PG8_LDB(B0, 1, 0); PG8_LDB(B1, 1, 1); PG8_SCHED; PG8_LDA(At, 1, 0); PG8_STAGE(PG8_SA(0, 1), a2 + hstepA, voffA);
.Ltl_qp_0d:
	s_waitcnt lgkmcnt(0)
	s_barrier
	s_setprio 1
	s_waitcnt lgkmcnt(0)
	v_mfma_f32_16x16x32_bf16 v[126:129], v[10:13], v[146:149], v[126:129]
	v_mfma_f32_16x16x32_bf16 v[122:125], v[18:21], v[146:149], v[122:125]
	v_mfma_f32_16x16x32_bf16 v[110:113], v[10:13], v[162:165], v[110:113]
	v_mfma_f32_16x16x32_bf16 v[106:109], v[18:21], v[162:165], v[106:109]
	v_mfma_f32_16x16x32_bf16 v[94:97], v[10:13], v[178:181], v[94:97]
	v_mfma_f32_16x16x32_bf16 v[90:93], v[18:21], v[178:181], v[90:93]
	v_mfma_f32_16x16x32_bf16 v[10:13], v[10:13], v[198:201], v[78:81]
	v_mfma_f32_16x16x32_bf16 v[126:129], v[14:17], v[150:153], v[126:129]
	v_mfma_f32_16x16x32_bf16 v[122:125], v[22:25], v[150:153], v[122:125]
	v_mfma_f32_16x16x32_bf16 v[110:113], v[14:17], v[166:169], v[110:113]
	v_mfma_f32_16x16x32_bf16 v[106:109], v[22:25], v[166:169], v[106:109]
	v_mfma_f32_16x16x32_bf16 v[94:97], v[14:17], v[182:185], v[94:97]
	v_mfma_f32_16x16x32_bf16 v[90:93], v[22:25], v[182:185], v[90:93]
	v_mfma_f32_16x16x32_bf16 v[10:13], v[14:17], v[208:211], v[10:13]
	v_mfma_f32_16x16x32_bf16 v[14:17], v[18:21], v[198:201], v[74:77]
	v_mfma_f32_16x16x32_bf16 v[14:17], v[22:25], v[208:211], v[14:17]
	s_setprio 0
	s_setprio 1
	v_mfma_f32_16x16x32_bf16 v[74:77], v[26:29], v[162:165], v[102:105]
	v_mfma_f32_16x16x32_bf16 v[102:105], v[30:33], v[166:169], v[74:77]
	v_mfma_f32_16x16x32_bf16 v[74:77], v[42:45], v[162:165], v[98:101]
	v_mfma_f32_16x16x32_bf16 v[98:101], v[46:49], v[166:169], v[74:77]
	v_mfma_f32_16x16x32_bf16 v[74:77], v[26:29], v[178:181], v[86:89]
	v_mfma_f32_16x16x32_bf16 v[18:21], v[26:29], v[146:149], v[118:121]
	v_mfma_f32_16x16x32_bf16 v[86:89], v[30:33], v[182:185], v[74:77]
	v_mfma_f32_16x16x32_bf16 v[74:77], v[42:45], v[178:181], v[82:85]
	v_mfma_f32_16x16x32_bf16 v[26:29], v[26:29], v[198:201], v[70:73]
	v_mfma_f32_16x16x32_bf16 v[18:21], v[30:33], v[150:153], v[18:21]
	v_mfma_f32_16x16x32_bf16 v[22:25], v[42:45], v[146:149], v[114:117]
	v_mfma_f32_16x16x32_bf16 v[82:85], v[46:49], v[182:185], v[74:77]
	v_mfma_f32_16x16x32_bf16 v[26:29], v[30:33], v[208:211], v[26:29]
	v_mfma_f32_16x16x32_bf16 v[30:33], v[42:45], v[198:201], v[66:69]
	s_setprio 2
	s_barrier
	v_mfma_f32_16x16x32_bf16 v[22:25], v[46:49], v[150:153], v[22:25]
	v_mfma_f32_16x16x32_bf16 v[30:33], v[46:49], v[208:211], v[30:33]
	s_setprio 0
	v_add_u32_e32 v0, s69, v216
	ds_read_b128 v[42:45], v0
	ds_read_b128 v[46:49], v0 offset:1024
	ds_read_b128 v[66:69], v0 offset:2048
	ds_read_b128 v[70:73], v0 offset:3072
	v_add_u32_e32 v0, s74, v216
	ds_read_b128 v[178:181], v0
	ds_read_b128 v[182:185], v0 offset:1024
	ds_read_b128 v[198:201], v0 offset:2048
	ds_read_b128 v[208:211], v0 offset:3072
	s_add_u32 s34, s34, 0x20000
	s_addc_u32 s35, s35, 0
	s_mov_b32 m0, s64
	ds_read_b128 v[74:77], v217 offset:32768
	ds_read_b128 v[78:81], v217 offset:33792
	ds_read_b128 v[114:117], v217 offset:34816
	ds_read_b128 v[118:121], v217 offset:35840
	ds_read_b128 v[146:149], v217 offset:36864
	ds_read_b128 v[212:215], v217 offset:37888
	ds_read_b128 v[218:221], v217 offset:38912
	ds_read_b128 v[226:229], v217 offset:39936
	s_cmp_lg_u32 s100, 0
	s_cbranch_scc1 .Ltl_qp_1s
	global_load_lds_dwordx4 v186, s[34:35]
	s_mov_b32 m0, s68
	s_nop 0
	global_load_lds_dwordx4 v190, s[34:35]
	s_waitcnt vmcnt(8)
	s_branch .Ltl_qp_1d

; #define PG8_STAGE(bufoff, gbase, voff) do { _Pragma("unroll") for (int _i = 0; _i < 2; ++_i) \
;         __builtin_amdgcn_global_load_lds((const unsigned*)((const char*)(gbase) + (voff)[_i]), (LAS unsigned*)(lds + (bufoff) + ldsw + _i * 8192), 16, 0, 0); } while (0)
; #define PG8_LDA(dst, b, h) do { _Pragma("unroll") for (int m = 0; m < NM; ++m) _Pragma("unroll") for (int k = 0; k < 2; ++k) dst[m][k] = *(const LAS bf16x8*)(lds + PG8_SA(b, h) + aoff + m * 2048 + k * 1024); } while (0)
; #define PG8_MMA(ai, bj, At, Bt) do { __builtin_amdgcn_s_setprio(1); _Pragma("unroll") for (int m = 0; m < NM; ++m) _Pragma("unroll") for (int n = 0; n < 2; ++n) _Pragma("unroll") for (int k = 0; k < 2; ++k) \
;         acc[ai][bj][m][n] = __builtin_amdgcn_mfma_f32_16x16x32_bf16(Bt[n][k], At[m][k], acc[ai][bj][m][n], 0, 0, 0); __builtin_amdgcn_s_setprio(0); } while (0)
; #define PG8_WAIT_V(n) asm volatile("s_waitcnt vmcnt(" #n ")" ::: "memory")
; #define PG8_WAIT_L(n) asm volatile("s_waitcnt lgkmcnt(" #n ")" ::: "memory")
; #define PG8_BAR __builtin_amdgcn_s_barrier()
; #define PG8_SCHED __builtin_amdgcn_sched_barrier(0)
;     ...
;             PG8_WAIT_V(8); PG8_WAIT_L(0); PG8_BAR; PG8_MMA(0, 0, At, B0); PG8_MMA(0, 1, At, B1); PG8_BAR; PG8_SCHED;
;             PG8_LDA(At, 1, 1); PG8_STAGE(PG8_SB(1, 0), b3, voffB); PG8_STAGE(PG8_SB(1, 1), b3 + hstepB, voffB); PG8_STAGE(PG8_SA(1, 0), a3, voffA);
.Ltl_qp_1d:
	s_waitcnt lgkmcnt(0)
	s_barrier
	s_setprio 1
	s_waitcnt lgkmcnt(0)
	v_mfma_f32_16x16x32_bf16 v[150:153], v[42:45], v[114:117], v[174:177]
	v_mfma_f32_16x16x32_bf16 v[174:177], v[46:49], v[118:121], v[150:153]
	v_mfma_f32_16x16x32_bf16 v[150:153], v[66:69], v[114:117], v[170:173]
	v_mfma_f32_16x16x32_bf16 v[170:173], v[70:73], v[118:121], v[150:153]
	v_mfma_f32_16x16x32_bf16 v[150:153], v[42:45], v[146:149], v[158:161]
	v_mfma_f32_16x16x32_bf16 v[38:41], v[42:45], v[74:77], v[38:41]
	v_mfma_f32_16x16x32_bf16 v[34:37], v[66:69], v[74:77], v[34:37]
	v_mfma_f32_16x16x32_bf16 v[158:161], v[46:49], v[212:215], v[150:153]
	v_mfma_f32_16x16x32_bf16 v[150:153], v[66:69], v[146:149], v[154:157]
	v_mfma_f32_16x16x32_bf16 v[142:145], v[42:45], v[218:221], v[142:145]
	v_mfma_f32_16x16x32_bf16 v[138:141], v[66:69], v[218:221], v[138:141]
	v_mfma_f32_16x16x32_bf16 v[38:41], v[46:49], v[78:81], v[38:41]
	v_mfma_f32_16x16x32_bf16 v[34:37], v[70:73], v[78:81], v[34:37]
	v_mfma_f32_16x16x32_bf16 v[154:157], v[70:73], v[212:215], v[150:153]
	v_mfma_f32_16x16x32_bf16 v[142:145], v[46:49], v[226:229], v[142:145]
	v_mfma_f32_16x16x32_bf16 v[138:141], v[70:73], v[226:229], v[138:141]
	s_setprio 0
	s_setprio 1
	v_mfma_f32_16x16x32_bf16 v[50:53], v[178:181], v[114:117], v[50:53]
	v_mfma_f32_16x16x32_bf16 v[166:169], v[182:185], v[118:121], v[50:53]
	v_mfma_f32_16x16x32_bf16 v[50:53], v[198:201], v[114:117], v[54:57]
	v_mfma_f32_16x16x32_bf16 v[162:165], v[208:211], v[118:121], v[50:53]
	v_mfma_f32_16x16x32_bf16 v[50:53], v[178:181], v[146:149], v[58:61]
	v_mfma_f32_16x16x32_bf16 v[150:153], v[182:185], v[212:215], v[50:53]
	v_mfma_f32_16x16x32_bf16 v[50:53], v[198:201], v[146:149], v[62:65]
	v_mfma_f32_16x16x32_bf16 v[146:149], v[208:211], v[212:215], v[50:53]
	v_mfma_f32_16x16x32_bf16 v[50:53], v[178:181], v[218:221], v[134:137]
	v_mfma_f32_16x16x32_bf16 v[6:9], v[178:181], v[74:77], v[6:9]
	v_mfma_f32_16x16x32_bf16 v[2:5], v[198:201], v[74:77], v[2:5]
	v_mfma_f32_16x16x32_bf16 v[134:137], v[182:185], v[226:229], v[50:53]
	v_mfma_f32_16x16x32_bf16 v[50:53], v[198:201], v[218:221], v[130:133]
	v_mfma_f32_16x16x32_bf16 v[6:9], v[182:185], v[78:81], v[6:9]
	s_setprio 2
	s_barrier
	v_mfma_f32_16x16x32_bf16 v[2:5], v[208:211], v[78:81], v[2:5]
	v_mfma_f32_16x16x32_bf16 v[130:133], v[208:211], v[226:229], v[50:53]
	s_setprio 0
	s_mov_b32 m0, s70
	v_lshl_add_u64 v[74:75], v[202:203], 0, s[66:67]
	s_add_u32 s12, s12, 0x20080
	s_addc_u32 s13, s13, 0
	ds_read_b128 v[50:53], v217 offset:49152
	ds_read_b128 v[54:57], v217 offset:50176
	ds_read_b128 v[58:61], v217 offset:51200
	ds_read_b128 v[62:65], v217 offset:52224
	ds_read_b128 v[212:215], v217 offset:53248
	ds_read_b128 v[218:221], v217 offset:54272
	ds_read_b128 v[226:229], v217 offset:55296
	ds_read_b128 v[230:233], v217 offset:56320
	s_cmp_lg_u32 s100, 0
	s_cbranch_scc1 .Ltl_qp_2s
	global_load_lds_dwordx4 v[74:75], off
	v_lshl_add_u64 v[74:75], v[204:205], 0, s[66:67]
	s_mov_b32 m0, s71
	s_nop 0
	global_load_lds_dwordx4 v[74:75], off
	s_mov_b32 m0, s75
	s_nop 0
	global_load_lds_dwordx4 v188, s[12:13]
	s_mov_b32 m0, s80
	s_nop 0
	global_load_lds_dwordx4 v192, s[12:13]
	v_lshl_add_u64 v[74:75], v[206:207], 0, s[66:67]
	s_mov_b32 m0, s72
	s_nop 0
	global_load_lds_dwordx4 v[74:75], off
	v_lshl_add_u64 v[74:75], v[222:223], 0, s[66:67]
	s_mov_b32 m0, s73
	s_nop 0
	global_load_lds_dwordx4 v[74:75], off
	s_waitcnt vmcnt(8)
	s_branch .Ltl_qp_2d

; #define PG8_STAGE(bufoff, gbase, voff) do { _Pragma("unroll") for (int _i = 0; _i < 2; ++_i) \
;         __builtin_amdgcn_global_load_lds((const unsigned*)((const char*)(gbase) + (voff)[_i]), (LAS unsigned*)(lds + (bufoff) + ldsw + _i * 8192), 16, 0, 0); } while (0)
; #define PG8_LDA(dst, b, h) do { _Pragma("unroll") for (int m = 0; m < NM; ++m) _Pragma("unroll") for (int k = 0; k < 2; ++k) dst[m][k] = *(const LAS bf16x8*)(lds + PG8_SA(b, h) + aoff + m * 2048 + k * 1024); } while (0)
; #define PG8_MMA(ai, bj, At, Bt) do { __builtin_amdgcn_s_setprio(1); _Pragma("unroll") for (int m = 0; m < NM; ++m) _Pragma("unroll") for (int n = 0; n < 2; ++n) _Pragma("unroll") for (int k = 0; k < 2; ++k) \
;         acc[ai][bj][m][n] = __builtin_amdgcn_mfma_f32_16x16x32_bf16(Bt[n][k], At[m][k], acc[ai][bj][m][n], 0, 0, 0); __builtin_amdgcn_s_setprio(0); } while (0)
; #define PG8_WAIT_V(n) asm volatile("s_waitcnt vmcnt(" #n ")" ::: "memory")
; #define PG8_WAIT_L(n) asm volatile("s_waitcnt lgkmcnt(" #n ")" ::: "memory")
; #define PG8_BAR __builtin_amdgcn_s_barrier()
; #define PG8_SCHED __builtin_amdgcn_sched_barrier(0)
;     ...
;             PG8_WAIT_V(8); PG8_WAIT_L(0); PG8_BAR; PG8_MMA(0, 0, At, B0); PG8_MMA(0, 1, At, B1); PG8_BAR; PG8_SCHED;
;             PG8_LDA(At, 1, 1); PG8_STAGE(PG8_SB(1, 0), b3, voffB); PG8_STAGE(PG8_SB(1, 1), b3 + hstepB, voffB); PG8_STAGE(PG8_SA(1, 0), a3, voffA);
;             PG8_WAIT_V(8); PG8_WAIT_L(0); PG8_BAR; PG8_MMA(1, 0, At, B0); PG8_MMA(1, 1, At, B1); PG8_BAR; PG8_SCHED;
.Ltl_qp_2d:
	s_waitcnt lgkmcnt(0)
	s_barrier
	s_setprio 1
	s_waitcnt lgkmcnt(0)
	v_mfma_f32_16x16x32_bf16 v[74:77], v[42:45], v[50:53], v[126:129]
	v_mfma_f32_16x16x32_bf16 v[126:129], v[46:49], v[54:57], v[74:77]
	v_mfma_f32_16x16x32_bf16 v[74:77], v[66:69], v[50:53], v[122:125]
	v_mfma_f32_16x16x32_bf16 v[122:125], v[70:73], v[54:57], v[74:77]
	v_mfma_f32_16x16x32_bf16 v[74:77], v[42:45], v[58:61], v[110:113]
	v_mfma_f32_16x16x32_bf16 v[110:113], v[46:49], v[62:65], v[74:77]
	v_mfma_f32_16x16x32_bf16 v[74:77], v[66:69], v[58:61], v[106:109]
	v_mfma_f32_16x16x32_bf16 v[106:109], v[70:73], v[62:65], v[74:77]
	v_mfma_f32_16x16x32_bf16 v[74:77], v[42:45], v[212:215], v[94:97]
	v_mfma_f32_16x16x32_bf16 v[10:13], v[42:45], v[226:229], v[10:13]
	v_mfma_f32_16x16x32_bf16 v[94:97], v[46:49], v[218:221], v[74:77]
	v_mfma_f32_16x16x32_bf16 v[74:77], v[66:69], v[212:215], v[90:93]
	v_mfma_f32_16x16x32_bf16 v[78:81], v[46:49], v[230:233], v[10:13]
	v_mfma_f32_16x16x32_bf16 v[10:13], v[66:69], v[226:229], v[14:17]
	v_mfma_f32_16x16x32_bf16 v[90:93], v[70:73], v[218:221], v[74:77]
	v_mfma_f32_16x16x32_bf16 v[74:77], v[70:73], v[230:233], v[10:13]
	s_setprio 0
	s_setprio 1
	v_mfma_f32_16x16x32_bf16 v[10:13], v[178:181], v[50:53], v[18:21]
	v_mfma_f32_16x16x32_bf16 v[118:121], v[182:185], v[54:57], v[10:13]
	v_mfma_f32_16x16x32_bf16 v[10:13], v[198:201], v[50:53], v[22:25]
	v_mfma_f32_16x16x32_bf16 v[114:117], v[208:211], v[54:57], v[10:13]
	v_mfma_f32_16x16x32_bf16 v[10:13], v[178:181], v[58:61], v[102:105]
	v_mfma_f32_16x16x32_bf16 v[102:105], v[182:185], v[62:65], v[10:13]
	v_mfma_f32_16x16x32_bf16 v[10:13], v[198:201], v[58:61], v[98:101]
	v_mfma_f32_16x16x32_bf16 v[98:101], v[208:211], v[62:65], v[10:13]
	v_mfma_f32_16x16x32_bf16 v[10:13], v[178:181], v[212:215], v[86:89]
	v_mfma_f32_16x16x32_bf16 v[86:89], v[182:185], v[218:221], v[10:13]
	v_mfma_f32_16x16x32_bf16 v[10:13], v[198:201], v[212:215], v[82:85]
	v_mfma_f32_16x16x32_bf16 v[82:85], v[208:211], v[218:221], v[10:13]
	v_mfma_f32_16x16x32_bf16 v[10:13], v[178:181], v[226:229], v[26:29]
	v_mfma_f32_16x16x32_bf16 v[70:73], v[182:185], v[230:233], v[10:13]
	s_setprio 2
	s_barrier
	v_mfma_f32_16x16x32_bf16 v[10:13], v[198:201], v[226:229], v[30:33]
	v_mfma_f32_16x16x32_bf16 v[66:69], v[208:211], v[230:233], v[10:13]
	s_setprio 0
	s_add_i32 s54, s54, 2
	s_add_u32 s10, s10, 0x100
	s_addc_u32 s11, s11, 0
	s_add_u32 s9, s9, 0x100
	s_addc_u32 s52, s52, 0
	s_cmp_gt_u32 s54, 5
	s_cbranch_scc0 .LBB0_1192
	s_and_b64 vcc, exec, s[16:17]
	s_cbranch_vccz .LBB0_1195
	s_barrier

; #define PG8_STAGE(bufoff, gbase, voff) do { _Pragma("unroll") for (int _i = 0; _i < 2; ++_i) \
;         __builtin_amdgcn_global_load_lds((const unsigned*)((const char*)(gbase) + (voff)[_i]), (LAS unsigned*)(lds + (bufoff) + ldsw + _i * 8192), 16, 0, 0); } while (0)
; #define PG8_LDA(dst, b, h) do { _Pragma("unroll") for (int m = 0; m < NM; ++m) _Pragma("unroll") for (int k = 0; k < 2; ++k) dst[m][k] = *(const LAS bf16x8*)(lds + PG8_SA(b, h) + aoff + m * 2048 + k * 1024); } while (0)
; #define PG8_LDB(dst, b, h) do { _Pragma("unroll") for (int n = 0; n < 2; ++n) _Pragma("unroll") for (int k = 0; k < 2; ++k) dst[n][k] = *(const LAS bf16x8*)(lds + PG8_SB(b, h) + boff + n * 2048 + k * 1024); } while (0)
; #define PG8_MMA(ai, bj, At, Bt) do { __builtin_amdgcn_s_setprio(1); _Pragma("unroll") for (int m = 0; m < NM; ++m) _Pragma("unroll") for (int n = 0; n < 2; ++n) _Pragma("unroll") for (int k = 0; k < 2; ++k) \
;         acc[ai][bj][m][n] = __builtin_amdgcn_mfma_f32_16x16x32_bf16(Bt[n][k], At[m][k], acc[ai][bj][m][n], 0, 0, 0); __builtin_amdgcn_s_setprio(0); } while (0)
; #define PG8_WAIT_V(n) asm volatile("s_waitcnt vmcnt(" #n ")" ::: "memory")
; #define PG8_WAIT_L(n) asm volatile("s_waitcnt lgkmcnt(" #n ")" ::: "memory")
; #define PG8_BAR __builtin_amdgcn_s_barrier()
; #define PG8_SCHED __builtin_amdgcn_sched_barrier(0)
;     ...
;             PG8_LDB(B0, 0, 0); PG8_LDB(B1, 0, 1); PG8_SCHED; PG8_LDA(At, 0, 0); PG8_STAGE(PG8_SA(1, 1), a1 + hstepA, voffA);
;             PG8_WAIT_V(8); PG8_WAIT_L(0); PG8_BAR; PG8_MMA(0, 0, At, B0); PG8_MMA(0, 1, At, B1); PG8_BAR; PG8_SCHED;
;             PG8_LDA(At, 0, 1); PG8_STAGE(PG8_SB(0, 0), b2, voffB); PG8_STAGE(PG8_SB(0, 1), b2 + hstepB, voffB); PG8_STAGE(PG8_SA(0, 0), a2, voffA);
.LBB0_1454:
	v_add_u32_e32 v140, s31, v142
	ds_read_b128 v[144:147], v140
	ds_read_b128 v[148:151], v140 offset:1024
	ds_read_b128 v[152:155], v140 offset:2048
	ds_read_b128 v[156:159], v140 offset:3072
	v_add_u32_e32 v140, s35, v142
	ds_read_b128 v[160:163], v140
	ds_read_b128 v[164:167], v140 offset:1024
	ds_read_b128 v[168:171], v140 offset:2048
	ds_read_b128 v[172:175], v140 offset:3072
	s_add_u32 s6, s20, 0x100
	s_addc_u32 s7, s21, 0
	s_cmp_eq_u32 s73, 4
	s_cselect_b32 s25, s17, s7
	s_cselect_b32 s24, s16, s6
	s_cselect_b32 s23, s2, s60
	s_cselect_b32 s22, s3, s15
	s_cselect_b32 s100, -1, 0
	s_andn2_b32 s100, s100, s101
	s_add_i32 m0, s45, 0xc000
	ds_read_b128 v[176:179], v143
	ds_read_b128 v[180:183], v143 offset:1024
	ds_read_b128 v[184:187], v143 offset:2048
	ds_read_b128 v[188:191], v143 offset:3072
	ds_read_b128 v[192:195], v143 offset:4096
	ds_read_b128 v[196:199], v143 offset:5120
	ds_read_b128 v[200:203], v143 offset:6144
	ds_read_b128 v[208:211], v143 offset:7168
	global_load_lds_dwordx4 v136, s[20:21]
	s_add_i32 m0, s45, 0xe000
	s_nop 0
	global_load_lds_dwordx4 v138, s[20:21]
	s_waitcnt vmcnt(8)
	s_waitcnt lgkmcnt(0)
	s_barrier
	s_setprio 1
	s_waitcnt lgkmcnt(0)
	v_mfma_f32_16x16x32_bf16 v[126:129], v[144:147], v[176:179], v[126:129]
	v_mfma_f32_16x16x32_bf16 v[122:125], v[152:155], v[176:179], v[122:125]
	v_mfma_f32_16x16x32_bf16 v[118:121], v[144:147], v[184:187], v[118:121]
	v_mfma_f32_16x16x32_bf16 v[114:117], v[152:155], v[184:187], v[114:117]
	v_mfma_f32_16x16x32_bf16 v[110:113], v[144:147], v[192:195], v[110:113]
	v_mfma_f32_16x16x32_bf16 v[106:109], v[152:155], v[192:195], v[106:109]
	v_mfma_f32_16x16x32_bf16 v[102:105], v[144:147], v[200:203], v[102:105]
	v_mfma_f32_16x16x32_bf16 v[98:101], v[152:155], v[200:203], v[98:101]
	v_mfma_f32_16x16x32_bf16 v[126:129], v[148:151], v[180:183], v[126:129]
	v_mfma_f32_16x16x32_bf16 v[122:125], v[156:159], v[180:183], v[122:125]
	v_mfma_f32_16x16x32_bf16 v[118:121], v[148:151], v[188:191], v[118:121]
	v_mfma_f32_16x16x32_bf16 v[114:117], v[156:159], v[188:191], v[114:117]
	v_mfma_f32_16x16x32_bf16 v[110:113], v[148:151], v[196:199], v[110:113]
	v_mfma_f32_16x16x32_bf16 v[106:109], v[156:159], v[196:199], v[106:109]
	v_mfma_f32_16x16x32_bf16 v[102:105], v[148:151], v[208:211], v[102:105]
	v_mfma_f32_16x16x32_bf16 v[98:101], v[156:159], v[208:211], v[98:101]
	s_setprio 0
	s_setprio 1
	v_mfma_f32_16x16x32_bf16 v[62:65], v[160:163], v[176:179], v[62:65]
	v_mfma_f32_16x16x32_bf16 v[58:61], v[168:171], v[176:179], v[58:61]
	v_mfma_f32_16x16x32_bf16 v[54:57], v[160:163], v[184:187], v[54:57]
	v_mfma_f32_16x16x32_bf16 v[50:53], v[168:171], v[184:187], v[50:53]
	v_mfma_f32_16x16x32_bf16 v[46:49], v[160:163], v[192:195], v[46:49]
	v_mfma_f32_16x16x32_bf16 v[42:45], v[168:171], v[192:195], v[42:45]
	v_mfma_f32_16x16x32_bf16 v[38:41], v[160:163], v[200:203], v[38:41]
	v_mfma_f32_16x16x32_bf16 v[34:37], v[168:171], v[200:203], v[34:37]
	v_mfma_f32_16x16x32_bf16 v[62:65], v[164:167], v[180:183], v[62:65]
	v_mfma_f32_16x16x32_bf16 v[58:61], v[172:175], v[180:183], v[58:61]
	v_mfma_f32_16x16x32_bf16 v[54:57], v[164:167], v[188:191], v[54:57]
	v_mfma_f32_16x16x32_bf16 v[50:53], v[172:175], v[188:191], v[50:53]
	v_mfma_f32_16x16x32_bf16 v[46:49], v[164:167], v[196:199], v[46:49]
	v_mfma_f32_16x16x32_bf16 v[42:45], v[172:175], v[196:199], v[42:45]
	s_setprio 2
	s_barrier
	v_mfma_f32_16x16x32_bf16 v[38:41], v[164:167], v[208:211], v[38:41]
	v_mfma_f32_16x16x32_bf16 v[34:37], v[172:175], v[208:211], v[34:37]
	s_setprio 0
	s_mov_b32 m0, s33
	v_lshl_add_u64 v[140:141], s[22:23], 0, v[0:1]
	s_add_u32 s20, s22, 0x20000
	s_addc_u32 s21, s23, 0
	ds_read_b128 v[176:179], v143 offset:16384
	ds_read_b128 v[180:183], v143 offset:17408
	ds_read_b128 v[184:187], v143 offset:18432
	ds_read_b128 v[188:191], v143 offset:19456
	ds_read_b128 v[192:195], v143 offset:20480
	ds_read_b128 v[196:199], v143 offset:21504
	ds_read_b128 v[200:203], v143 offset:22528
	ds_read_b128 v[208:211], v143 offset:23552
	s_cmp_lg_u32 s100, 0
	s_cbranch_scc1 .Ltl_kv_0s
	global_load_lds_dwordx4 v0, s[22:23]
	v_lshl_add_u64 v[204:205], s[22:23], 0, v[134:135]
	s_mov_b32 m0, s34
	s_nop 0
	global_load_lds_dwordx4 v134, s[22:23]
	s_mov_b32 m0, s43
	v_lshl_add_u64 v[212:213], s[24:25], 0, v[132:133]
	global_load_lds_dwordx4 v0, s[20:21]
	s_mov_b32 m0, s44
	s_nop 0
	global_load_lds_dwordx4 v134, s[20:21]
	v_lshl_add_u64 v[206:207], s[24:25], 0, v[130:131]
	s_mov_b32 m0, s45
	s_nop 0
	global_load_lds_dwordx4 v130, s[24:25]
	s_mov_b32 m0, s47
	s_nop 0
	global_load_lds_dwordx4 v132, s[24:25]
	s_waitcnt vmcnt(8)
	s_branch .Ltl_kv_0d

; #define PG8_STAGE(bufoff, gbase, voff) do { _Pragma("unroll") for (int _i = 0; _i < 2; ++_i) \
;         __builtin_amdgcn_global_load_lds((const unsigned*)((const char*)(gbase) + (voff)[_i]), (LAS unsigned*)(lds + (bufoff) + ldsw + _i * 8192), 16, 0, 0); } while (0)
; #define PG8_LDA(dst, b, h) do { _Pragma("unroll") for (int m = 0; m < NM; ++m) _Pragma("unroll") for (int k = 0; k < 2; ++k) dst[m][k] = *(const LAS bf16x8*)(lds + PG8_SA(b, h) + aoff + m * 2048 + k * 1024); } while (0)
; #define PG8_LDB(dst, b, h) do { _Pragma("unroll") for (int n = 0; n < 2; ++n) _Pragma("unroll") for (int k = 0; k < 2; ++k) dst[n][k] = *(const LAS bf16x8*)(lds + PG8_SB(b, h) + boff + n * 2048 + k * 1024); } while (0)
; #define PG8_MMA(ai, bj, At, Bt) do { __builtin_amdgcn_s_setprio(1); _Pragma("unroll") for (int m = 0; m < NM; ++m) _Pragma("unroll") for (int n = 0; n < 2; ++n) _Pragma("unroll") for (int k = 0; k < 2; ++k) \
;         acc[ai][bj][m][n] = __builtin_amdgcn_mfma_f32_16x16x32_bf16(Bt[n][k], At[m][k], acc[ai][bj][m][n], 0, 0, 0); __builtin_amdgcn_s_setprio(0); } while (0)
; #define PG8_WAIT_V(n) asm volatile("s_waitcnt vmcnt(" #n ")" ::: "memory")
; #define PG8_WAIT_L(n) asm volatile("s_waitcnt lgkmcnt(" #n ")" ::: "memory")
; #define PG8_BAR __builtin_amdgcn_s_barrier()
; #define PG8_SCHED __builtin_amdgcn_sched_barrier(0)
;     ...
;             PG8_WAIT_V(8); PG8_WAIT_L(0); PG8_BAR; PG8_MMA(1, 0, At, B0); PG8_MMA(1, 1, At, B1); PG8_BAR; PG8_SCHED;
;             PG8_LDB(B0, 1, 0); PG8_LDB(B1, 1, 1); PG8_SCHED; PG8_LDA(At, 1, 0); PG8_STAGE(PG8_SA(0, 1), a2 + hstepA, voffA);
.Ltl_kv_0d:
	s_waitcnt lgkmcnt(0)
	s_barrier
	s_setprio 1
	s_waitcnt lgkmcnt(0)
	v_mfma_f32_16x16x32_bf16 v[94:97], v[144:147], v[176:179], v[94:97]
	v_mfma_f32_16x16x32_bf16 v[90:93], v[152:155], v[176:179], v[90:93]
	v_mfma_f32_16x16x32_bf16 v[86:89], v[144:147], v[184:187], v[86:89]
	v_mfma_f32_16x16x32_bf16 v[82:85], v[152:155], v[184:187], v[82:85]
	v_mfma_f32_16x16x32_bf16 v[78:81], v[144:147], v[192:195], v[78:81]
	v_mfma_f32_16x16x32_bf16 v[74:77], v[152:155], v[192:195], v[74:77]
	v_mfma_f32_16x16x32_bf16 v[70:73], v[144:147], v[200:203], v[70:73]
	v_mfma_f32_16x16x32_bf16 v[66:69], v[152:155], v[200:203], v[66:69]
	v_mfma_f32_16x16x32_bf16 v[94:97], v[148:151], v[180:183], v[94:97]
	v_mfma_f32_16x16x32_bf16 v[90:93], v[156:159], v[180:183], v[90:93]
	v_mfma_f32_16x16x32_bf16 v[86:89], v[148:151], v[188:191], v[86:89]
	v_mfma_f32_16x16x32_bf16 v[82:85], v[156:159], v[188:191], v[82:85]
	v_mfma_f32_16x16x32_bf16 v[78:81], v[148:151], v[196:199], v[78:81]
	v_mfma_f32_16x16x32_bf16 v[74:77], v[156:159], v[196:199], v[74:77]
	v_mfma_f32_16x16x32_bf16 v[70:73], v[148:151], v[208:211], v[70:73]
	v_mfma_f32_16x16x32_bf16 v[66:69], v[156:159], v[208:211], v[66:69]
	s_setprio 0
	s_setprio 1
	v_mfma_f32_16x16x32_bf16 v[30:33], v[160:163], v[176:179], v[30:33]
	v_mfma_f32_16x16x32_bf16 v[26:29], v[168:171], v[176:179], v[26:29]
	v_mfma_f32_16x16x32_bf16 v[22:25], v[160:163], v[184:187], v[22:25]
	v_mfma_f32_16x16x32_bf16 v[18:21], v[168:171], v[184:187], v[18:21]
	v_mfma_f32_16x16x32_bf16 v[14:17], v[160:163], v[192:195], v[14:17]
	v_mfma_f32_16x16x32_bf16 v[10:13], v[168:171], v[192:195], v[10:13]
	v_mfma_f32_16x16x32_bf16 v[6:9], v[160:163], v[200:203], v[6:9]
	v_mfma_f32_16x16x32_bf16 v[2:5], v[168:171], v[200:203], v[2:5]
	v_mfma_f32_16x16x32_bf16 v[30:33], v[164:167], v[180:183], v[30:33]
	v_mfma_f32_16x16x32_bf16 v[26:29], v[172:175], v[180:183], v[26:29]
	v_mfma_f32_16x16x32_bf16 v[22:25], v[164:167], v[188:191], v[22:25]
	v_mfma_f32_16x16x32_bf16 v[18:21], v[172:175], v[188:191], v[18:21]
	v_mfma_f32_16x16x32_bf16 v[14:17], v[164:167], v[196:199], v[14:17]
	v_mfma_f32_16x16x32_bf16 v[10:13], v[172:175], v[196:199], v[10:13]
	s_setprio 2
	s_barrier
	v_mfma_f32_16x16x32_bf16 v[6:9], v[164:167], v[208:211], v[6:9]
	v_mfma_f32_16x16x32_bf16 v[2:5], v[172:175], v[208:211], v[2:5]
	s_setprio 0
	v_add_u32_e32 v156, s50, v142
	v_add_u32_e32 v172, s57, v142
	ds_read_b128 v[144:147], v156
	ds_read_b128 v[148:151], v156 offset:1024
	ds_read_b128 v[152:155], v156 offset:2048
	ds_read_b128 v[156:159], v156 offset:3072
	ds_read_b128 v[160:163], v172
	ds_read_b128 v[164:167], v172 offset:1024
	ds_read_b128 v[168:171], v172 offset:2048
	ds_read_b128 v[172:175], v172 offset:3072
	s_add_u32 s20, s24, 0x24000
	s_addc_u32 s21, s25, 0
	s_mov_b32 m0, s48
	ds_read_b128 v[176:179], v143 offset:32768
	ds_read_b128 v[180:183], v143 offset:33792
	ds_read_b128 v[184:187], v143 offset:34816
	ds_read_b128 v[188:191], v143 offset:35840
	ds_read_b128 v[192:195], v143 offset:36864
	ds_read_b128 v[196:199], v143 offset:37888
	ds_read_b128 v[200:203], v143 offset:38912
	ds_read_b128 v[208:211], v143 offset:39936
	s_cmp_lg_u32 s100, 0
	s_cbranch_scc1 .Ltl_kv_1s
	global_load_lds_dwordx4 v130, s[20:21]
	s_mov_b32 m0, s49
	s_nop 0
	global_load_lds_dwordx4 v132, s[20:21]
	s_waitcnt vmcnt(8)
	s_branch .Ltl_kv_1d

; #define PG8_STAGE(bufoff, gbase, voff) do { _Pragma("unroll") for (int _i = 0; _i < 2; ++_i) \
;         __builtin_amdgcn_global_load_lds((const unsigned*)((const char*)(gbase) + (voff)[_i]), (LAS unsigned*)(lds + (bufoff) + ldsw + _i * 8192), 16, 0, 0); } while (0)
; #define PG8_LDA(dst, b, h) do { _Pragma("unroll") for (int m = 0; m < NM; ++m) _Pragma("unroll") for (int k = 0; k < 2; ++k) dst[m][k] = *(const LAS bf16x8*)(lds + PG8_SA(b, h) + aoff + m * 2048 + k * 1024); } while (0)
; #define PG8_MMA(ai, bj, At, Bt) do { __builtin_amdgcn_s_setprio(1); _Pragma("unroll") for (int m = 0; m < NM; ++m) _Pragma("unroll") for (int n = 0; n < 2; ++n) _Pragma("unroll") for (int k = 0; k < 2; ++k) \
;         acc[ai][bj][m][n] = __builtin_amdgcn_mfma_f32_16x16x32_bf16(Bt[n][k], At[m][k], acc[ai][bj][m][n], 0, 0, 0); __builtin_amdgcn_s_setprio(0); } while (0)
; #define PG8_WAIT_V(n) asm volatile("s_waitcnt vmcnt(" #n ")" ::: "memory")
; #define PG8_WAIT_L(n) asm volatile("s_waitcnt lgkmcnt(" #n ")" ::: "memory")
; #define PG8_BAR __builtin_amdgcn_s_barrier()
; #define PG8_SCHED __builtin_amdgcn_sched_barrier(0)
;     ...
;             PG8_WAIT_V(8); PG8_WAIT_L(0); PG8_BAR; PG8_MMA(0, 0, At, B0); PG8_MMA(0, 1, At, B1); PG8_BAR; PG8_SCHED;
;             PG8_LDA(At, 1, 1); PG8_STAGE(PG8_SB(1, 0), b3, voffB); PG8_STAGE(PG8_SB(1, 1), b3 + hstepB, voffB); PG8_STAGE(PG8_SA(1, 0), a3, voffA);
.Ltl_kv_1d:
	s_waitcnt lgkmcnt(0)
	s_barrier
	s_setprio 1
	s_waitcnt lgkmcnt(0)
	v_mfma_f32_16x16x32_bf16 v[126:129], v[144:147], v[176:179], v[126:129]
	v_mfma_f32_16x16x32_bf16 v[122:125], v[152:155], v[176:179], v[122:125]
	v_mfma_f32_16x16x32_bf16 v[118:121], v[144:147], v[184:187], v[118:121]
	v_mfma_f32_16x16x32_bf16 v[114:117], v[152:155], v[184:187], v[114:117]
	v_mfma_f32_16x16x32_bf16 v[110:113], v[144:147], v[192:195], v[110:113]
	v_mfma_f32_16x16x32_bf16 v[106:109], v[152:155], v[192:195], v[106:109]
	v_mfma_f32_16x16x32_bf16 v[102:105], v[144:147], v[200:203], v[102:105]
	v_mfma_f32_16x16x32_bf16 v[98:101], v[152:155], v[200:203], v[98:101]
	v_mfma_f32_16x16x32_bf16 v[126:129], v[148:151], v[180:183], v[126:129]
	v_mfma_f32_16x16x32_bf16 v[122:125], v[156:159], v[180:183], v[122:125]
	v_mfma_f32_16x16x32_bf16 v[118:121], v[148:151], v[188:191], v[118:121]
	v_mfma_f32_16x16x32_bf16 v[114:117], v[156:159], v[188:191], v[114:117]
	v_mfma_f32_16x16x32_bf16 v[110:113], v[148:151], v[196:199], v[110:113]
	v_mfma_f32_16x16x32_bf16 v[106:109], v[156:159], v[196:199], v[106:109]
	v_mfma_f32_16x16x32_bf16 v[102:105], v[148:151], v[208:211], v[102:105]
	v_mfma_f32_16x16x32_bf16 v[98:101], v[156:159], v[208:211], v[98:101]
	s_setprio 0
	s_setprio 1
	v_mfma_f32_16x16x32_bf16 v[62:65], v[160:163], v[176:179], v[62:65]
	v_mfma_f32_16x16x32_bf16 v[58:61], v[168:171], v[176:179], v[58:61]
	v_mfma_f32_16x16x32_bf16 v[54:57], v[160:163], v[184:187], v[54:57]
	v_mfma_f32_16x16x32_bf16 v[50:53], v[168:171], v[184:187], v[50:53]
	v_mfma_f32_16x16x32_bf16 v[46:49], v[160:163], v[192:195], v[46:49]
	v_mfma_f32_16x16x32_bf16 v[42:45], v[168:171], v[192:195], v[42:45]
	v_mfma_f32_16x16x32_bf16 v[38:41], v[160:163], v[200:203], v[38:41]
	v_mfma_f32_16x16x32_bf16 v[34:37], v[168:171], v[200:203], v[34:37]
	v_mfma_f32_16x16x32_bf16 v[62:65], v[164:167], v[180:183], v[62:65]
	v_mfma_f32_16x16x32_bf16 v[58:61], v[172:175], v[180:183], v[58:61]
	v_mfma_f32_16x16x32_bf16 v[54:57], v[164:167], v[188:191], v[54:57]
	v_mfma_f32_16x16x32_bf16 v[50:53], v[172:175], v[188:191], v[50:53]
	v_mfma_f32_16x16x32_bf16 v[46:49], v[164:167], v[196:199], v[46:49]
	v_mfma_f32_16x16x32_bf16 v[42:45], v[172:175], v[196:199], v[42:45]
	s_setprio 2
	s_barrier
	v_mfma_f32_16x16x32_bf16 v[38:41], v[164:167], v[208:211], v[38:41]
	v_mfma_f32_16x16x32_bf16 v[34:37], v[172:175], v[208:211], v[34:37]
	s_setprio 0
	s_mov_b32 m0, s51
	v_lshl_add_u64 v[140:141], v[140:141], 0, s[66:67]
	s_add_u32 s20, s22, 0x20080
	s_addc_u32 s21, s23, 0
	ds_read_b128 v[176:179], v143 offset:49152
	ds_read_b128 v[180:183], v143 offset:50176
	ds_read_b128 v[184:187], v143 offset:51200
	ds_read_b128 v[188:191], v143 offset:52224
	ds_read_b128 v[192:195], v143 offset:53248
	ds_read_b128 v[196:199], v143 offset:54272
	ds_read_b128 v[200:203], v143 offset:55296
	ds_read_b128 v[208:211], v143 offset:56320
	s_cmp_lg_u32 s100, 0
	s_cbranch_scc1 .Ltl_kv_2s
	global_load_lds_dwordx4 v[140:141], off
	v_lshl_add_u64 v[140:141], v[204:205], 0, s[66:67]
	s_mov_b32 m0, s52
	s_nop 0
	global_load_lds_dwordx4 v[140:141], off
	s_mov_b32 m0, s58
	s_nop 0
	global_load_lds_dwordx4 v0, s[20:21]
	s_mov_b32 m0, s59
	s_nop 0
	global_load_lds_dwordx4 v134, s[20:21]
	v_lshl_add_u64 v[140:141], v[206:207], 0, s[66:67]
	s_mov_b32 m0, s54
	s_nop 0
	global_load_lds_dwordx4 v[140:141], off
	v_lshl_add_u64 v[140:141], v[212:213], 0, s[66:67]
	s_mov_b32 m0, s56
	s_nop 0
	global_load_lds_dwordx4 v[140:141], off
	s_waitcnt vmcnt(8)
	s_branch .Ltl_kv_2d

; #define PG8_STAGE(bufoff, gbase, voff) do { _Pragma("unroll") for (int _i = 0; _i < 2; ++_i) \
;         __builtin_amdgcn_global_load_lds((const unsigned*)((const char*)(gbase) + (voff)[_i]), (LAS unsigned*)(lds + (bufoff) + ldsw + _i * 8192), 16, 0, 0); } while (0)
; #define PG8_LDA(dst, b, h) do { _Pragma("unroll") for (int m = 0; m < NM; ++m) _Pragma("unroll") for (int k = 0; k < 2; ++k) dst[m][k] = *(const LAS bf16x8*)(lds + PG8_SA(b, h) + aoff + m * 2048 + k * 1024); } while (0)
; #define PG8_MMA(ai, bj, At, Bt) do { __builtin_amdgcn_s_setprio(1); _Pragma("unroll") for (int m = 0; m < NM; ++m) _Pragma("unroll") for (int n = 0; n < 2; ++n) _Pragma("unroll") for (int k = 0; k < 2; ++k) \
;         acc[ai][bj][m][n] = __builtin_amdgcn_mfma_f32_16x16x32_bf16(Bt[n][k], At[m][k], acc[ai][bj][m][n], 0, 0, 0); __builtin_amdgcn_s_setprio(0); } while (0)
; #define PG8_WAIT_V(n) asm volatile("s_waitcnt vmcnt(" #n ")" ::: "memory")
; #define PG8_WAIT_L(n) asm volatile("s_waitcnt lgkmcnt(" #n ")" ::: "memory")
; #define PG8_BAR __builtin_amdgcn_s_barrier()
; #define PG8_SCHED __builtin_amdgcn_sched_barrier(0)
;     ...
;             PG8_WAIT_V(8); PG8_WAIT_L(0); PG8_BAR; PG8_MMA(0, 0, At, B0); PG8_MMA(0, 1, At, B1); PG8_BAR; PG8_SCHED;
;             PG8_LDA(At, 1, 1); PG8_STAGE(PG8_SB(1, 0), b3, voffB); PG8_STAGE(PG8_SB(1, 1), b3 + hstepB, voffB); PG8_STAGE(PG8_SA(1, 0), a3, voffA);
;             PG8_WAIT_V(8); PG8_WAIT_L(0); PG8_BAR; PG8_MMA(1, 0, At, B0); PG8_MMA(1, 1, At, B1); PG8_BAR; PG8_SCHED;
.Ltl_kv_2d:
	s_waitcnt lgkmcnt(0)
	s_barrier
	s_setprio 1
	s_waitcnt lgkmcnt(0)
	v_mfma_f32_16x16x32_bf16 v[94:97], v[144:147], v[176:179], v[94:97]
	v_mfma_f32_16x16x32_bf16 v[90:93], v[152:155], v[176:179], v[90:93]
	v_mfma_f32_16x16x32_bf16 v[86:89], v[144:147], v[184:187], v[86:89]
	v_mfma_f32_16x16x32_bf16 v[82:85], v[152:155], v[184:187], v[82:85]
	v_mfma_f32_16x16x32_bf16 v[78:81], v[144:147], v[192:195], v[78:81]
	v_mfma_f32_16x16x32_bf16 v[74:77], v[152:155], v[192:195], v[74:77]
	v_mfma_f32_16x16x32_bf16 v[70:73], v[144:147], v[200:203], v[70:73]
	v_mfma_f32_16x16x32_bf16 v[66:69], v[152:155], v[200:203], v[66:69]
	v_mfma_f32_16x16x32_bf16 v[94:97], v[148:151], v[180:183], v[94:97]
	v_mfma_f32_16x16x32_bf16 v[90:93], v[156:159], v[180:183], v[90:93]
	v_mfma_f32_16x16x32_bf16 v[86:89], v[148:151], v[188:191], v[86:89]
	v_mfma_f32_16x16x32_bf16 v[82:85], v[156:159], v[188:191], v[82:85]
	v_mfma_f32_16x16x32_bf16 v[78:81], v[148:151], v[196:199], v[78:81]
	v_mfma_f32_16x16x32_bf16 v[74:77], v[156:159], v[196:199], v[74:77]
	v_mfma_f32_16x16x32_bf16 v[70:73], v[148:151], v[208:211], v[70:73]
	v_mfma_f32_16x16x32_bf16 v[66:69], v[156:159], v[208:211], v[66:69]
	s_setprio 0
	s_setprio 1
	v_mfma_f32_16x16x32_bf16 v[30:33], v[160:163], v[176:179], v[30:33]
	v_mfma_f32_16x16x32_bf16 v[26:29], v[168:171], v[176:179], v[26:29]
	v_mfma_f32_16x16x32_bf16 v[22:25], v[160:163], v[184:187], v[22:25]
	v_mfma_f32_16x16x32_bf16 v[18:21], v[168:171], v[184:187], v[18:21]
	v_mfma_f32_16x16x32_bf16 v[14:17], v[160:163], v[192:195], v[14:17]
	v_mfma_f32_16x16x32_bf16 v[10:13], v[168:171], v[192:195], v[10:13]
	v_mfma_f32_16x16x32_bf16 v[6:9], v[160:163], v[200:203], v[6:9]
	v_mfma_f32_16x16x32_bf16 v[2:5], v[168:171], v[200:203], v[2:5]
	v_mfma_f32_16x16x32_bf16 v[30:33], v[164:167], v[180:183], v[30:33]
	v_mfma_f32_16x16x32_bf16 v[26:29], v[172:175], v[180:183], v[26:29]
	v_mfma_f32_16x16x32_bf16 v[22:25], v[164:167], v[188:191], v[22:25]
	v_mfma_f32_16x16x32_bf16 v[18:21], v[172:175], v[188:191], v[18:21]
	v_mfma_f32_16x16x32_bf16 v[14:17], v[164:167], v[196:199], v[14:17]
	v_mfma_f32_16x16x32_bf16 v[10:13], v[172:175], v[196:199], v[10:13]
	s_setprio 2
	s_barrier
	v_mfma_f32_16x16x32_bf16 v[6:9], v[164:167], v[208:211], v[6:9]
	v_mfma_f32_16x16x32_bf16 v[2:5], v[172:175], v[208:211], v[2:5]
	s_setprio 0
	s_add_i32 s73, s73, 2
	s_add_u32 s15, s15, 0x100
	s_addc_u32 s60, s60, 0
	s_cmp_gt_u32 s73, 5
	s_mov_b64 s[20:21], s[6:7]
	s_cbranch_scc0 .LBB0_1454
	s_and_b64 vcc, exec, s[12:13]
	s_cbranch_vccz .LBB0_1457
	s_barrier

; #define PG8_STAGE(bufoff, gbase, voff) do { _Pragma("unroll") for (int _i = 0; _i < 2; ++_i) \
;         __builtin_amdgcn_global_load_lds((const unsigned*)((const char*)(gbase) + (voff)[_i]), (LAS unsigned*)(lds + (bufoff) + ldsw + _i * 8192), 16, 0, 0); } while (0)
; #define PG8_LDA(dst, b, h) do { _Pragma("unroll") for (int m = 0; m < NM; ++m) _Pragma("unroll") for (int k = 0; k < 2; ++k) dst[m][k] = *(const LAS bf16x8*)(lds + PG8_SA(b, h) + aoff + m * 2048 + k * 1024); } while (0)
; #define PG8_MMA(ai, bj, At, Bt) do { __builtin_amdgcn_s_setprio(1); _Pragma("unroll") for (int m = 0; m < NM; ++m) _Pragma("unroll") for (int n = 0; n < 2; ++n) _Pragma("unroll") for (int k = 0; k < 2; ++k) \
;         acc[ai][bj][m][n] = __builtin_amdgcn_mfma_f32_16x16x32_bf16(Bt[n][k], At[m][k], acc[ai][bj][m][n], 0, 0, 0); __builtin_amdgcn_s_setprio(0); } while (0)
; #define PG8_WAIT_V(n) asm volatile("s_waitcnt vmcnt(" #n ")" ::: "memory")
; #define PG8_WAIT_L(n) asm volatile("s_waitcnt lgkmcnt(" #n ")" ::: "memory")
; #define PG8_BAR __builtin_amdgcn_s_barrier()
; #define PG8_SCHED __builtin_amdgcn_sched_barrier(0)
;     ...
;             PG8_WAIT_V(8); PG8_WAIT_L(0); PG8_BAR; PG8_MMA(0, 0, At, B0); PG8_MMA(0, 1, At, B1); PG8_BAR; PG8_SCHED;
;             PG8_LDA(At, 0, 1); PG8_STAGE(PG8_SB(0, 0), b2, voffB); PG8_STAGE(PG8_SB(0, 1), b2 + hstepB, voffB); PG8_STAGE(PG8_SA(0, 0), a2, voffA);
.Lnm3o_done0:
	s_waitcnt lgkmcnt(0)
	s_barrier
	s_setprio 1
	s_waitcnt lgkmcnt(0)
	v_mfma_f32_16x16x32_bf16 v[110:113], v[90:93], v[130:133], v[110:113]
	v_mfma_f32_16x16x32_bf16 v[106:109], v[98:101], v[130:133], v[106:109]
	v_mfma_f32_16x16x32_bf16 v[78:81], v[90:93], v[138:141], v[78:81]
	v_mfma_f32_16x16x32_bf16 v[74:77], v[98:101], v[138:141], v[74:77]
	v_mfma_f32_16x16x32_bf16 v[62:65], v[90:93], v[156:159], v[62:65]
	v_mfma_f32_16x16x32_bf16 v[58:61], v[98:101], v[156:159], v[58:61]
	v_mfma_f32_16x16x32_bf16 v[110:113], v[94:97], v[134:137], v[110:113]
	v_mfma_f32_16x16x32_bf16 v[106:109], v[102:105], v[134:137], v[106:109]
	v_mfma_f32_16x16x32_bf16 v[78:81], v[94:97], v[152:155], v[78:81]
	v_mfma_f32_16x16x32_bf16 v[74:77], v[102:105], v[152:155], v[74:77]
	v_mfma_f32_16x16x32_bf16 v[62:65], v[94:97], v[160:163], v[62:65]
	v_mfma_f32_16x16x32_bf16 v[58:61], v[102:105], v[160:163], v[58:61]
	s_setprio 0
	s_setprio 1
	v_mfma_f32_16x16x32_bf16 v[86:89], v[114:117], v[130:133], v[86:89]
	v_mfma_f32_16x16x32_bf16 v[82:85], v[122:125], v[130:133], v[82:85]
	v_mfma_f32_16x16x32_bf16 v[70:73], v[114:117], v[138:141], v[70:73]
	v_mfma_f32_16x16x32_bf16 v[66:69], v[122:125], v[138:141], v[66:69]
	v_mfma_f32_16x16x32_bf16 v[54:57], v[114:117], v[156:159], v[54:57]
	v_mfma_f32_16x16x32_bf16 v[50:53], v[122:125], v[156:159], v[50:53]
	v_mfma_f32_16x16x32_bf16 v[86:89], v[118:121], v[134:137], v[86:89]
	v_mfma_f32_16x16x32_bf16 v[82:85], v[126:129], v[134:137], v[82:85]
	v_mfma_f32_16x16x32_bf16 v[70:73], v[118:121], v[152:155], v[70:73]
	v_mfma_f32_16x16x32_bf16 v[66:69], v[126:129], v[152:155], v[66:69]
	s_setprio 2
	s_barrier
	v_mfma_f32_16x16x32_bf16 v[54:57], v[118:121], v[160:163], v[54:57]
	v_mfma_f32_16x16x32_bf16 v[50:53], v[126:129], v[160:163], v[50:53]
	s_setprio 0
	s_mov_b32 m0, s29
	v_lshl_add_u64 v[164:165], s[22:23], 0, v[0:1]
	s_add_u32 s62, s22, 0x80000
	s_addc_u32 s63, s23, 0
	ds_read_b128 v[130:133], v167 offset:16384
	ds_read_b128 v[134:137], v167 offset:17408
	ds_read_b128 v[138:141], v167 offset:18432
	ds_read_b128 v[152:155], v167 offset:19456
	ds_read_b128 v[156:159], v167 offset:20480
	ds_read_b128 v[160:163], v167 offset:21504
	s_cmp_lg_u32 s100, 0
	s_cbranch_scc1 .Ltl_ou_0s
	global_load_lds_dwordx4 v0, s[22:23]
	v_lshl_add_u64 v[168:169], s[22:23], 0, v[146:147]
	s_mov_b32 m0, s30
	s_nop 0
	global_load_lds_dwordx4 v146, s[22:23]
	s_mov_b32 m0, s33
	v_lshl_add_u64 v[172:173], s[24:25], 0, v[144:145]
	global_load_lds_dwordx4 v0, s[62:63]
	s_mov_b32 m0, s34
	s_nop 0
	global_load_lds_dwordx4 v146, s[62:63]
	v_lshl_add_u64 v[170:171], s[24:25], 0, v[142:143]
	s_mov_b32 m0, s35
	s_nop 0
	global_load_lds_dwordx4 v142, s[24:25]
	s_mov_b32 m0, s36
	s_nop 0
	s_and_b64 vcc, exec, s[10:11]
	s_cbranch_vccz .Lnm3o_skip1
	global_load_lds_dwordx4 v144, s[24:25]
	s_waitcnt vmcnt(8)
	s_branch .Lnm3o_done1

; #define PG8_STAGE(bufoff, gbase, voff) do { _Pragma("unroll") for (int _i = 0; _i < 2; ++_i) \
;         __builtin_amdgcn_global_load_lds((const unsigned*)((const char*)(gbase) + (voff)[_i]), (LAS unsigned*)(lds + (bufoff) + ldsw + _i * 8192), 16, 0, 0); } while (0)
; #define PG8_LDA(dst, b, h) do { _Pragma("unroll") for (int m = 0; m < NM; ++m) _Pragma("unroll") for (int k = 0; k < 2; ++k) dst[m][k] = *(const LAS bf16x8*)(lds + PG8_SA(b, h) + aoff + m * 2048 + k * 1024); } while (0)
; #define PG8_LDB(dst, b, h) do { _Pragma("unroll") for (int n = 0; n < 2; ++n) _Pragma("unroll") for (int k = 0; k < 2; ++k) dst[n][k] = *(const LAS bf16x8*)(lds + PG8_SB(b, h) + boff + n * 2048 + k * 1024); } while (0)
; #define PG8_MMA(ai, bj, At, Bt) do { __builtin_amdgcn_s_setprio(1); _Pragma("unroll") for (int m = 0; m < NM; ++m) _Pragma("unroll") for (int n = 0; n < 2; ++n) _Pragma("unroll") for (int k = 0; k < 2; ++k) \
;         acc[ai][bj][m][n] = __builtin_amdgcn_mfma_f32_16x16x32_bf16(Bt[n][k], At[m][k], acc[ai][bj][m][n], 0, 0, 0); __builtin_amdgcn_s_setprio(0); } while (0)
; #define PG8_WAIT_V(n) asm volatile("s_waitcnt vmcnt(" #n ")" ::: "memory")
; #define PG8_WAIT_L(n) asm volatile("s_waitcnt lgkmcnt(" #n ")" ::: "memory")
; #define PG8_BAR __builtin_amdgcn_s_barrier()
; #define PG8_SCHED __builtin_amdgcn_sched_barrier(0)
;     ...
;             PG8_WAIT_V(8); PG8_WAIT_L(0); PG8_BAR; PG8_MMA(1, 0, At, B0); PG8_MMA(1, 1, At, B1); PG8_BAR; PG8_SCHED;
;             PG8_LDB(B0, 1, 0); PG8_LDB(B1, 1, 1); PG8_SCHED; PG8_LDA(At, 1, 0); PG8_STAGE(PG8_SA(0, 1), a2 + hstepA, voffA);
.Ltl_ou_0d:
	s_waitcnt lgkmcnt(0)
	s_barrier
	s_setprio 1
	s_waitcnt lgkmcnt(0)
	v_mfma_f32_16x16x32_bf16 v[46:49], v[90:93], v[130:133], v[46:49]
	v_mfma_f32_16x16x32_bf16 v[42:45], v[98:101], v[130:133], v[42:45]
	v_mfma_f32_16x16x32_bf16 v[30:33], v[90:93], v[138:141], v[30:33]
	v_mfma_f32_16x16x32_bf16 v[26:29], v[98:101], v[138:141], v[26:29]
	v_mfma_f32_16x16x32_bf16 v[14:17], v[90:93], v[156:159], v[14:17]
	v_mfma_f32_16x16x32_bf16 v[10:13], v[98:101], v[156:159], v[10:13]
	v_mfma_f32_16x16x32_bf16 v[46:49], v[94:97], v[134:137], v[46:49]
	v_mfma_f32_16x16x32_bf16 v[42:45], v[102:105], v[134:137], v[42:45]
	v_mfma_f32_16x16x32_bf16 v[30:33], v[94:97], v[152:155], v[30:33]
	v_mfma_f32_16x16x32_bf16 v[26:29], v[102:105], v[152:155], v[26:29]
	v_mfma_f32_16x16x32_bf16 v[14:17], v[94:97], v[160:163], v[14:17]
	v_mfma_f32_16x16x32_bf16 v[10:13], v[102:105], v[160:163], v[10:13]
	s_setprio 0
	s_setprio 1
	v_mfma_f32_16x16x32_bf16 v[38:41], v[114:117], v[130:133], v[38:41]
	v_mfma_f32_16x16x32_bf16 v[34:37], v[122:125], v[130:133], v[34:37]
	v_mfma_f32_16x16x32_bf16 v[22:25], v[114:117], v[138:141], v[22:25]
	v_mfma_f32_16x16x32_bf16 v[18:21], v[122:125], v[138:141], v[18:21]
	v_mfma_f32_16x16x32_bf16 v[6:9], v[114:117], v[156:159], v[6:9]
	v_mfma_f32_16x16x32_bf16 v[2:5], v[122:125], v[156:159], v[2:5]
	v_mfma_f32_16x16x32_bf16 v[38:41], v[118:121], v[134:137], v[38:41]
	v_mfma_f32_16x16x32_bf16 v[34:37], v[126:129], v[134:137], v[34:37]
	v_mfma_f32_16x16x32_bf16 v[22:25], v[118:121], v[152:155], v[22:25]
	v_mfma_f32_16x16x32_bf16 v[18:21], v[126:129], v[152:155], v[18:21]
	s_setprio 2
	s_barrier
	v_mfma_f32_16x16x32_bf16 v[6:9], v[118:121], v[160:163], v[6:9]
	v_mfma_f32_16x16x32_bf16 v[2:5], v[126:129], v[160:163], v[2:5]
	s_setprio 0
	v_add_u32_e32 v102, s40, v166
	v_add_u32_e32 v126, s45, v166
	ds_read_b128 v[90:93], v102
	ds_read_b128 v[94:97], v102 offset:1024
	ds_read_b128 v[98:101], v102 offset:2048
	ds_read_b128 v[102:105], v102 offset:3072
	ds_read_b128 v[114:117], v126
	ds_read_b128 v[118:121], v126 offset:1024
	ds_read_b128 v[122:125], v126 offset:2048
	ds_read_b128 v[126:129], v126 offset:3072
	s_add_u32 s24, s24, 0x60000
	s_addc_u32 s25, s25, 0
	s_mov_b32 m0, s37
	ds_read_b128 v[130:133], v167 offset:32768
	ds_read_b128 v[134:137], v167 offset:33792
	ds_read_b128 v[138:141], v167 offset:34816
	ds_read_b128 v[152:155], v167 offset:35840
	ds_read_b128 v[156:159], v167 offset:36864
	ds_read_b128 v[160:163], v167 offset:37888
	s_cmp_lg_u32 s100, 0
	s_cbranch_scc1 .Ltl_ou_1s
	global_load_lds_dwordx4 v142, s[24:25]
	s_mov_b32 m0, s38
	s_nop 0
	s_and_b64 vcc, exec, s[10:11]
	s_cbranch_vccz .Lnm3o_skip2
	global_load_lds_dwordx4 v144, s[24:25]
	s_waitcnt vmcnt(8)
	s_branch .Lnm3o_done2

; #define PG8_STAGE(bufoff, gbase, voff) do { _Pragma("unroll") for (int _i = 0; _i < 2; ++_i) \
;         __builtin_amdgcn_global_load_lds((const unsigned*)((const char*)(gbase) + (voff)[_i]), (LAS unsigned*)(lds + (bufoff) + ldsw + _i * 8192), 16, 0, 0); } while (0)
; #define PG8_LDA(dst, b, h) do { _Pragma("unroll") for (int m = 0; m < NM; ++m) _Pragma("unroll") for (int k = 0; k < 2; ++k) dst[m][k] = *(const LAS bf16x8*)(lds + PG8_SA(b, h) + aoff + m * 2048 + k * 1024); } while (0)
; #define PG8_MMA(ai, bj, At, Bt) do { __builtin_amdgcn_s_setprio(1); _Pragma("unroll") for (int m = 0; m < NM; ++m) _Pragma("unroll") for (int n = 0; n < 2; ++n) _Pragma("unroll") for (int k = 0; k < 2; ++k) \
;         acc[ai][bj][m][n] = __builtin_amdgcn_mfma_f32_16x16x32_bf16(Bt[n][k], At[m][k], acc[ai][bj][m][n], 0, 0, 0); __builtin_amdgcn_s_setprio(0); } while (0)
; #define PG8_WAIT_V(n) asm volatile("s_waitcnt vmcnt(" #n ")" ::: "memory")
; #define PG8_WAIT_L(n) asm volatile("s_waitcnt lgkmcnt(" #n ")" ::: "memory")
; #define PG8_BAR __builtin_amdgcn_s_barrier()
; #define PG8_SCHED __builtin_amdgcn_sched_barrier(0)
;     ...
;             PG8_WAIT_V(8); PG8_WAIT_L(0); PG8_BAR; PG8_MMA(0, 0, At, B0); PG8_MMA(0, 1, At, B1); PG8_BAR; PG8_SCHED;
;             PG8_LDA(At, 1, 1); PG8_STAGE(PG8_SB(1, 0), b3, voffB); PG8_STAGE(PG8_SB(1, 1), b3 + hstepB, voffB); PG8_STAGE(PG8_SA(1, 0), a3, voffA);
.Ltl_ou_1d:
	s_waitcnt lgkmcnt(0)
	s_barrier
	s_setprio 1
	s_waitcnt lgkmcnt(0)
	v_mfma_f32_16x16x32_bf16 v[110:113], v[90:93], v[130:133], v[110:113]
	v_mfma_f32_16x16x32_bf16 v[106:109], v[98:101], v[130:133], v[106:109]
	v_mfma_f32_16x16x32_bf16 v[78:81], v[90:93], v[138:141], v[78:81]
	v_mfma_f32_16x16x32_bf16 v[74:77], v[98:101], v[138:141], v[74:77]
	v_mfma_f32_16x16x32_bf16 v[62:65], v[90:93], v[156:159], v[62:65]
	v_mfma_f32_16x16x32_bf16 v[58:61], v[98:101], v[156:159], v[58:61]
	v_mfma_f32_16x16x32_bf16 v[110:113], v[94:97], v[134:137], v[110:113]
	v_mfma_f32_16x16x32_bf16 v[106:109], v[102:105], v[134:137], v[106:109]
	v_mfma_f32_16x16x32_bf16 v[78:81], v[94:97], v[152:155], v[78:81]
	v_mfma_f32_16x16x32_bf16 v[74:77], v[102:105], v[152:155], v[74:77]
	v_mfma_f32_16x16x32_bf16 v[62:65], v[94:97], v[160:163], v[62:65]
	v_mfma_f32_16x16x32_bf16 v[58:61], v[102:105], v[160:163], v[58:61]
	s_setprio 0
	s_setprio 1
	v_mfma_f32_16x16x32_bf16 v[86:89], v[114:117], v[130:133], v[86:89]
	v_mfma_f32_16x16x32_bf16 v[82:85], v[122:125], v[130:133], v[82:85]
	v_mfma_f32_16x16x32_bf16 v[70:73], v[114:117], v[138:141], v[70:73]
	v_mfma_f32_16x16x32_bf16 v[66:69], v[122:125], v[138:141], v[66:69]
	v_mfma_f32_16x16x32_bf16 v[54:57], v[114:117], v[156:159], v[54:57]
	v_mfma_f32_16x16x32_bf16 v[50:53], v[122:125], v[156:159], v[50:53]
	v_mfma_f32_16x16x32_bf16 v[86:89], v[118:121], v[134:137], v[86:89]
	v_mfma_f32_16x16x32_bf16 v[82:85], v[126:129], v[134:137], v[82:85]
	v_mfma_f32_16x16x32_bf16 v[70:73], v[118:121], v[152:155], v[70:73]
	v_mfma_f32_16x16x32_bf16 v[66:69], v[126:129], v[152:155], v[66:69]
	s_setprio 2
	s_barrier
	v_mfma_f32_16x16x32_bf16 v[54:57], v[118:121], v[160:163], v[54:57]
	v_mfma_f32_16x16x32_bf16 v[50:53], v[126:129], v[160:163], v[50:53]
	s_setprio 0
	s_mov_b32 m0, s41
	v_lshl_add_u64 v[164:165], v[164:165], 0, s[66:67]
	s_add_u32 s22, s22, 0x80080
	s_addc_u32 s23, s23, 0
	ds_read_b128 v[130:133], v167 offset:49152
	ds_read_b128 v[134:137], v167 offset:50176
	ds_read_b128 v[138:141], v167 offset:51200
	ds_read_b128 v[152:155], v167 offset:52224
	ds_read_b128 v[156:159], v167 offset:53248
	ds_read_b128 v[160:163], v167 offset:54272
	s_cmp_lg_u32 s100, 0
	s_cbranch_scc1 .Ltl_ou_2s
	global_load_lds_dwordx4 v[164:165], off
	v_lshl_add_u64 v[164:165], v[168:169], 0, s[66:67]
	s_mov_b32 m0, s42
	s_nop 0
	global_load_lds_dwordx4 v[164:165], off
	s_mov_b32 m0, s46
	s_nop 0
	global_load_lds_dwordx4 v0, s[22:23]
	s_mov_b32 m0, s47
	s_nop 0
	global_load_lds_dwordx4 v146, s[22:23]
	v_lshl_add_u64 v[164:165], v[170:171], 0, s[66:67]
	s_mov_b32 m0, s43
	s_nop 0
	global_load_lds_dwordx4 v[164:165], off
	v_lshl_add_u64 v[164:165], v[172:173], 0, s[66:67]
	s_mov_b32 m0, s44
	s_nop 0
	s_and_b64 vcc, exec, s[10:11]
	s_cbranch_vccz .Lnm3o_skip3
	global_load_lds_dwordx4 v[164:165], off
	s_waitcnt vmcnt(8)
	s_branch .Lnm3o_done3

; #define PG8_STAGE(bufoff, gbase, voff) do { _Pragma("unroll") for (int _i = 0; _i < 2; ++_i) \
;         __builtin_amdgcn_global_load_lds((const unsigned*)((const char*)(gbase) + (voff)[_i]), (LAS unsigned*)(lds + (bufoff) + ldsw + _i * 8192), 16, 0, 0); } while (0)
; #define PG8_LDA(dst, b, h) do { _Pragma("unroll") for (int m = 0; m < NM; ++m) _Pragma("unroll") for (int k = 0; k < 2; ++k) dst[m][k] = *(const LAS bf16x8*)(lds + PG8_SA(b, h) + aoff + m * 2048 + k * 1024); } while (0)
; #define PG8_MMA(ai, bj, At, Bt) do { __builtin_amdgcn_s_setprio(1); _Pragma("unroll") for (int m = 0; m < NM; ++m) _Pragma("unroll") for (int n = 0; n < 2; ++n) _Pragma("unroll") for (int k = 0; k < 2; ++k) \
;         acc[ai][bj][m][n] = __builtin_amdgcn_mfma_f32_16x16x32_bf16(Bt[n][k], At[m][k], acc[ai][bj][m][n], 0, 0, 0); __builtin_amdgcn_s_setprio(0); } while (0)
; #define PG8_WAIT_V(n) asm volatile("s_waitcnt vmcnt(" #n ")" ::: "memory")
; #define PG8_WAIT_L(n) asm volatile("s_waitcnt lgkmcnt(" #n ")" ::: "memory")
; #define PG8_BAR __builtin_amdgcn_s_barrier()
; #define PG8_SCHED __builtin_amdgcn_sched_barrier(0)
;     ...
;             PG8_WAIT_V(8); PG8_WAIT_L(0); PG8_BAR; PG8_MMA(0, 0, At, B0); PG8_MMA(0, 1, At, B1); PG8_BAR; PG8_SCHED;
;             PG8_LDA(At, 1, 1); PG8_STAGE(PG8_SB(1, 0), b3, voffB); PG8_STAGE(PG8_SB(1, 1), b3 + hstepB, voffB); PG8_STAGE(PG8_SA(1, 0), a3, voffA);
;             PG8_WAIT_V(8); PG8_WAIT_L(0); PG8_BAR; PG8_MMA(1, 0, At, B0); PG8_MMA(1, 1, At, B1); PG8_BAR; PG8_SCHED;
.Ltl_ou_2d:
	s_waitcnt lgkmcnt(0)
	s_barrier
	s_setprio 1
	s_waitcnt lgkmcnt(0)
	v_mfma_f32_16x16x32_bf16 v[46:49], v[90:93], v[130:133], v[46:49]
	v_mfma_f32_16x16x32_bf16 v[42:45], v[98:101], v[130:133], v[42:45]
	v_mfma_f32_16x16x32_bf16 v[30:33], v[90:93], v[138:141], v[30:33]
	v_mfma_f32_16x16x32_bf16 v[26:29], v[98:101], v[138:141], v[26:29]
	v_mfma_f32_16x16x32_bf16 v[14:17], v[90:93], v[156:159], v[14:17]
	v_mfma_f32_16x16x32_bf16 v[10:13], v[98:101], v[156:159], v[10:13]
	v_mfma_f32_16x16x32_bf16 v[46:49], v[94:97], v[134:137], v[46:49]
	v_mfma_f32_16x16x32_bf16 v[42:45], v[102:105], v[134:137], v[42:45]
	v_mfma_f32_16x16x32_bf16 v[30:33], v[94:97], v[152:155], v[30:33]
	v_mfma_f32_16x16x32_bf16 v[26:29], v[102:105], v[152:155], v[26:29]
	v_mfma_f32_16x16x32_bf16 v[14:17], v[94:97], v[160:163], v[14:17]
	v_mfma_f32_16x16x32_bf16 v[10:13], v[102:105], v[160:163], v[10:13]
	s_setprio 0
	s_setprio 1
	v_mfma_f32_16x16x32_bf16 v[38:41], v[114:117], v[130:133], v[38:41]
	v_mfma_f32_16x16x32_bf16 v[34:37], v[122:125], v[130:133], v[34:37]
	v_mfma_f32_16x16x32_bf16 v[22:25], v[114:117], v[138:141], v[22:25]
	v_mfma_f32_16x16x32_bf16 v[18:21], v[122:125], v[138:141], v[18:21]
	v_mfma_f32_16x16x32_bf16 v[6:9], v[114:117], v[156:159], v[6:9]
	v_mfma_f32_16x16x32_bf16 v[2:5], v[122:125], v[156:159], v[2:5]
	v_mfma_f32_16x16x32_bf16 v[38:41], v[118:121], v[134:137], v[38:41]
	v_mfma_f32_16x16x32_bf16 v[34:37], v[126:129], v[134:137], v[34:37]
	v_mfma_f32_16x16x32_bf16 v[22:25], v[118:121], v[152:155], v[22:25]
	v_mfma_f32_16x16x32_bf16 v[18:21], v[126:129], v[152:155], v[18:21]
	s_setprio 2
	s_barrier
	v_mfma_f32_16x16x32_bf16 v[6:9], v[118:121], v[160:163], v[6:9]
	v_mfma_f32_16x16x32_bf16 v[2:5], v[126:129], v[160:163], v[2:5]
	s_setprio 0
	s_add_i32 s59, s59, 2
	s_add_u32 s8, s8, 0x100
	s_addc_u32 s9, s9, 0
	s_add_u32 s15, s15, 0x100
	s_addc_u32 s58, s58, 0
	s_cmp_gt_u32 s59, 29
	s_cbranch_scc0 .LBB0_1650
	s_and_b64 vcc, exec, s[10:11]
	s_cbranch_vccz .LBB0_1653
	s_barrier

; #define PG8_STAGE(bufoff, gbase, voff) do { _Pragma("unroll") for (int _i = 0; _i < 2; ++_i) \
;         __builtin_amdgcn_global_load_lds((const unsigned*)((const char*)(gbase) + (voff)[_i]), (LAS unsigned*)(lds + (bufoff) + ldsw + _i * 8192), 16, 0, 0); } while (0)
; #define PG8_LDA(dst, b, h) do { _Pragma("unroll") for (int m = 0; m < NM; ++m) _Pragma("unroll") for (int k = 0; k < 2; ++k) dst[m][k] = *(const LAS bf16x8*)(lds + PG8_SA(b, h) + aoff + m * 2048 + k * 1024); } while (0)
; #define PG8_LDB(dst, b, h) do { _Pragma("unroll") for (int n = 0; n < 2; ++n) _Pragma("unroll") for (int k = 0; k < 2; ++k) dst[n][k] = *(const LAS bf16x8*)(lds + PG8_SB(b, h) + boff + n * 2048 + k * 1024); } while (0)
; #define PG8_MMA(ai, bj, At, Bt) do { __builtin_amdgcn_s_setprio(1); _Pragma("unroll") for (int m = 0; m < NM; ++m) _Pragma("unroll") for (int n = 0; n < 2; ++n) _Pragma("unroll") for (int k = 0; k < 2; ++k) \
;         acc[ai][bj][m][n] = __builtin_amdgcn_mfma_f32_16x16x32_bf16(Bt[n][k], At[m][k], acc[ai][bj][m][n], 0, 0, 0); __builtin_amdgcn_s_setprio(0); } while (0)
; #define PG8_WAIT_V(n) asm volatile("s_waitcnt vmcnt(" #n ")" ::: "memory")
; #define PG8_WAIT_L(n) asm volatile("s_waitcnt lgkmcnt(" #n ")" ::: "memory")
; #define PG8_BAR __builtin_amdgcn_s_barrier()
; #define PG8_SCHED __builtin_amdgcn_sched_barrier(0)
;     ...
;             PG8_LDB(B0, 0, 0); PG8_LDB(B1, 0, 1); PG8_SCHED; PG8_LDA(At, 0, 0); PG8_STAGE(PG8_SA(1, 1), a1 + hstepA, voffA);
;             PG8_WAIT_V(8); PG8_WAIT_L(0); PG8_BAR; PG8_MMA(0, 0, At, B0); PG8_MMA(0, 1, At, B1); PG8_BAR; PG8_SCHED;
;             PG8_LDA(At, 0, 1); PG8_STAGE(PG8_SB(0, 0), b2, voffB); PG8_STAGE(PG8_SB(0, 1), b2 + hstepB, voffB); PG8_STAGE(PG8_SA(0, 0), a2, voffA);
.LBB0_1783:
	v_add_u32_e32 v0, s64, v208
	ds_read_b128 v[130:133], v0
	ds_read_b128 v[134:137], v0 offset:1024
	ds_read_b128 v[138:141], v0 offset:2048
	ds_read_b128 v[142:145], v0 offset:3072
	v_add_u32_e32 v0, s70, v208
	ds_read_b128 v[146:149], v0
	ds_read_b128 v[150:153], v0 offset:1024
	ds_read_b128 v[154:157], v0 offset:2048
	ds_read_b128 v[158:161], v0 offset:3072
	s_add_u32 s14, s12, 0xfff80080
	s_addc_u32 s15, s13, -1
	s_cmp_eq_u32 vcc_lo, 28
	s_cselect_b32 s47, s2, s15
	s_cselect_b32 s46, s3, s14
	s_cselect_b32 s15, s9, s41
	s_cselect_b32 s14, s11, s37
	s_cselect_b32 s100, -1, 0
	s_andn2_b32 s100, s100, s101
	s_add_i32 m0, s73, 0xc000
	ds_read_b128 v[162:165], v209
	ds_read_b128 v[166:169], v209 offset:1024
	ds_read_b128 v[170:173], v209 offset:2048
	ds_read_b128 v[174:177], v209 offset:3072
	ds_read_b128 v[190:193], v209 offset:4096
	ds_read_b128 v[194:197], v209 offset:5120
	ds_read_b128 v[198:201], v209 offset:6144
	ds_read_b128 v[202:205], v209 offset:7168
	global_load_lds_dwordx4 v186, s[12:13]
	s_add_i32 m0, s73, 0xe000
	s_nop 0
	global_load_lds_dwordx4 v188, s[12:13]
	s_waitcnt vmcnt(8)
	s_waitcnt lgkmcnt(0)
	s_barrier
	s_setprio 1
	s_waitcnt lgkmcnt(0)
	v_mfma_f32_16x16x32_bf16 v[126:129], v[130:133], v[162:165], v[126:129]
	v_mfma_f32_16x16x32_bf16 v[94:97], v[138:141], v[162:165], v[94:97]
	v_mfma_f32_16x16x32_bf16 v[110:113], v[130:133], v[170:173], v[110:113]
	v_mfma_f32_16x16x32_bf16 v[70:73], v[138:141], v[170:173], v[70:73]
	v_mfma_f32_16x16x32_bf16 v[106:109], v[130:133], v[190:193], v[106:109]
	v_mfma_f32_16x16x32_bf16 v[66:69], v[138:141], v[190:193], v[66:69]
	v_mfma_f32_16x16x32_bf16 v[118:121], v[130:133], v[198:201], v[118:121]
	v_mfma_f32_16x16x32_bf16 v[86:89], v[138:141], v[198:201], v[86:89]
	v_mfma_f32_16x16x32_bf16 v[126:129], v[134:137], v[166:169], v[126:129]
	v_mfma_f32_16x16x32_bf16 v[94:97], v[142:145], v[166:169], v[94:97]
	v_mfma_f32_16x16x32_bf16 v[110:113], v[134:137], v[174:177], v[110:113]
	v_mfma_f32_16x16x32_bf16 v[70:73], v[142:145], v[174:177], v[70:73]
	v_mfma_f32_16x16x32_bf16 v[106:109], v[134:137], v[194:197], v[106:109]
	v_mfma_f32_16x16x32_bf16 v[66:69], v[142:145], v[194:197], v[66:69]
	v_mfma_f32_16x16x32_bf16 v[118:121], v[134:137], v[202:205], v[118:121]
	v_mfma_f32_16x16x32_bf16 v[86:89], v[142:145], v[202:205], v[86:89]
	s_setprio 0
	s_setprio 1
	v_mfma_f32_16x16x32_bf16 v[122:125], v[146:149], v[162:165], v[122:125]
	v_mfma_f32_16x16x32_bf16 v[90:93], v[154:157], v[162:165], v[90:93]
	v_mfma_f32_16x16x32_bf16 v[102:105], v[146:149], v[170:173], v[102:105]
	v_mfma_f32_16x16x32_bf16 v[62:65], v[154:157], v[170:173], v[62:65]
	v_mfma_f32_16x16x32_bf16 v[98:101], v[146:149], v[190:193], v[98:101]
	v_mfma_f32_16x16x32_bf16 v[58:61], v[154:157], v[190:193], v[58:61]
	v_mfma_f32_16x16x32_bf16 v[114:117], v[146:149], v[198:201], v[114:117]
	v_mfma_f32_16x16x32_bf16 v[82:85], v[154:157], v[198:201], v[82:85]
	v_mfma_f32_16x16x32_bf16 v[122:125], v[150:153], v[166:169], v[122:125]
	v_mfma_f32_16x16x32_bf16 v[90:93], v[158:161], v[166:169], v[90:93]
	v_mfma_f32_16x16x32_bf16 v[102:105], v[150:153], v[174:177], v[102:105]
	v_mfma_f32_16x16x32_bf16 v[62:65], v[158:161], v[174:177], v[62:65]
	v_mfma_f32_16x16x32_bf16 v[98:101], v[150:153], v[194:197], v[98:101]
	v_mfma_f32_16x16x32_bf16 v[58:61], v[158:161], v[194:197], v[58:61]
	s_setprio 2
	s_barrier
	v_mfma_f32_16x16x32_bf16 v[114:117], v[150:153], v[202:205], v[114:117]
	v_mfma_f32_16x16x32_bf16 v[82:85], v[158:161], v[202:205], v[82:85]
	s_setprio 0
	s_mov_b32 m0, s68
	s_add_u32 s22, s14, 0x80000
	s_addc_u32 s23, s15, 0
	ds_read_b128 v[162:165], v209 offset:16384
	ds_read_b128 v[166:169], v209 offset:17408
	ds_read_b128 v[170:173], v209 offset:18432
	ds_read_b128 v[174:177], v209 offset:19456
	ds_read_b128 v[190:193], v209 offset:20480
	ds_read_b128 v[194:197], v209 offset:21504
	ds_read_b128 v[198:201], v209 offset:22528
	ds_read_b128 v[202:205], v209 offset:23552
	s_cmp_lg_u32 s100, 0
	s_cbranch_scc1 .Ltl_up_0s
	global_load_lds_dwordx4 v180, s[14:15]
	s_mov_b32 m0, s69
	s_nop 0
	global_load_lds_dwordx4 v184, s[14:15]
	s_mov_b32 m0, s71
	s_nop 0
	global_load_lds_dwordx4 v180, s[22:23]
	s_mov_b32 m0, s72
	s_nop 0
	global_load_lds_dwordx4 v184, s[22:23]
	s_mov_b32 m0, s73
	s_nop 0
	global_load_lds_dwordx4 v178, s[46:47]
	s_mov_b32 m0, s74
	s_nop 0
	global_load_lds_dwordx4 v182, s[46:47]
	s_waitcnt vmcnt(8)
	s_branch .Ltl_up_0d

; #define PG8_STAGE(bufoff, gbase, voff) do { _Pragma("unroll") for (int _i = 0; _i < 2; ++_i) \
;         __builtin_amdgcn_global_load_lds((const unsigned*)((const char*)(gbase) + (voff)[_i]), (LAS unsigned*)(lds + (bufoff) + ldsw + _i * 8192), 16, 0, 0); } while (0)
; #define PG8_LDA(dst, b, h) do { _Pragma("unroll") for (int m = 0; m < NM; ++m) _Pragma("unroll") for (int k = 0; k < 2; ++k) dst[m][k] = *(const LAS bf16x8*)(lds + PG8_SA(b, h) + aoff + m * 2048 + k * 1024); } while (0)
; #define PG8_LDB(dst, b, h) do { _Pragma("unroll") for (int n = 0; n < 2; ++n) _Pragma("unroll") for (int k = 0; k < 2; ++k) dst[n][k] = *(const LAS bf16x8*)(lds + PG8_SB(b, h) + boff + n * 2048 + k * 1024); } while (0)
; #define PG8_MMA(ai, bj, At, Bt) do { __builtin_amdgcn_s_setprio(1); _Pragma("unroll") for (int m = 0; m < NM; ++m) _Pragma("unroll") for (int n = 0; n < 2; ++n) _Pragma("unroll") for (int k = 0; k < 2; ++k) \
;         acc[ai][bj][m][n] = __builtin_amdgcn_mfma_f32_16x16x32_bf16(Bt[n][k], At[m][k], acc[ai][bj][m][n], 0, 0, 0); __builtin_amdgcn_s_setprio(0); } while (0)
; #define PG8_WAIT_V(n) asm volatile("s_waitcnt vmcnt(" #n ")" ::: "memory")
; #define PG8_WAIT_L(n) asm volatile("s_waitcnt lgkmcnt(" #n ")" ::: "memory")
; #define PG8_BAR __builtin_amdgcn_s_barrier()
; #define PG8_SCHED __builtin_amdgcn_sched_barrier(0)
;     ...
;             PG8_WAIT_V(8); PG8_WAIT_L(0); PG8_BAR; PG8_MMA(1, 0, At, B0); PG8_MMA(1, 1, At, B1); PG8_BAR; PG8_SCHED;
;             PG8_LDB(B0, 1, 0); PG8_LDB(B1, 1, 1); PG8_SCHED; PG8_LDA(At, 1, 0); PG8_STAGE(PG8_SA(0, 1), a2 + hstepA, voffA);
.Ltl_up_0d:
	s_waitcnt lgkmcnt(0)
	s_barrier
	s_setprio 1
	s_waitcnt lgkmcnt(0)
	v_mfma_f32_16x16x32_bf16 v[46:49], v[130:133], v[162:165], v[46:49]
	v_mfma_f32_16x16x32_bf16 v[22:25], v[138:141], v[162:165], v[22:25]
	v_mfma_f32_16x16x32_bf16 v[42:45], v[130:133], v[170:173], v[42:45]
	v_mfma_f32_16x16x32_bf16 v[18:21], v[138:141], v[170:173], v[18:21]
	v_mfma_f32_16x16x32_bf16 v[38:41], v[130:133], v[190:193], v[38:41]
	v_mfma_f32_16x16x32_bf16 v[14:17], v[138:141], v[190:193], v[14:17]
	v_mfma_f32_16x16x32_bf16 v[78:81], v[130:133], v[198:201], v[78:81]
	v_mfma_f32_16x16x32_bf16 v[54:57], v[138:141], v[198:201], v[54:57]
	v_mfma_f32_16x16x32_bf16 v[46:49], v[134:137], v[166:169], v[46:49]
	v_mfma_f32_16x16x32_bf16 v[22:25], v[142:145], v[166:169], v[22:25]
	v_mfma_f32_16x16x32_bf16 v[42:45], v[134:137], v[174:177], v[42:45]
	v_mfma_f32_16x16x32_bf16 v[18:21], v[142:145], v[174:177], v[18:21]
	v_mfma_f32_16x16x32_bf16 v[38:41], v[134:137], v[194:197], v[38:41]
	v_mfma_f32_16x16x32_bf16 v[14:17], v[142:145], v[194:197], v[14:17]
	v_mfma_f32_16x16x32_bf16 v[78:81], v[134:137], v[202:205], v[78:81]
	v_mfma_f32_16x16x32_bf16 v[54:57], v[142:145], v[202:205], v[54:57]
	s_setprio 0
	s_setprio 1
	v_mfma_f32_16x16x32_bf16 v[34:37], v[146:149], v[162:165], v[34:37]
	v_mfma_f32_16x16x32_bf16 v[10:13], v[154:157], v[162:165], v[10:13]
	v_mfma_f32_16x16x32_bf16 v[30:33], v[146:149], v[170:173], v[30:33]
	v_mfma_f32_16x16x32_bf16 v[6:9], v[154:157], v[170:173], v[6:9]
	v_mfma_f32_16x16x32_bf16 v[26:29], v[146:149], v[190:193], v[26:29]
	v_mfma_f32_16x16x32_bf16 v[2:5], v[154:157], v[190:193], v[2:5]
	v_mfma_f32_16x16x32_bf16 v[74:77], v[146:149], v[198:201], v[74:77]
	v_mfma_f32_16x16x32_bf16 v[50:53], v[154:157], v[198:201], v[50:53]
	v_mfma_f32_16x16x32_bf16 v[34:37], v[150:153], v[166:169], v[34:37]
	v_mfma_f32_16x16x32_bf16 v[10:13], v[158:161], v[166:169], v[10:13]
	v_mfma_f32_16x16x32_bf16 v[30:33], v[150:153], v[174:177], v[30:33]
	v_mfma_f32_16x16x32_bf16 v[6:9], v[158:161], v[174:177], v[6:9]
	v_mfma_f32_16x16x32_bf16 v[26:29], v[150:153], v[194:197], v[26:29]
	v_mfma_f32_16x16x32_bf16 v[2:5], v[158:161], v[194:197], v[2:5]
	s_setprio 2
	s_barrier
	v_mfma_f32_16x16x32_bf16 v[74:77], v[150:153], v[202:205], v[74:77]
	v_mfma_f32_16x16x32_bf16 v[50:53], v[158:161], v[202:205], v[50:53]
	s_setprio 0
	v_add_u32_e32 v0, s94, v208
	ds_read_b128 v[130:133], v0
	ds_read_b128 v[134:137], v0 offset:1024
	ds_read_b128 v[138:141], v0 offset:2048
	ds_read_b128 v[142:145], v0 offset:3072
	v_add_u32_e32 v0, s62, v208
	ds_read_b128 v[146:149], v0
	ds_read_b128 v[150:153], v0 offset:1024
	ds_read_b128 v[154:157], v0 offset:2048
	ds_read_b128 v[158:161], v0 offset:3072
	s_add_u32 s22, s46, 0x80000
	s_addc_u32 s23, s47, 0
	s_mov_b32 m0, s75
	ds_read_b128 v[162:165], v209 offset:32768
	ds_read_b128 v[166:169], v209 offset:33792
	ds_read_b128 v[170:173], v209 offset:34816
	ds_read_b128 v[174:177], v209 offset:35840
	ds_read_b128 v[190:193], v209 offset:36864
	ds_read_b128 v[194:197], v209 offset:37888
	ds_read_b128 v[198:201], v209 offset:38912
	ds_read_b128 v[202:205], v209 offset:39936
	s_cmp_lg_u32 s100, 0
	s_cbranch_scc1 .Ltl_up_1s
	global_load_lds_dwordx4 v178, s[22:23]
	s_mov_b32 m0, s80
	s_nop 0
	global_load_lds_dwordx4 v182, s[22:23]
	s_waitcnt vmcnt(8)
	s_branch .Ltl_up_1d

; #define PG8_STAGE(bufoff, gbase, voff) do { _Pragma("unroll") for (int _i = 0; _i < 2; ++_i) \
;         __builtin_amdgcn_global_load_lds((const unsigned*)((const char*)(gbase) + (voff)[_i]), (LAS unsigned*)(lds + (bufoff) + ldsw + _i * 8192), 16, 0, 0); } while (0)
; #define PG8_LDA(dst, b, h) do { _Pragma("unroll") for (int m = 0; m < NM; ++m) _Pragma("unroll") for (int k = 0; k < 2; ++k) dst[m][k] = *(const LAS bf16x8*)(lds + PG8_SA(b, h) + aoff + m * 2048 + k * 1024); } while (0)
; #define PG8_MMA(ai, bj, At, Bt) do { __builtin_amdgcn_s_setprio(1); _Pragma("unroll") for (int m = 0; m < NM; ++m) _Pragma("unroll") for (int n = 0; n < 2; ++n) _Pragma("unroll") for (int k = 0; k < 2; ++k) \
;         acc[ai][bj][m][n] = __builtin_amdgcn_mfma_f32_16x16x32_bf16(Bt[n][k], At[m][k], acc[ai][bj][m][n], 0, 0, 0); __builtin_amdgcn_s_setprio(0); } while (0)
; #define PG8_WAIT_V(n) asm volatile("s_waitcnt vmcnt(" #n ")" ::: "memory")
; #define PG8_WAIT_L(n) asm volatile("s_waitcnt lgkmcnt(" #n ")" ::: "memory")
; #define PG8_BAR __builtin_amdgcn_s_barrier()
; #define PG8_SCHED __builtin_amdgcn_sched_barrier(0)
;     ...
;             PG8_WAIT_V(8); PG8_WAIT_L(0); PG8_BAR; PG8_MMA(0, 0, At, B0); PG8_MMA(0, 1, At, B1); PG8_BAR; PG8_SCHED;
;             PG8_LDA(At, 1, 1); PG8_STAGE(PG8_SB(1, 0), b3, voffB); PG8_STAGE(PG8_SB(1, 1), b3 + hstepB, voffB); PG8_STAGE(PG8_SA(1, 0), a3, voffA);
.Ltl_up_1d:
	s_waitcnt lgkmcnt(0)
	s_barrier
	s_setprio 1
	s_waitcnt lgkmcnt(0)
	v_mfma_f32_16x16x32_bf16 v[126:129], v[130:133], v[162:165], v[126:129]
	v_mfma_f32_16x16x32_bf16 v[94:97], v[138:141], v[162:165], v[94:97]
	v_mfma_f32_16x16x32_bf16 v[110:113], v[130:133], v[170:173], v[110:113]
	v_mfma_f32_16x16x32_bf16 v[70:73], v[138:141], v[170:173], v[70:73]
	v_mfma_f32_16x16x32_bf16 v[106:109], v[130:133], v[190:193], v[106:109]
	v_mfma_f32_16x16x32_bf16 v[66:69], v[138:141], v[190:193], v[66:69]
	v_mfma_f32_16x16x32_bf16 v[118:121], v[130:133], v[198:201], v[118:121]
	v_mfma_f32_16x16x32_bf16 v[86:89], v[138:141], v[198:201], v[86:89]
	v_mfma_f32_16x16x32_bf16 v[126:129], v[134:137], v[166:169], v[126:129]
	v_mfma_f32_16x16x32_bf16 v[94:97], v[142:145], v[166:169], v[94:97]
	v_mfma_f32_16x16x32_bf16 v[110:113], v[134:137], v[174:177], v[110:113]
	v_mfma_f32_16x16x32_bf16 v[70:73], v[142:145], v[174:177], v[70:73]
	v_mfma_f32_16x16x32_bf16 v[106:109], v[134:137], v[194:197], v[106:109]
	v_mfma_f32_16x16x32_bf16 v[66:69], v[142:145], v[194:197], v[66:69]
	v_mfma_f32_16x16x32_bf16 v[118:121], v[134:137], v[202:205], v[118:121]
	v_mfma_f32_16x16x32_bf16 v[86:89], v[142:145], v[202:205], v[86:89]
	s_setprio 0
	s_setprio 1
	v_mfma_f32_16x16x32_bf16 v[122:125], v[146:149], v[162:165], v[122:125]
	v_mfma_f32_16x16x32_bf16 v[90:93], v[154:157], v[162:165], v[90:93]
	v_mfma_f32_16x16x32_bf16 v[102:105], v[146:149], v[170:173], v[102:105]
	v_mfma_f32_16x16x32_bf16 v[62:65], v[154:157], v[170:173], v[62:65]
	v_mfma_f32_16x16x32_bf16 v[98:101], v[146:149], v[190:193], v[98:101]
	v_mfma_f32_16x16x32_bf16 v[58:61], v[154:157], v[190:193], v[58:61]
	v_mfma_f32_16x16x32_bf16 v[114:117], v[146:149], v[198:201], v[114:117]
	v_mfma_f32_16x16x32_bf16 v[82:85], v[154:157], v[198:201], v[82:85]
	v_mfma_f32_16x16x32_bf16 v[122:125], v[150:153], v[166:169], v[122:125]
	v_mfma_f32_16x16x32_bf16 v[90:93], v[158:161], v[166:169], v[90:93]
	v_mfma_f32_16x16x32_bf16 v[102:105], v[150:153], v[174:177], v[102:105]
	v_mfma_f32_16x16x32_bf16 v[62:65], v[158:161], v[174:177], v[62:65]
	v_mfma_f32_16x16x32_bf16 v[98:101], v[150:153], v[194:197], v[98:101]
	v_mfma_f32_16x16x32_bf16 v[58:61], v[158:161], v[194:197], v[58:61]
	s_setprio 2
	s_barrier
	v_mfma_f32_16x16x32_bf16 v[114:117], v[150:153], v[202:205], v[114:117]
	v_mfma_f32_16x16x32_bf16 v[82:85], v[158:161], v[202:205], v[82:85]
	s_setprio 0
	s_mov_b32 m0, s51
	s_add_u32 s22, s14, s66
	s_addc_u32 s23, s15, s67
	s_add_u32 s14, s14, 0x80080
	s_addc_u32 s15, s15, 0
	ds_read_b128 v[162:165], v209 offset:49152
	ds_read_b128 v[166:169], v209 offset:50176
	ds_read_b128 v[170:173], v209 offset:51200
	ds_read_b128 v[174:177], v209 offset:52224
	ds_read_b128 v[190:193], v209 offset:53248
	ds_read_b128 v[194:197], v209 offset:54272
	ds_read_b128 v[198:201], v209 offset:55296
	ds_read_b128 v[202:205], v209 offset:56320
	s_cmp_lg_u32 s100, 0
	s_cbranch_scc1 .Ltl_up_2s
	global_load_lds_dwordx4 v180, s[22:23]
	s_mov_b32 m0, s95
	s_nop 0
	global_load_lds_dwordx4 v184, s[22:23]
	s_add_u32 s22, s46, s66
	s_addc_u32 s23, s47, s67
	s_mov_b32 m0, s50
	s_nop 0
	global_load_lds_dwordx4 v180, s[14:15]
	s_mov_b32 m0, s49
	s_nop 0
	global_load_lds_dwordx4 v184, s[14:15]
	s_mov_b32 m0, s58
	s_nop 0
	global_load_lds_dwordx4 v178, s[22:23]
	s_mov_b32 m0, s59
	s_nop 0
	global_load_lds_dwordx4 v182, s[22:23]
	s_waitcnt vmcnt(8)
	s_branch .Ltl_up_2d

; #define PG8_STAGE(bufoff, gbase, voff) do { _Pragma("unroll") for (int _i = 0; _i < 2; ++_i) \
;         __builtin_amdgcn_global_load_lds((const unsigned*)((const char*)(gbase) + (voff)[_i]), (LAS unsigned*)(lds + (bufoff) + ldsw + _i * 8192), 16, 0, 0); } while (0)
; #define PG8_LDA(dst, b, h) do { _Pragma("unroll") for (int m = 0; m < NM; ++m) _Pragma("unroll") for (int k = 0; k < 2; ++k) dst[m][k] = *(const LAS bf16x8*)(lds + PG8_SA(b, h) + aoff + m * 2048 + k * 1024); } while (0)
; #define PG8_MMA(ai, bj, At, Bt) do { __builtin_amdgcn_s_setprio(1); _Pragma("unroll") for (int m = 0; m < NM; ++m) _Pragma("unroll") for (int n = 0; n < 2; ++n) _Pragma("unroll") for (int k = 0; k < 2; ++k) \
;         acc[ai][bj][m][n] = __builtin_amdgcn_mfma_f32_16x16x32_bf16(Bt[n][k], At[m][k], acc[ai][bj][m][n], 0, 0, 0); __builtin_amdgcn_s_setprio(0); } while (0)
; #define PG8_WAIT_V(n) asm volatile("s_waitcnt vmcnt(" #n ")" ::: "memory")
; #define PG8_WAIT_L(n) asm volatile("s_waitcnt lgkmcnt(" #n ")" ::: "memory")
; #define PG8_BAR __builtin_amdgcn_s_barrier()
; #define PG8_SCHED __builtin_amdgcn_sched_barrier(0)
;     ...
;             PG8_WAIT_V(8); PG8_WAIT_L(0); PG8_BAR; PG8_MMA(0, 0, At, B0); PG8_MMA(0, 1, At, B1); PG8_BAR; PG8_SCHED;
;             PG8_LDA(At, 1, 1); PG8_STAGE(PG8_SB(1, 0), b3, voffB); PG8_STAGE(PG8_SB(1, 1), b3 + hstepB, voffB); PG8_STAGE(PG8_SA(1, 0), a3, voffA);
;             PG8_WAIT_V(8); PG8_WAIT_L(0); PG8_BAR; PG8_MMA(1, 0, At, B0); PG8_MMA(1, 1, At, B1); PG8_BAR; PG8_SCHED;
.Ltl_up_2d:
	s_waitcnt lgkmcnt(0)
	s_barrier
	s_setprio 1
	s_waitcnt lgkmcnt(0)
	v_mfma_f32_16x16x32_bf16 v[46:49], v[130:133], v[162:165], v[46:49]
	v_mfma_f32_16x16x32_bf16 v[22:25], v[138:141], v[162:165], v[22:25]
	v_mfma_f32_16x16x32_bf16 v[42:45], v[130:133], v[170:173], v[42:45]
	v_mfma_f32_16x16x32_bf16 v[18:21], v[138:141], v[170:173], v[18:21]
	v_mfma_f32_16x16x32_bf16 v[38:41], v[130:133], v[190:193], v[38:41]
	v_mfma_f32_16x16x32_bf16 v[14:17], v[138:141], v[190:193], v[14:17]
	v_mfma_f32_16x16x32_bf16 v[78:81], v[130:133], v[198:201], v[78:81]
	v_mfma_f32_16x16x32_bf16 v[54:57], v[138:141], v[198:201], v[54:57]
	v_mfma_f32_16x16x32_bf16 v[46:49], v[134:137], v[166:169], v[46:49]
	v_mfma_f32_16x16x32_bf16 v[22:25], v[142:145], v[166:169], v[22:25]
	v_mfma_f32_16x16x32_bf16 v[42:45], v[134:137], v[174:177], v[42:45]
	v_mfma_f32_16x16x32_bf16 v[18:21], v[142:145], v[174:177], v[18:21]
	v_mfma_f32_16x16x32_bf16 v[38:41], v[134:137], v[194:197], v[38:41]
	v_mfma_f32_16x16x32_bf16 v[14:17], v[142:145], v[194:197], v[14:17]
	v_mfma_f32_16x16x32_bf16 v[78:81], v[134:137], v[202:205], v[78:81]
	v_mfma_f32_16x16x32_bf16 v[54:57], v[142:145], v[202:205], v[54:57]
	s_setprio 0
	s_setprio 1
	v_mfma_f32_16x16x32_bf16 v[34:37], v[146:149], v[162:165], v[34:37]
	v_mfma_f32_16x16x32_bf16 v[10:13], v[154:157], v[162:165], v[10:13]
	v_mfma_f32_16x16x32_bf16 v[30:33], v[146:149], v[170:173], v[30:33]
	v_mfma_f32_16x16x32_bf16 v[6:9], v[154:157], v[170:173], v[6:9]
	v_mfma_f32_16x16x32_bf16 v[26:29], v[146:149], v[190:193], v[26:29]
	v_mfma_f32_16x16x32_bf16 v[2:5], v[154:157], v[190:193], v[2:5]
	v_mfma_f32_16x16x32_bf16 v[74:77], v[146:149], v[198:201], v[74:77]
	v_mfma_f32_16x16x32_bf16 v[50:53], v[154:157], v[198:201], v[50:53]
	v_mfma_f32_16x16x32_bf16 v[34:37], v[150:153], v[166:169], v[34:37]
	v_mfma_f32_16x16x32_bf16 v[10:13], v[158:161], v[166:169], v[10:13]
	v_mfma_f32_16x16x32_bf16 v[30:33], v[150:153], v[174:177], v[30:33]
	v_mfma_f32_16x16x32_bf16 v[6:9], v[158:161], v[174:177], v[6:9]
	v_mfma_f32_16x16x32_bf16 v[26:29], v[150:153], v[194:197], v[26:29]
	v_mfma_f32_16x16x32_bf16 v[2:5], v[158:161], v[194:197], v[2:5]
	s_setprio 2
	s_barrier
	v_mfma_f32_16x16x32_bf16 v[74:77], v[150:153], v[202:205], v[74:77]
	v_mfma_f32_16x16x32_bf16 v[50:53], v[158:161], v[202:205], v[50:53]
	s_setprio 0
	s_add_i32 vcc_lo, vcc_lo, 2
	s_add_u32 s12, s12, 0x100
	s_addc_u32 s13, s13, 0
	s_add_u32 s37, s37, 0x100
	s_addc_u32 s41, s41, 0
	s_cmp_gt_u32 vcc_lo, 29
	s_cbranch_scc0 .LBB0_1783
	s_and_b64 vcc, exec, s[24:25]
	s_cbranch_vccz .LBB0_1786
	s_barrier

; #define PG8_STAGE(bufoff, gbase, voff) do { _Pragma("unroll") for (int _i = 0; _i < 2; ++_i) \
;         __builtin_amdgcn_global_load_lds((const unsigned*)((const char*)(gbase) + (voff)[_i]), (LAS unsigned*)(lds + (bufoff) + ldsw + _i * 8192), 16, 0, 0); } while (0)
; #define PG8_LDA(dst, b, h) do { _Pragma("unroll") for (int m = 0; m < NM; ++m) _Pragma("unroll") for (int k = 0; k < 2; ++k) dst[m][k] = *(const LAS bf16x8*)(lds + PG8_SA(b, h) + aoff + m * 2048 + k * 1024); } while (0)
; #define PG8_MMA(ai, bj, At, Bt) do { __builtin_amdgcn_s_setprio(1); _Pragma("unroll") for (int m = 0; m < NM; ++m) _Pragma("unroll") for (int n = 0; n < 2; ++n) _Pragma("unroll") for (int k = 0; k < 2; ++k) \
;         acc[ai][bj][m][n] = __builtin_amdgcn_mfma_f32_16x16x32_bf16(Bt[n][k], At[m][k], acc[ai][bj][m][n], 0, 0, 0); __builtin_amdgcn_s_setprio(0); } while (0)
; #define PG8_WAIT_V(n) asm volatile("s_waitcnt vmcnt(" #n ")" ::: "memory")
; #define PG8_WAIT_L(n) asm volatile("s_waitcnt lgkmcnt(" #n ")" ::: "memory")
; #define PG8_BAR __builtin_amdgcn_s_barrier()
; #define PG8_SCHED __builtin_amdgcn_sched_barrier(0)
;     ...
;             PG8_WAIT_V(8); PG8_WAIT_L(0); PG8_BAR; PG8_MMA(0, 0, At, B0); PG8_MMA(0, 1, At, B1); PG8_BAR; PG8_SCHED;
;             PG8_LDA(At, 0, 1); PG8_STAGE(PG8_SB(0, 0), b2, voffB); PG8_STAGE(PG8_SB(0, 1), b2 + hstepB, voffB); PG8_STAGE(PG8_SA(0, 0), a2, voffA);
.Lnm3d_done0:
	s_waitcnt lgkmcnt(0)
	s_barrier
	s_setprio 1
	s_waitcnt lgkmcnt(0)
	v_mfma_f32_16x16x32_bf16 v[110:113], v[90:93], v[130:133], v[110:113]
	v_mfma_f32_16x16x32_bf16 v[106:109], v[98:101], v[130:133], v[106:109]
	v_mfma_f32_16x16x32_bf16 v[78:81], v[90:93], v[138:141], v[78:81]
	v_mfma_f32_16x16x32_bf16 v[74:77], v[98:101], v[138:141], v[74:77]
	v_mfma_f32_16x16x32_bf16 v[62:65], v[90:93], v[156:159], v[62:65]
	v_mfma_f32_16x16x32_bf16 v[58:61], v[98:101], v[156:159], v[58:61]
	v_mfma_f32_16x16x32_bf16 v[110:113], v[94:97], v[134:137], v[110:113]
	v_mfma_f32_16x16x32_bf16 v[106:109], v[102:105], v[134:137], v[106:109]
	v_mfma_f32_16x16x32_bf16 v[78:81], v[94:97], v[152:155], v[78:81]
	v_mfma_f32_16x16x32_bf16 v[74:77], v[102:105], v[152:155], v[74:77]
	v_mfma_f32_16x16x32_bf16 v[62:65], v[94:97], v[160:163], v[62:65]
	v_mfma_f32_16x16x32_bf16 v[58:61], v[102:105], v[160:163], v[58:61]
	s_setprio 0
	s_setprio 1
	v_mfma_f32_16x16x32_bf16 v[86:89], v[114:117], v[130:133], v[86:89]
	v_mfma_f32_16x16x32_bf16 v[82:85], v[122:125], v[130:133], v[82:85]
	v_mfma_f32_16x16x32_bf16 v[70:73], v[114:117], v[138:141], v[70:73]
	v_mfma_f32_16x16x32_bf16 v[66:69], v[122:125], v[138:141], v[66:69]
	v_mfma_f32_16x16x32_bf16 v[54:57], v[114:117], v[156:159], v[54:57]
	v_mfma_f32_16x16x32_bf16 v[50:53], v[122:125], v[156:159], v[50:53]
	v_mfma_f32_16x16x32_bf16 v[86:89], v[118:121], v[134:137], v[86:89]
	v_mfma_f32_16x16x32_bf16 v[82:85], v[126:129], v[134:137], v[82:85]
	v_mfma_f32_16x16x32_bf16 v[70:73], v[118:121], v[152:155], v[70:73]
	v_mfma_f32_16x16x32_bf16 v[66:69], v[126:129], v[152:155], v[66:69]
	s_setprio 2
	s_barrier
	v_mfma_f32_16x16x32_bf16 v[54:57], v[118:121], v[160:163], v[54:57]
	v_mfma_f32_16x16x32_bf16 v[50:53], v[126:129], v[160:163], v[50:53]
	s_setprio 0
	s_mov_b32 m0, s27
	v_lshl_add_u64 v[164:165], s[18:19], 0, v[0:1]
	s_add_u32 s14, s18, 0x160000
	s_addc_u32 s15, s19, 0
	ds_read_b128 v[130:133], v167 offset:16384
	ds_read_b128 v[134:137], v167 offset:17408
	ds_read_b128 v[138:141], v167 offset:18432
	ds_read_b128 v[152:155], v167 offset:19456
	ds_read_b128 v[156:159], v167 offset:20480
	ds_read_b128 v[160:163], v167 offset:21504
	s_cmp_lg_u32 s100, 0
	s_cbranch_scc1 .Ltl_dn_0s
	global_load_lds_dwordx4 v0, s[18:19]
	v_lshl_add_u64 v[168:169], s[18:19], 0, v[146:147]
	s_mov_b32 m0, s28
	s_nop 0
	global_load_lds_dwordx4 v146, s[18:19]
	s_mov_b32 m0, s30
	v_lshl_add_u64 v[172:173], s[20:21], 0, v[144:145]
	global_load_lds_dwordx4 v0, s[14:15]
	s_mov_b32 m0, s31
	s_nop 0
	global_load_lds_dwordx4 v146, s[14:15]
	v_lshl_add_u64 v[170:171], s[20:21], 0, v[142:143]
	s_mov_b32 m0, s34
	s_nop 0
	global_load_lds_dwordx4 v142, s[20:21]
	s_mov_b32 m0, s35
	s_nop 0
	s_and_b64 vcc, exec, s[8:9]
	s_cbranch_vccz .Lnm3d_skip1
	global_load_lds_dwordx4 v144, s[20:21]
	s_waitcnt vmcnt(8)
	s_branch .Lnm3d_done1

; #define PG8_STAGE(bufoff, gbase, voff) do { _Pragma("unroll") for (int _i = 0; _i < 2; ++_i) \
;         __builtin_amdgcn_global_load_lds((const unsigned*)((const char*)(gbase) + (voff)[_i]), (LAS unsigned*)(lds + (bufoff) + ldsw + _i * 8192), 16, 0, 0); } while (0)
; #define PG8_LDA(dst, b, h) do { _Pragma("unroll") for (int m = 0; m < NM; ++m) _Pragma("unroll") for (int k = 0; k < 2; ++k) dst[m][k] = *(const LAS bf16x8*)(lds + PG8_SA(b, h) + aoff + m * 2048 + k * 1024); } while (0)
; #define PG8_LDB(dst, b, h) do { _Pragma("unroll") for (int n = 0; n < 2; ++n) _Pragma("unroll") for (int k = 0; k < 2; ++k) dst[n][k] = *(const LAS bf16x8*)(lds + PG8_SB(b, h) + boff + n * 2048 + k * 1024); } while (0)
; #define PG8_MMA(ai, bj, At, Bt) do { __builtin_amdgcn_s_setprio(1); _Pragma("unroll") for (int m = 0; m < NM; ++m) _Pragma("unroll") for (int n = 0; n < 2; ++n) _Pragma("unroll") for (int k = 0; k < 2; ++k) \
;         acc[ai][bj][m][n] = __builtin_amdgcn_mfma_f32_16x16x32_bf16(Bt[n][k], At[m][k], acc[ai][bj][m][n], 0, 0, 0); __builtin_amdgcn_s_setprio(0); } while (0)
; #define PG8_WAIT_V(n) asm volatile("s_waitcnt vmcnt(" #n ")" ::: "memory")
; #define PG8_WAIT_L(n) asm volatile("s_waitcnt lgkmcnt(" #n ")" ::: "memory")
; #define PG8_BAR __builtin_amdgcn_s_barrier()
; #define PG8_SCHED __builtin_amdgcn_sched_barrier(0)
;     ...
;             PG8_WAIT_V(8); PG8_WAIT_L(0); PG8_BAR; PG8_MMA(1, 0, At, B0); PG8_MMA(1, 1, At, B1); PG8_BAR; PG8_SCHED;
;             PG8_LDB(B0, 1, 0); PG8_LDB(B1, 1, 1); PG8_SCHED; PG8_LDA(At, 1, 0); PG8_STAGE(PG8_SA(0, 1), a2 + hstepA, voffA);
.Ltl_dn_0d:
	s_waitcnt lgkmcnt(0)
	s_barrier
	s_setprio 1
	s_waitcnt lgkmcnt(0)
	v_mfma_f32_16x16x32_bf16 v[46:49], v[90:93], v[130:133], v[46:49]
	v_mfma_f32_16x16x32_bf16 v[42:45], v[98:101], v[130:133], v[42:45]
	v_mfma_f32_16x16x32_bf16 v[30:33], v[90:93], v[138:141], v[30:33]
	v_mfma_f32_16x16x32_bf16 v[26:29], v[98:101], v[138:141], v[26:29]
	v_mfma_f32_16x16x32_bf16 v[14:17], v[90:93], v[156:159], v[14:17]
	v_mfma_f32_16x16x32_bf16 v[10:13], v[98:101], v[156:159], v[10:13]
	v_mfma_f32_16x16x32_bf16 v[46:49], v[94:97], v[134:137], v[46:49]
	v_mfma_f32_16x16x32_bf16 v[42:45], v[102:105], v[134:137], v[42:45]
	v_mfma_f32_16x16x32_bf16 v[30:33], v[94:97], v[152:155], v[30:33]
	v_mfma_f32_16x16x32_bf16 v[26:29], v[102:105], v[152:155], v[26:29]
	v_mfma_f32_16x16x32_bf16 v[14:17], v[94:97], v[160:163], v[14:17]
	v_mfma_f32_16x16x32_bf16 v[10:13], v[102:105], v[160:163], v[10:13]
	s_setprio 0
	s_setprio 1
	v_mfma_f32_16x16x32_bf16 v[38:41], v[114:117], v[130:133], v[38:41]
	v_mfma_f32_16x16x32_bf16 v[34:37], v[122:125], v[130:133], v[34:37]
	v_mfma_f32_16x16x32_bf16 v[22:25], v[114:117], v[138:141], v[22:25]
	v_mfma_f32_16x16x32_bf16 v[18:21], v[122:125], v[138:141], v[18:21]
	v_mfma_f32_16x16x32_bf16 v[6:9], v[114:117], v[156:159], v[6:9]
	v_mfma_f32_16x16x32_bf16 v[2:5], v[122:125], v[156:159], v[2:5]
	v_mfma_f32_16x16x32_bf16 v[38:41], v[118:121], v[134:137], v[38:41]
	v_mfma_f32_16x16x32_bf16 v[34:37], v[126:129], v[134:137], v[34:37]
	v_mfma_f32_16x16x32_bf16 v[22:25], v[118:121], v[152:155], v[22:25]
	v_mfma_f32_16x16x32_bf16 v[18:21], v[126:129], v[152:155], v[18:21]
	s_setprio 2
	s_barrier
	v_mfma_f32_16x16x32_bf16 v[6:9], v[118:121], v[160:163], v[6:9]
	v_mfma_f32_16x16x32_bf16 v[2:5], v[126:129], v[160:163], v[2:5]
	s_setprio 0
	v_add_u32_e32 v102, s38, v166
	v_add_u32_e32 v126, s45, v166
	ds_read_b128 v[90:93], v102
	ds_read_b128 v[94:97], v102 offset:1024
	ds_read_b128 v[98:101], v102 offset:2048
	ds_read_b128 v[102:105], v102 offset:3072
	ds_read_b128 v[114:117], v126
	ds_read_b128 v[118:121], v126 offset:1024
	ds_read_b128 v[122:125], v126 offset:2048
	ds_read_b128 v[126:129], v126 offset:3072
	s_add_u32 s14, s20, 0x108000
	s_addc_u32 s15, s21, 0
	s_mov_b32 m0, s36
	ds_read_b128 v[130:133], v167 offset:32768
	ds_read_b128 v[134:137], v167 offset:33792
	ds_read_b128 v[138:141], v167 offset:34816
	ds_read_b128 v[152:155], v167 offset:35840
	ds_read_b128 v[156:159], v167 offset:36864
	ds_read_b128 v[160:163], v167 offset:37888
	s_cmp_lg_u32 s100, 0
	s_cbranch_scc1 .Ltl_dn_1s
	global_load_lds_dwordx4 v142, s[14:15]
	s_mov_b32 m0, s37
	s_nop 0
	s_and_b64 vcc, exec, s[8:9]
	s_cbranch_vccz .Lnm3d_skip2
	global_load_lds_dwordx4 v144, s[14:15]
	s_waitcnt vmcnt(8)
	s_branch .Lnm3d_done2

; #define PG8_STAGE(bufoff, gbase, voff) do { _Pragma("unroll") for (int _i = 0; _i < 2; ++_i) \
;         __builtin_amdgcn_global_load_lds((const unsigned*)((const char*)(gbase) + (voff)[_i]), (LAS unsigned*)(lds + (bufoff) + ldsw + _i * 8192), 16, 0, 0); } while (0)
; #define PG8_LDA(dst, b, h) do { _Pragma("unroll") for (int m = 0; m < NM; ++m) _Pragma("unroll") for (int k = 0; k < 2; ++k) dst[m][k] = *(const LAS bf16x8*)(lds + PG8_SA(b, h) + aoff + m * 2048 + k * 1024); } while (0)
; #define PG8_MMA(ai, bj, At, Bt) do { __builtin_amdgcn_s_setprio(1); _Pragma("unroll") for (int m = 0; m < NM; ++m) _Pragma("unroll") for (int n = 0; n < 2; ++n) _Pragma("unroll") for (int k = 0; k < 2; ++k) \
;         acc[ai][bj][m][n] = __builtin_amdgcn_mfma_f32_16x16x32_bf16(Bt[n][k], At[m][k], acc[ai][bj][m][n], 0, 0, 0); __builtin_amdgcn_s_setprio(0); } while (0)
; #define PG8_WAIT_V(n) asm volatile("s_waitcnt vmcnt(" #n ")" ::: "memory")
; #define PG8_WAIT_L(n) asm volatile("s_waitcnt lgkmcnt(" #n ")" ::: "memory")
; #define PG8_BAR __builtin_amdgcn_s_barrier()
; #define PG8_SCHED __builtin_amdgcn_sched_barrier(0)
;     ...
;             PG8_WAIT_V(8); PG8_WAIT_L(0); PG8_BAR; PG8_MMA(0, 0, At, B0); PG8_MMA(0, 1, At, B1); PG8_BAR; PG8_SCHED;
;             PG8_LDA(At, 1, 1); PG8_STAGE(PG8_SB(1, 0), b3, voffB); PG8_STAGE(PG8_SB(1, 1), b3 + hstepB, voffB); PG8_STAGE(PG8_SA(1, 0), a3, voffA);
.Ltl_dn_1d:
	s_waitcnt lgkmcnt(0)
	s_barrier
	s_setprio 1
	s_waitcnt lgkmcnt(0)
	v_mfma_f32_16x16x32_bf16 v[110:113], v[90:93], v[130:133], v[110:113]
	v_mfma_f32_16x16x32_bf16 v[106:109], v[98:101], v[130:133], v[106:109]
	v_mfma_f32_16x16x32_bf16 v[78:81], v[90:93], v[138:141], v[78:81]
	v_mfma_f32_16x16x32_bf16 v[74:77], v[98:101], v[138:141], v[74:77]
	v_mfma_f32_16x16x32_bf16 v[62:65], v[90:93], v[156:159], v[62:65]
	v_mfma_f32_16x16x32_bf16 v[58:61], v[98:101], v[156:159], v[58:61]
	v_mfma_f32_16x16x32_bf16 v[110:113], v[94:97], v[134:137], v[110:113]
	v_mfma_f32_16x16x32_bf16 v[106:109], v[102:105], v[134:137], v[106:109]
	v_mfma_f32_16x16x32_bf16 v[78:81], v[94:97], v[152:155], v[78:81]
	v_mfma_f32_16x16x32_bf16 v[74:77], v[102:105], v[152:155], v[74:77]
	v_mfma_f32_16x16x32_bf16 v[62:65], v[94:97], v[160:163], v[62:65]
	v_mfma_f32_16x16x32_bf16 v[58:61], v[102:105], v[160:163], v[58:61]
	s_setprio 0
	s_setprio 1
	v_mfma_f32_16x16x32_bf16 v[86:89], v[114:117], v[130:133], v[86:89]
	v_mfma_f32_16x16x32_bf16 v[82:85], v[122:125], v[130:133], v[82:85]
	v_mfma_f32_16x16x32_bf16 v[70:73], v[114:117], v[138:141], v[70:73]
	v_mfma_f32_16x16x32_bf16 v[66:69], v[122:125], v[138:141], v[66:69]
	v_mfma_f32_16x16x32_bf16 v[54:57], v[114:117], v[156:159], v[54:57]
	v_mfma_f32_16x16x32_bf16 v[50:53], v[122:125], v[156:159], v[50:53]
	v_mfma_f32_16x16x32_bf16 v[86:89], v[118:121], v[134:137], v[86:89]
	v_mfma_f32_16x16x32_bf16 v[82:85], v[126:129], v[134:137], v[82:85]
	v_mfma_f32_16x16x32_bf16 v[70:73], v[118:121], v[152:155], v[70:73]
	v_mfma_f32_16x16x32_bf16 v[66:69], v[126:129], v[152:155], v[66:69]
	s_setprio 2
	s_barrier
	v_mfma_f32_16x16x32_bf16 v[54:57], v[118:121], v[160:163], v[54:57]
	v_mfma_f32_16x16x32_bf16 v[50:53], v[126:129], v[160:163], v[50:53]
	s_setprio 0
	s_mov_b32 m0, s41
	v_lshl_add_u64 v[164:165], v[164:165], 0, s[66:67]
	s_add_u32 s14, s18, 0x160080
	s_addc_u32 s15, s19, 0
	ds_read_b128 v[130:133], v167 offset:49152
	ds_read_b128 v[134:137], v167 offset:50176
	ds_read_b128 v[138:141], v167 offset:51200
	ds_read_b128 v[152:155], v167 offset:52224
	ds_read_b128 v[156:159], v167 offset:53248
	ds_read_b128 v[160:163], v167 offset:54272
	s_cmp_lg_u32 s100, 0
	s_cbranch_scc1 .Ltl_dn_2s
	global_load_lds_dwordx4 v[164:165], off
	v_lshl_add_u64 v[164:165], v[168:169], 0, s[66:67]
	s_mov_b32 m0, s42
	s_nop 0
	global_load_lds_dwordx4 v[164:165], off
	s_mov_b32 m0, s46
	s_nop 0
	global_load_lds_dwordx4 v0, s[14:15]
	s_mov_b32 m0, s47
	s_nop 0
	global_load_lds_dwordx4 v146, s[14:15]
	v_lshl_add_u64 v[164:165], v[170:171], 0, s[66:67]
	s_mov_b32 m0, s43
	s_nop 0
	global_load_lds_dwordx4 v[164:165], off
	v_lshl_add_u64 v[164:165], v[172:173], 0, s[66:67]
	s_mov_b32 m0, s44
	s_nop 0
	s_and_b64 vcc, exec, s[8:9]
	s_cbranch_vccz .Lnm3d_skip3
	global_load_lds_dwordx4 v[164:165], off
	s_waitcnt vmcnt(8)
	s_branch .Lnm3d_done3

; #define PG8_STAGE(bufoff, gbase, voff) do { _Pragma("unroll") for (int _i = 0; _i < 2; ++_i) \
;         __builtin_amdgcn_global_load_lds((const unsigned*)((const char*)(gbase) + (voff)[_i]), (LAS unsigned*)(lds + (bufoff) + ldsw + _i * 8192), 16, 0, 0); } while (0)
; #define PG8_LDA(dst, b, h) do { _Pragma("unroll") for (int m = 0; m < NM; ++m) _Pragma("unroll") for (int k = 0; k < 2; ++k) dst[m][k] = *(const LAS bf16x8*)(lds + PG8_SA(b, h) + aoff + m * 2048 + k * 1024); } while (0)
; #define PG8_MMA(ai, bj, At, Bt) do { __builtin_amdgcn_s_setprio(1); _Pragma("unroll") for (int m = 0; m < NM; ++m) _Pragma("unroll") for (int n = 0; n < 2; ++n) _Pragma("unroll") for (int k = 0; k < 2; ++k) \
;         acc[ai][bj][m][n] = __builtin_amdgcn_mfma_f32_16x16x32_bf16(Bt[n][k], At[m][k], acc[ai][bj][m][n], 0, 0, 0); __builtin_amdgcn_s_setprio(0); } while (0)
; #define PG8_WAIT_V(n) asm volatile("s_waitcnt vmcnt(" #n ")" ::: "memory")
; #define PG8_WAIT_L(n) asm volatile("s_waitcnt lgkmcnt(" #n ")" ::: "memory")
; #define PG8_BAR __builtin_amdgcn_s_barrier()
; #define PG8_SCHED __builtin_amdgcn_sched_barrier(0)
;     ...
;             PG8_WAIT_V(8); PG8_WAIT_L(0); PG8_BAR; PG8_MMA(0, 0, At, B0); PG8_MMA(0, 1, At, B1); PG8_BAR; PG8_SCHED;
;             PG8_LDA(At, 1, 1); PG8_STAGE(PG8_SB(1, 0), b3, voffB); PG8_STAGE(PG8_SB(1, 1), b3 + hstepB, voffB); PG8_STAGE(PG8_SA(1, 0), a3, voffA);
;             PG8_WAIT_V(8); PG8_WAIT_L(0); PG8_BAR; PG8_MMA(1, 0, At, B0); PG8_MMA(1, 1, At, B1); PG8_BAR; PG8_SCHED;
.Ltl_dn_2d:
	s_waitcnt lgkmcnt(0)
	s_barrier
	s_setprio 1
	s_waitcnt lgkmcnt(0)
	v_mfma_f32_16x16x32_bf16 v[46:49], v[90:93], v[130:133], v[46:49]
	v_mfma_f32_16x16x32_bf16 v[42:45], v[98:101], v[130:133], v[42:45]
	v_mfma_f32_16x16x32_bf16 v[30:33], v[90:93], v[138:141], v[30:33]
	v_mfma_f32_16x16x32_bf16 v[26:29], v[98:101], v[138:141], v[26:29]
	v_mfma_f32_16x16x32_bf16 v[14:17], v[90:93], v[156:159], v[14:17]
	v_mfma_f32_16x16x32_bf16 v[10:13], v[98:101], v[156:159], v[10:13]
	v_mfma_f32_16x16x32_bf16 v[46:49], v[94:97], v[134:137], v[46:49]
	v_mfma_f32_16x16x32_bf16 v[42:45], v[102:105], v[134:137], v[42:45]
	v_mfma_f32_16x16x32_bf16 v[30:33], v[94:97], v[152:155], v[30:33]
	v_mfma_f32_16x16x32_bf16 v[26:29], v[102:105], v[152:155], v[26:29]
	v_mfma_f32_16x16x32_bf16 v[14:17], v[94:97], v[160:163], v[14:17]
	v_mfma_f32_16x16x32_bf16 v[10:13], v[102:105], v[160:163], v[10:13]
	s_setprio 0
	s_setprio 1
	v_mfma_f32_16x16x32_bf16 v[38:41], v[114:117], v[130:133], v[38:41]
	v_mfma_f32_16x16x32_bf16 v[34:37], v[122:125], v[130:133], v[34:37]
	v_mfma_f32_16x16x32_bf16 v[22:25], v[114:117], v[138:141], v[22:25]
	v_mfma_f32_16x16x32_bf16 v[18:21], v[122:125], v[138:141], v[18:21]
	v_mfma_f32_16x16x32_bf16 v[6:9], v[114:117], v[156:159], v[6:9]
	v_mfma_f32_16x16x32_bf16 v[2:5], v[122:125], v[156:159], v[2:5]
	v_mfma_f32_16x16x32_bf16 v[38:41], v[118:121], v[134:137], v[38:41]
	v_mfma_f32_16x16x32_bf16 v[34:37], v[126:129], v[134:137], v[34:37]
	v_mfma_f32_16x16x32_bf16 v[22:25], v[118:121], v[152:155], v[22:25]
	v_mfma_f32_16x16x32_bf16 v[18:21], v[126:129], v[152:155], v[18:21]
	s_setprio 2
	s_barrier
	v_mfma_f32_16x16x32_bf16 v[6:9], v[118:121], v[160:163], v[6:9]
	v_mfma_f32_16x16x32_bf16 v[2:5], v[126:129], v[160:163], v[2:5]
	s_setprio 0
	s_add_i32 s60, s60, 2
	s_add_u32 s2, s2, 0x100
	s_addc_u32 s3, s3, 0
	s_cmpk_gt_u32 s60, 0x55
	s_mov_b64 s[14:15], s[16:17]
	s_cbranch_scc0 .LBB0_2158
	s_and_b64 vcc, exec, s[8:9]
	s_cbranch_vccz .LBB0_2161
	s_barrier
